# v12 + all ds_reads of each load segment issued first (scalar address code moved behind the reads)
# baseline (speedup 1.0000x reference)
.LBB0_642:
	ds_read_b128 v[148:151], v139
	ds_read_b128 v[152:155], v139 offset:1024
	ds_read_b128 v[156:159], v139 offset:2048
	ds_read_b128 v[160:163], v139 offset:3072
	ds_read_b128 v[164:167], v140
	ds_read_b128 v[168:171], v140 offset:1024
	ds_read_b128 v[172:175], v140 offset:2048
	ds_read_b128 v[176:179], v140 offset:3072
	ds_read_b128 v[180:183], v141
	ds_read_b128 v[184:187], v141 offset:1024
	ds_read_b128 v[188:191], v141 offset:2048
	ds_read_b128 v[192:195], v141 offset:3072
	ds_read_b128 v[196:199], v141 offset:4096
	ds_read_b128 v[200:203], v141 offset:5120
	ds_read_b128 v[204:207], v141 offset:6144
	ds_read_b128 v[208:211], v141 offset:7168
	s_add_i32 s18, s71, 0xffe80080
	s_cmp_eq_u32 s58, s73
	s_cselect_b32 s74, s69, s18
	s_cselect_b32 s76, s70, s72
	s_or_b32 s75, s74, 0x80
	s_add_i32 s18, s71, 0xfff80000
	s_mov_b32 m0, s59
	s_nop 0
	buffer_load_dwordx4 v137, s[12:15], s18 offen lds
	s_mov_b32 m0, s60
	s_nop 0
	buffer_load_dwordx4 v137, s[12:15], s71 offen lds
	s_waitcnt vmcnt(8)
	s_waitcnt lgkmcnt(0)
	s_setprio 1
	v_mfma_f32_16x16x32_bf16 v[118:121], v[148:151], v[180:183], v[118:121]
	s_barrier
	v_mfma_f32_16x16x32_bf16 v[118:121], v[152:155], v[184:187], v[118:121]
	v_mfma_f32_16x16x32_bf16 v[114:117], v[156:159], v[180:183], v[114:117]
	v_mfma_f32_16x16x32_bf16 v[114:117], v[160:163], v[184:187], v[114:117]
	v_mfma_f32_16x16x32_bf16 v[126:129], v[164:167], v[180:183], v[126:129]
	v_mfma_f32_16x16x32_bf16 v[126:129], v[168:171], v[184:187], v[126:129]
	v_mfma_f32_16x16x32_bf16 v[122:125], v[172:175], v[180:183], v[122:125]
	v_mfma_f32_16x16x32_bf16 v[122:125], v[176:179], v[184:187], v[122:125]
	v_mfma_f32_16x16x32_bf16 v[98:101], v[172:175], v[188:191], v[98:101]
	v_mfma_f32_16x16x32_bf16 v[98:101], v[176:179], v[192:195], v[98:101]
	v_mfma_f32_16x16x32_bf16 v[106:109], v[164:167], v[188:191], v[106:109]
	v_mfma_f32_16x16x32_bf16 v[106:109], v[168:171], v[192:195], v[106:109]
	v_mfma_f32_16x16x32_bf16 v[102:105], v[156:159], v[188:191], v[102:105]
	v_mfma_f32_16x16x32_bf16 v[102:105], v[160:163], v[192:195], v[102:105]
	v_mfma_f32_16x16x32_bf16 v[110:113], v[148:151], v[188:191], v[110:113]
	v_mfma_f32_16x16x32_bf16 v[110:113], v[152:155], v[192:195], v[110:113]
	v_mfma_f32_16x16x32_bf16 v[94:97], v[148:151], v[196:199], v[94:97]
	v_mfma_f32_16x16x32_bf16 v[94:97], v[152:155], v[200:203], v[94:97]
	v_mfma_f32_16x16x32_bf16 v[86:89], v[156:159], v[196:199], v[86:89]
	v_mfma_f32_16x16x32_bf16 v[86:89], v[160:163], v[200:203], v[86:89]
	v_mfma_f32_16x16x32_bf16 v[90:93], v[164:167], v[196:199], v[90:93]
	v_mfma_f32_16x16x32_bf16 v[90:93], v[168:171], v[200:203], v[90:93]
	v_mfma_f32_16x16x32_bf16 v[82:85], v[172:175], v[196:199], v[82:85]
	v_mfma_f32_16x16x32_bf16 v[82:85], v[176:179], v[200:203], v[82:85]
	v_mfma_f32_16x16x32_bf16 v[70:73], v[172:175], v[204:207], v[70:73]
	v_mfma_f32_16x16x32_bf16 v[70:73], v[176:179], v[208:211], v[70:73]
	v_mfma_f32_16x16x32_bf16 v[74:77], v[164:167], v[204:207], v[74:77]
	v_mfma_f32_16x16x32_bf16 v[74:77], v[168:171], v[208:211], v[74:77]
	v_mfma_f32_16x16x32_bf16 v[66:69], v[156:159], v[204:207], v[66:69]
	v_mfma_f32_16x16x32_bf16 v[66:69], v[160:163], v[208:211], v[66:69]
	v_mfma_f32_16x16x32_bf16 v[78:81], v[148:151], v[204:207], v[78:81]
	v_mfma_f32_16x16x32_bf16 v[78:81], v[152:155], v[208:211], v[78:81]
	s_setprio 0
	s_barrier
	ds_read_b128 v[180:183], v141 offset:16384
	ds_read_b128 v[184:187], v141 offset:17408
	ds_read_b128 v[188:191], v141 offset:18432
	ds_read_b128 v[192:195], v141 offset:19456
	ds_read_b128 v[196:199], v141 offset:20480
	ds_read_b128 v[200:203], v141 offset:21504
	ds_read_b128 v[204:207], v141 offset:22528
	ds_read_b128 v[208:211], v141 offset:23552
	s_mov_b32 m0, s30
	s_mov_b32 s18, s14
	s_mov_b32 s19, s15
	buffer_load_dwordx4 v138, s[16:19], s76 offen lds
	s_add_i32 s77, s76, 0x80000
	s_mov_b32 m0, s31
	s_nop 0
	buffer_load_dwordx4 v138, s[16:19], s77 offen lds
	s_add_i32 s77, s76, 0x100000
	s_mov_b32 m0, s44
	s_nop 0
	buffer_load_dwordx4 v138, s[16:19], s77 offen lds
	s_add_i32 s77, s76, 0x180000
	s_mov_b32 m0, s45
	s_nop 0
	buffer_load_dwordx4 v138, s[16:19], s77 offen lds
	s_mov_b32 m0, s27
	s_add_i32 s77, s74, 0x80000
	buffer_load_dwordx4 v137, s[12:15], s74 offen lds
	s_mov_b32 m0, s46
	s_nop 0
	buffer_load_dwordx4 v137, s[12:15], s77 offen lds
	s_waitcnt vmcnt(8)
	s_waitcnt lgkmcnt(0)
	s_setprio 1
	v_mfma_f32_16x16x32_bf16 v[62:65], v[148:151], v[180:183], v[62:65]
	s_barrier
	v_mfma_f32_16x16x32_bf16 v[62:65], v[152:155], v[184:187], v[62:65]
	v_mfma_f32_16x16x32_bf16 v[54:57], v[156:159], v[180:183], v[54:57]
	v_mfma_f32_16x16x32_bf16 v[54:57], v[160:163], v[184:187], v[54:57]
	v_mfma_f32_16x16x32_bf16 v[58:61], v[164:167], v[180:183], v[58:61]
	v_mfma_f32_16x16x32_bf16 v[58:61], v[168:171], v[184:187], v[58:61]
	v_mfma_f32_16x16x32_bf16 v[50:53], v[172:175], v[180:183], v[50:53]
	v_mfma_f32_16x16x32_bf16 v[50:53], v[176:179], v[184:187], v[50:53]
	v_mfma_f32_16x16x32_bf16 v[34:37], v[172:175], v[188:191], v[34:37]
	v_mfma_f32_16x16x32_bf16 v[34:37], v[176:179], v[192:195], v[34:37]
	v_mfma_f32_16x16x32_bf16 v[42:45], v[164:167], v[188:191], v[42:45]
	v_mfma_f32_16x16x32_bf16 v[42:45], v[168:171], v[192:195], v[42:45]
	v_mfma_f32_16x16x32_bf16 v[38:41], v[156:159], v[188:191], v[38:41]
	v_mfma_f32_16x16x32_bf16 v[38:41], v[160:163], v[192:195], v[38:41]
	v_mfma_f32_16x16x32_bf16 v[46:49], v[148:151], v[188:191], v[46:49]
	v_mfma_f32_16x16x32_bf16 v[46:49], v[152:155], v[192:195], v[46:49]
	v_mfma_f32_16x16x32_bf16 v[30:33], v[148:151], v[196:199], v[30:33]
	v_mfma_f32_16x16x32_bf16 v[30:33], v[152:155], v[200:203], v[30:33]
	v_mfma_f32_16x16x32_bf16 v[22:25], v[156:159], v[196:199], v[22:25]
	v_mfma_f32_16x16x32_bf16 v[22:25], v[160:163], v[200:203], v[22:25]
	v_mfma_f32_16x16x32_bf16 v[26:29], v[164:167], v[196:199], v[26:29]
	v_mfma_f32_16x16x32_bf16 v[26:29], v[168:171], v[200:203], v[26:29]
	v_mfma_f32_16x16x32_bf16 v[18:21], v[172:175], v[196:199], v[18:21]
	v_mfma_f32_16x16x32_bf16 v[18:21], v[176:179], v[200:203], v[18:21]
	v_mfma_f32_16x16x32_bf16 v[2:5], v[172:175], v[204:207], v[2:5]
	v_mfma_f32_16x16x32_bf16 v[2:5], v[176:179], v[208:211], v[2:5]
	v_mfma_f32_16x16x32_bf16 v[10:13], v[164:167], v[204:207], v[10:13]
	v_mfma_f32_16x16x32_bf16 v[10:13], v[168:171], v[208:211], v[10:13]
	v_mfma_f32_16x16x32_bf16 v[6:9], v[156:159], v[204:207], v[6:9]
	v_mfma_f32_16x16x32_bf16 v[6:9], v[160:163], v[208:211], v[6:9]
	v_mfma_f32_16x16x32_bf16 v[14:17], v[148:151], v[204:207], v[14:17]
	v_mfma_f32_16x16x32_bf16 v[14:17], v[152:155], v[208:211], v[14:17]
	s_setprio 0
	s_barrier
	ds_read_b128 v[148:151], v142
	ds_read_b128 v[152:155], v142 offset:1024
	ds_read_b128 v[156:159], v142 offset:2048
	ds_read_b128 v[160:163], v142 offset:3072
	ds_read_b128 v[164:167], v143
	ds_read_b128 v[168:171], v143 offset:1024
	ds_read_b128 v[172:175], v143 offset:2048
	ds_read_b128 v[176:179], v143 offset:3072
	ds_read_b128 v[180:183], v141 offset:32768
	ds_read_b128 v[184:187], v141 offset:33792
	ds_read_b128 v[188:191], v141 offset:34816
	ds_read_b128 v[192:195], v141 offset:35840
	ds_read_b128 v[196:199], v141 offset:36864
	ds_read_b128 v[200:203], v141 offset:37888
	ds_read_b128 v[204:207], v141 offset:38912
	ds_read_b128 v[208:211], v141 offset:39936
	s_mov_b32 m0, s47
	s_add_i32 s77, s74, 0x100000
	buffer_load_dwordx4 v137, s[12:15], s77 offen lds
	s_add_i32 s77, s74, 0x180000
	s_mov_b32 m0, s48
	s_nop 0
	buffer_load_dwordx4 v137, s[12:15], s77 offen lds
	s_waitcnt vmcnt(8)
	s_waitcnt lgkmcnt(0)
	s_setprio 1
	v_mfma_f32_16x16x32_bf16 v[118:121], v[148:151], v[180:183], v[118:121]
	s_barrier
	v_mfma_f32_16x16x32_bf16 v[118:121], v[152:155], v[184:187], v[118:121]
	v_mfma_f32_16x16x32_bf16 v[114:117], v[156:159], v[180:183], v[114:117]
	v_mfma_f32_16x16x32_bf16 v[114:117], v[160:163], v[184:187], v[114:117]
	v_mfma_f32_16x16x32_bf16 v[126:129], v[164:167], v[180:183], v[126:129]
	v_mfma_f32_16x16x32_bf16 v[126:129], v[168:171], v[184:187], v[126:129]
	v_mfma_f32_16x16x32_bf16 v[122:125], v[172:175], v[180:183], v[122:125]
	v_mfma_f32_16x16x32_bf16 v[122:125], v[176:179], v[184:187], v[122:125]
	v_mfma_f32_16x16x32_bf16 v[98:101], v[172:175], v[188:191], v[98:101]
	v_mfma_f32_16x16x32_bf16 v[98:101], v[176:179], v[192:195], v[98:101]
	v_mfma_f32_16x16x32_bf16 v[106:109], v[164:167], v[188:191], v[106:109]
	v_mfma_f32_16x16x32_bf16 v[106:109], v[168:171], v[192:195], v[106:109]
	v_mfma_f32_16x16x32_bf16 v[102:105], v[156:159], v[188:191], v[102:105]
	v_mfma_f32_16x16x32_bf16 v[102:105], v[160:163], v[192:195], v[102:105]
	v_mfma_f32_16x16x32_bf16 v[110:113], v[148:151], v[188:191], v[110:113]
	v_mfma_f32_16x16x32_bf16 v[110:113], v[152:155], v[192:195], v[110:113]
	v_mfma_f32_16x16x32_bf16 v[94:97], v[148:151], v[196:199], v[94:97]
	v_mfma_f32_16x16x32_bf16 v[94:97], v[152:155], v[200:203], v[94:97]
	v_mfma_f32_16x16x32_bf16 v[86:89], v[156:159], v[196:199], v[86:89]
	v_mfma_f32_16x16x32_bf16 v[86:89], v[160:163], v[200:203], v[86:89]
	v_mfma_f32_16x16x32_bf16 v[90:93], v[164:167], v[196:199], v[90:93]
	v_mfma_f32_16x16x32_bf16 v[90:93], v[168:171], v[200:203], v[90:93]
	v_mfma_f32_16x16x32_bf16 v[82:85], v[172:175], v[196:199], v[82:85]
	v_mfma_f32_16x16x32_bf16 v[82:85], v[176:179], v[200:203], v[82:85]
	v_mfma_f32_16x16x32_bf16 v[70:73], v[172:175], v[204:207], v[70:73]
	v_mfma_f32_16x16x32_bf16 v[70:73], v[176:179], v[208:211], v[70:73]
	v_mfma_f32_16x16x32_bf16 v[74:77], v[164:167], v[204:207], v[74:77]
	v_mfma_f32_16x16x32_bf16 v[74:77], v[168:171], v[208:211], v[74:77]
	v_mfma_f32_16x16x32_bf16 v[66:69], v[156:159], v[204:207], v[66:69]
	v_mfma_f32_16x16x32_bf16 v[66:69], v[160:163], v[208:211], v[66:69]
	v_mfma_f32_16x16x32_bf16 v[78:81], v[148:151], v[204:207], v[78:81]
	v_mfma_f32_16x16x32_bf16 v[78:81], v[152:155], v[208:211], v[78:81]
	s_setprio 0
	s_barrier
	ds_read_b128 v[180:183], v141 offset:49152
	ds_read_b128 v[184:187], v141 offset:50176
	ds_read_b128 v[188:191], v141 offset:51200
	ds_read_b128 v[192:195], v141 offset:52224
	ds_read_b128 v[196:199], v141 offset:53248
	ds_read_b128 v[200:203], v141 offset:54272
	ds_read_b128 v[204:207], v141 offset:55296
	ds_read_b128 v[208:211], v141 offset:56320
	s_mov_b32 m0, s50
	s_or_b32 s77, s76, 0x80
	buffer_load_dwordx4 v138, s[16:19], s77 offen lds
	s_add_i32 s77, s76, 0x80080
	s_mov_b32 m0, s51
	s_add_i32 s74, s74, 0x80080
	buffer_load_dwordx4 v138, s[16:19], s77 offen lds
	s_add_i32 s77, s76, 0x100080
	s_mov_b32 m0, s54
	s_add_i32 s76, s76, 0x180080
	buffer_load_dwordx4 v138, s[16:19], s77 offen lds
	s_mov_b32 m0, s55
	s_nop 0
	buffer_load_dwordx4 v138, s[16:19], s76 offen lds
	s_mov_b32 m0, s52
	s_nop 0
	buffer_load_dwordx4 v137, s[12:15], s75 offen lds
	s_mov_b32 m0, s53
	s_nop 0
	buffer_load_dwordx4 v137, s[12:15], s74 offen lds
	s_waitcnt vmcnt(8)
	s_waitcnt lgkmcnt(0)
	s_setprio 1
	v_mfma_f32_16x16x32_bf16 v[62:65], v[148:151], v[180:183], v[62:65]
	s_barrier
	v_mfma_f32_16x16x32_bf16 v[62:65], v[152:155], v[184:187], v[62:65]
	v_mfma_f32_16x16x32_bf16 v[54:57], v[156:159], v[180:183], v[54:57]
	v_mfma_f32_16x16x32_bf16 v[54:57], v[160:163], v[184:187], v[54:57]
	v_mfma_f32_16x16x32_bf16 v[58:61], v[164:167], v[180:183], v[58:61]
	v_mfma_f32_16x16x32_bf16 v[58:61], v[168:171], v[184:187], v[58:61]
	v_mfma_f32_16x16x32_bf16 v[50:53], v[172:175], v[180:183], v[50:53]
	v_mfma_f32_16x16x32_bf16 v[50:53], v[176:179], v[184:187], v[50:53]
	v_mfma_f32_16x16x32_bf16 v[34:37], v[172:175], v[188:191], v[34:37]
	v_mfma_f32_16x16x32_bf16 v[34:37], v[176:179], v[192:195], v[34:37]
	v_mfma_f32_16x16x32_bf16 v[42:45], v[164:167], v[188:191], v[42:45]
	v_mfma_f32_16x16x32_bf16 v[42:45], v[168:171], v[192:195], v[42:45]
	v_mfma_f32_16x16x32_bf16 v[38:41], v[156:159], v[188:191], v[38:41]
	v_mfma_f32_16x16x32_bf16 v[38:41], v[160:163], v[192:195], v[38:41]
	v_mfma_f32_16x16x32_bf16 v[46:49], v[148:151], v[188:191], v[46:49]
	v_mfma_f32_16x16x32_bf16 v[46:49], v[152:155], v[192:195], v[46:49]
	v_mfma_f32_16x16x32_bf16 v[30:33], v[148:151], v[196:199], v[30:33]
	v_mfma_f32_16x16x32_bf16 v[30:33], v[152:155], v[200:203], v[30:33]
	v_mfma_f32_16x16x32_bf16 v[22:25], v[156:159], v[196:199], v[22:25]
	v_mfma_f32_16x16x32_bf16 v[22:25], v[160:163], v[200:203], v[22:25]
	v_mfma_f32_16x16x32_bf16 v[26:29], v[164:167], v[196:199], v[26:29]
	v_mfma_f32_16x16x32_bf16 v[26:29], v[168:171], v[200:203], v[26:29]
	v_mfma_f32_16x16x32_bf16 v[18:21], v[172:175], v[196:199], v[18:21]
	v_mfma_f32_16x16x32_bf16 v[18:21], v[176:179], v[200:203], v[18:21]
	v_mfma_f32_16x16x32_bf16 v[2:5], v[172:175], v[204:207], v[2:5]
	v_mfma_f32_16x16x32_bf16 v[2:5], v[176:179], v[208:211], v[2:5]
	v_mfma_f32_16x16x32_bf16 v[10:13], v[164:167], v[204:207], v[10:13]
	v_mfma_f32_16x16x32_bf16 v[10:13], v[168:171], v[208:211], v[10:13]
	v_mfma_f32_16x16x32_bf16 v[6:9], v[156:159], v[204:207], v[6:9]
	v_mfma_f32_16x16x32_bf16 v[6:9], v[160:163], v[208:211], v[6:9]
	v_mfma_f32_16x16x32_bf16 v[14:17], v[148:151], v[204:207], v[14:17]
	v_mfma_f32_16x16x32_bf16 v[14:17], v[152:155], v[208:211], v[14:17]
	s_setprio 0
	s_barrier
	s_add_i32 s73, s73, 2
	s_addk_i32 s71, 0x100
	s_addk_i32 s72, 0x100
	s_cmp_ge_i32 s73, s3
	s_cbranch_scc0 .LBB0_642
	s_and_b64 vcc, exec, s[42:43]
	s_cbranch_vccz .LBB0_645

.LBB0_799:
	ds_read_b128 v[134:137], v210
	ds_read_b128 v[138:141], v210 offset:1024
	ds_read_b128 v[142:145], v210 offset:2048
	ds_read_b128 v[148:151], v210 offset:3072
	ds_read_b128 v[152:155], v211
	ds_read_b128 v[156:159], v211 offset:1024
	ds_read_b128 v[160:163], v211 offset:2048
	ds_read_b128 v[164:167], v211 offset:3072
	ds_read_b128 v[168:171], v212
	ds_read_b128 v[172:175], v212 offset:1024
	ds_read_b128 v[176:179], v212 offset:2048
	ds_read_b128 v[180:183], v212 offset:3072
	ds_read_b128 v[184:187], v212 offset:4096
	ds_read_b128 v[188:191], v212 offset:5120
	ds_read_b128 v[192:195], v212 offset:6144
	ds_read_b128 v[196:199], v212 offset:7168
	s_add_i32 s18, s77, 0xffbf8080
	s_cmp_eq_u32 s62, s79
	s_cselect_b32 s80, s6, s18
	s_cselect_b32 s82, s7, s78
	s_or_b32 s81, s80, 0x80
	s_add_i32 s18, s77, 0xffea8000
	s_mov_b32 m0, s63
	s_nop 0
	buffer_load_dwordx4 v208, s[12:15], s18 offen lds
	s_mov_b32 m0, s66
	s_nop 0
	buffer_load_dwordx4 v208, s[12:15], s77 offen lds
	s_waitcnt vmcnt(8)
	s_waitcnt lgkmcnt(0)
	s_setprio 1
	v_mfma_f32_16x16x32_bf16 v[126:129], v[134:137], v[168:171], v[126:129]
	s_barrier
	v_mfma_f32_16x16x32_bf16 v[126:129], v[138:141], v[172:175], v[126:129]
	v_mfma_f32_16x16x32_bf16 v[122:125], v[142:145], v[168:171], v[122:125]
	v_mfma_f32_16x16x32_bf16 v[122:125], v[148:151], v[172:175], v[122:125]
	v_mfma_f32_16x16x32_bf16 v[110:113], v[152:155], v[168:171], v[110:113]
	v_mfma_f32_16x16x32_bf16 v[110:113], v[156:159], v[172:175], v[110:113]
	v_mfma_f32_16x16x32_bf16 v[102:105], v[160:163], v[168:171], v[102:105]
	v_mfma_f32_16x16x32_bf16 v[102:105], v[164:167], v[172:175], v[102:105]
	v_mfma_f32_16x16x32_bf16 v[86:89], v[160:163], v[176:179], v[86:89]
	v_mfma_f32_16x16x32_bf16 v[86:89], v[164:167], v[180:183], v[86:89]
	v_mfma_f32_16x16x32_bf16 v[94:97], v[152:155], v[176:179], v[94:97]
	v_mfma_f32_16x16x32_bf16 v[94:97], v[156:159], v[180:183], v[94:97]
	v_mfma_f32_16x16x32_bf16 v[114:117], v[142:145], v[176:179], v[114:117]
	v_mfma_f32_16x16x32_bf16 v[114:117], v[148:151], v[180:183], v[114:117]
	v_mfma_f32_16x16x32_bf16 v[118:121], v[134:137], v[176:179], v[118:121]
	v_mfma_f32_16x16x32_bf16 v[118:121], v[138:141], v[180:183], v[118:121]
	v_mfma_f32_16x16x32_bf16 v[106:109], v[134:137], v[184:187], v[106:109]
	v_mfma_f32_16x16x32_bf16 v[106:109], v[138:141], v[188:191], v[106:109]
	v_mfma_f32_16x16x32_bf16 v[98:101], v[142:145], v[184:187], v[98:101]
	v_mfma_f32_16x16x32_bf16 v[98:101], v[148:151], v[188:191], v[98:101]
	v_mfma_f32_16x16x32_bf16 v[78:81], v[152:155], v[184:187], v[78:81]
	v_mfma_f32_16x16x32_bf16 v[78:81], v[156:159], v[188:191], v[78:81]
	v_mfma_f32_16x16x32_bf16 v[74:77], v[160:163], v[184:187], v[74:77]
	v_mfma_f32_16x16x32_bf16 v[74:77], v[164:167], v[188:191], v[74:77]
	v_mfma_f32_16x16x32_bf16 v[66:69], v[160:163], v[192:195], v[66:69]
	v_mfma_f32_16x16x32_bf16 v[66:69], v[164:167], v[196:199], v[66:69]
	v_mfma_f32_16x16x32_bf16 v[70:73], v[152:155], v[192:195], v[70:73]
	v_mfma_f32_16x16x32_bf16 v[70:73], v[156:159], v[196:199], v[70:73]
	v_mfma_f32_16x16x32_bf16 v[82:85], v[142:145], v[192:195], v[82:85]
	v_mfma_f32_16x16x32_bf16 v[82:85], v[148:151], v[196:199], v[82:85]
	v_mfma_f32_16x16x32_bf16 v[90:93], v[134:137], v[192:195], v[90:93]
	v_mfma_f32_16x16x32_bf16 v[90:93], v[138:141], v[196:199], v[90:93]
	s_setprio 0
	s_barrier
	ds_read_b128 v[168:171], v212 offset:16384
	ds_read_b128 v[172:175], v212 offset:17408
	ds_read_b128 v[176:179], v212 offset:18432
	ds_read_b128 v[180:183], v212 offset:19456
	ds_read_b128 v[184:187], v212 offset:20480
	ds_read_b128 v[188:191], v212 offset:21504
	ds_read_b128 v[192:195], v212 offset:22528
	ds_read_b128 v[196:199], v212 offset:23552
	s_mov_b32 m0, s25
	s_mov_b32 s18, s14
	s_mov_b32 s19, s15
	buffer_load_dwordx4 v209, s[16:19], s82 offen lds
	s_add_i32 s83, s82, 0x158000
	s_mov_b32 m0, s27
	s_nop 0
	buffer_load_dwordx4 v209, s[16:19], s83 offen lds
	s_add_i32 s83, s82, 0x2b0000
	s_mov_b32 m0, s30
	s_nop 0
	buffer_load_dwordx4 v209, s[16:19], s83 offen lds
	s_add_i32 s83, s82, 0x408000
	s_mov_b32 m0, s31
	s_nop 0
	buffer_load_dwordx4 v209, s[16:19], s83 offen lds
	s_mov_b32 m0, s21
	s_add_i32 s83, s80, 0x158000
	buffer_load_dwordx4 v208, s[12:15], s80 offen lds
	s_mov_b32 m0, s48
	s_nop 0
	buffer_load_dwordx4 v208, s[12:15], s83 offen lds
	s_waitcnt vmcnt(8)
	s_waitcnt lgkmcnt(0)
	s_setprio 1
	v_mfma_f32_16x16x32_bf16 v[62:65], v[134:137], v[168:171], v[62:65]
	s_barrier
	v_mfma_f32_16x16x32_bf16 v[62:65], v[138:141], v[172:175], v[62:65]
	v_mfma_f32_16x16x32_bf16 v[58:61], v[142:145], v[168:171], v[58:61]
	v_mfma_f32_16x16x32_bf16 v[58:61], v[148:151], v[172:175], v[58:61]
	v_mfma_f32_16x16x32_bf16 v[46:49], v[152:155], v[168:171], v[46:49]
	v_mfma_f32_16x16x32_bf16 v[46:49], v[156:159], v[172:175], v[46:49]
	v_mfma_f32_16x16x32_bf16 v[38:41], v[160:163], v[168:171], v[38:41]
	v_mfma_f32_16x16x32_bf16 v[38:41], v[164:167], v[172:175], v[38:41]
	v_mfma_f32_16x16x32_bf16 v[22:25], v[160:163], v[176:179], v[22:25]
	v_mfma_f32_16x16x32_bf16 v[22:25], v[164:167], v[180:183], v[22:25]
	v_mfma_f32_16x16x32_bf16 v[30:33], v[152:155], v[176:179], v[30:33]
	v_mfma_f32_16x16x32_bf16 v[30:33], v[156:159], v[180:183], v[30:33]
	v_mfma_f32_16x16x32_bf16 v[50:53], v[142:145], v[176:179], v[50:53]
	v_mfma_f32_16x16x32_bf16 v[50:53], v[148:151], v[180:183], v[50:53]
	v_mfma_f32_16x16x32_bf16 v[54:57], v[134:137], v[176:179], v[54:57]
	v_mfma_f32_16x16x32_bf16 v[54:57], v[138:141], v[180:183], v[54:57]
	v_mfma_f32_16x16x32_bf16 v[42:45], v[134:137], v[184:187], v[42:45]
	v_mfma_f32_16x16x32_bf16 v[42:45], v[138:141], v[188:191], v[42:45]
	v_mfma_f32_16x16x32_bf16 v[34:37], v[142:145], v[184:187], v[34:37]
	v_mfma_f32_16x16x32_bf16 v[34:37], v[148:151], v[188:191], v[34:37]
	v_mfma_f32_16x16x32_bf16 v[14:17], v[152:155], v[184:187], v[14:17]
	v_mfma_f32_16x16x32_bf16 v[14:17], v[156:159], v[188:191], v[14:17]
	v_mfma_f32_16x16x32_bf16 v[10:13], v[160:163], v[184:187], v[10:13]
	v_mfma_f32_16x16x32_bf16 v[10:13], v[164:167], v[188:191], v[10:13]
	v_mfma_f32_16x16x32_bf16 v[2:5], v[160:163], v[192:195], v[2:5]
	v_mfma_f32_16x16x32_bf16 v[2:5], v[164:167], v[196:199], v[2:5]
	v_mfma_f32_16x16x32_bf16 v[6:9], v[152:155], v[192:195], v[6:9]
	v_mfma_f32_16x16x32_bf16 v[6:9], v[156:159], v[196:199], v[6:9]
	v_mfma_f32_16x16x32_bf16 v[18:21], v[142:145], v[192:195], v[18:21]
	v_mfma_f32_16x16x32_bf16 v[18:21], v[148:151], v[196:199], v[18:21]
	v_mfma_f32_16x16x32_bf16 v[26:29], v[134:137], v[192:195], v[26:29]
	v_mfma_f32_16x16x32_bf16 v[26:29], v[138:141], v[196:199], v[26:29]
	s_setprio 0
	s_barrier
	ds_read_b128 v[134:137], v213
	ds_read_b128 v[138:141], v213 offset:1024
	ds_read_b128 v[142:145], v213 offset:2048
	ds_read_b128 v[148:151], v213 offset:3072
	ds_read_b128 v[152:155], v214
	ds_read_b128 v[156:159], v214 offset:1024
	ds_read_b128 v[160:163], v214 offset:2048
	ds_read_b128 v[164:167], v214 offset:3072
	ds_read_b128 v[168:171], v212 offset:32768
	ds_read_b128 v[172:175], v212 offset:33792
	ds_read_b128 v[176:179], v212 offset:34816
	ds_read_b128 v[180:183], v212 offset:35840
	ds_read_b128 v[184:187], v212 offset:36864
	ds_read_b128 v[188:191], v212 offset:37888
	ds_read_b128 v[192:195], v212 offset:38912
	ds_read_b128 v[196:199], v212 offset:39936
	s_mov_b32 m0, s49
	s_add_i32 s83, s80, 0x2b0000
	buffer_load_dwordx4 v208, s[12:15], s83 offen lds
	s_add_i32 s83, s80, 0x408000
	s_mov_b32 m0, s50
	s_nop 0
	buffer_load_dwordx4 v208, s[12:15], s83 offen lds
	s_waitcnt vmcnt(8)
	s_waitcnt lgkmcnt(0)
	s_setprio 1
	v_mfma_f32_16x16x32_bf16 v[126:129], v[134:137], v[168:171], v[126:129]
	s_barrier
	v_mfma_f32_16x16x32_bf16 v[126:129], v[138:141], v[172:175], v[126:129]
	v_mfma_f32_16x16x32_bf16 v[122:125], v[142:145], v[168:171], v[122:125]
	v_mfma_f32_16x16x32_bf16 v[122:125], v[148:151], v[172:175], v[122:125]
	v_mfma_f32_16x16x32_bf16 v[110:113], v[152:155], v[168:171], v[110:113]
	v_mfma_f32_16x16x32_bf16 v[110:113], v[156:159], v[172:175], v[110:113]
	v_mfma_f32_16x16x32_bf16 v[102:105], v[160:163], v[168:171], v[102:105]
	v_mfma_f32_16x16x32_bf16 v[102:105], v[164:167], v[172:175], v[102:105]
	v_mfma_f32_16x16x32_bf16 v[86:89], v[160:163], v[176:179], v[86:89]
	v_mfma_f32_16x16x32_bf16 v[86:89], v[164:167], v[180:183], v[86:89]
	v_mfma_f32_16x16x32_bf16 v[94:97], v[152:155], v[176:179], v[94:97]
	v_mfma_f32_16x16x32_bf16 v[94:97], v[156:159], v[180:183], v[94:97]
	v_mfma_f32_16x16x32_bf16 v[114:117], v[142:145], v[176:179], v[114:117]
	v_mfma_f32_16x16x32_bf16 v[114:117], v[148:151], v[180:183], v[114:117]
	v_mfma_f32_16x16x32_bf16 v[118:121], v[134:137], v[176:179], v[118:121]
	v_mfma_f32_16x16x32_bf16 v[118:121], v[138:141], v[180:183], v[118:121]
	v_mfma_f32_16x16x32_bf16 v[106:109], v[134:137], v[184:187], v[106:109]
	v_mfma_f32_16x16x32_bf16 v[106:109], v[138:141], v[188:191], v[106:109]
	v_mfma_f32_16x16x32_bf16 v[98:101], v[142:145], v[184:187], v[98:101]
	v_mfma_f32_16x16x32_bf16 v[98:101], v[148:151], v[188:191], v[98:101]
	v_mfma_f32_16x16x32_bf16 v[78:81], v[152:155], v[184:187], v[78:81]
	v_mfma_f32_16x16x32_bf16 v[78:81], v[156:159], v[188:191], v[78:81]
	v_mfma_f32_16x16x32_bf16 v[74:77], v[160:163], v[184:187], v[74:77]
	v_mfma_f32_16x16x32_bf16 v[74:77], v[164:167], v[188:191], v[74:77]
	v_mfma_f32_16x16x32_bf16 v[66:69], v[160:163], v[192:195], v[66:69]
	v_mfma_f32_16x16x32_bf16 v[66:69], v[164:167], v[196:199], v[66:69]
	v_mfma_f32_16x16x32_bf16 v[70:73], v[152:155], v[192:195], v[70:73]
	v_mfma_f32_16x16x32_bf16 v[70:73], v[156:159], v[196:199], v[70:73]
	v_mfma_f32_16x16x32_bf16 v[82:85], v[142:145], v[192:195], v[82:85]
	v_mfma_f32_16x16x32_bf16 v[82:85], v[148:151], v[196:199], v[82:85]
	v_mfma_f32_16x16x32_bf16 v[90:93], v[134:137], v[192:195], v[90:93]
	v_mfma_f32_16x16x32_bf16 v[90:93], v[138:141], v[196:199], v[90:93]
	s_setprio 0
	s_barrier
	ds_read_b128 v[168:171], v212 offset:49152
	ds_read_b128 v[172:175], v212 offset:50176
	ds_read_b128 v[176:179], v212 offset:51200
	ds_read_b128 v[180:183], v212 offset:52224
	ds_read_b128 v[184:187], v212 offset:53248
	ds_read_b128 v[188:191], v212 offset:54272
	ds_read_b128 v[192:195], v212 offset:55296
	ds_read_b128 v[196:199], v212 offset:56320
	s_mov_b32 m0, s54
	s_or_b32 s83, s82, 0x80
	buffer_load_dwordx4 v209, s[16:19], s83 offen lds
	s_add_i32 s83, s82, 0x158080
	s_mov_b32 m0, s55
	s_add_i32 s80, s80, 0x158080
	buffer_load_dwordx4 v209, s[16:19], s83 offen lds
	s_add_i32 s83, s82, 0x2b0080
	s_mov_b32 m0, s58
	s_add_i32 s82, s82, 0x408080
	buffer_load_dwordx4 v209, s[16:19], s83 offen lds
	s_mov_b32 m0, s59
	s_nop 0
	buffer_load_dwordx4 v209, s[16:19], s82 offen lds
	s_mov_b32 m0, s56
	s_nop 0
	buffer_load_dwordx4 v208, s[12:15], s81 offen lds
	s_mov_b32 m0, s57
	s_nop 0
	buffer_load_dwordx4 v208, s[12:15], s80 offen lds
	s_waitcnt vmcnt(8)
	s_waitcnt lgkmcnt(0)
	s_setprio 1
	v_mfma_f32_16x16x32_bf16 v[62:65], v[134:137], v[168:171], v[62:65]
	s_barrier
	v_mfma_f32_16x16x32_bf16 v[62:65], v[138:141], v[172:175], v[62:65]
	v_mfma_f32_16x16x32_bf16 v[58:61], v[142:145], v[168:171], v[58:61]
	v_mfma_f32_16x16x32_bf16 v[58:61], v[148:151], v[172:175], v[58:61]
	v_mfma_f32_16x16x32_bf16 v[46:49], v[152:155], v[168:171], v[46:49]
	v_mfma_f32_16x16x32_bf16 v[46:49], v[156:159], v[172:175], v[46:49]
	v_mfma_f32_16x16x32_bf16 v[38:41], v[160:163], v[168:171], v[38:41]
	v_mfma_f32_16x16x32_bf16 v[38:41], v[164:167], v[172:175], v[38:41]
	v_mfma_f32_16x16x32_bf16 v[22:25], v[160:163], v[176:179], v[22:25]
	v_mfma_f32_16x16x32_bf16 v[22:25], v[164:167], v[180:183], v[22:25]
	v_mfma_f32_16x16x32_bf16 v[30:33], v[152:155], v[176:179], v[30:33]
	v_mfma_f32_16x16x32_bf16 v[30:33], v[156:159], v[180:183], v[30:33]
	v_mfma_f32_16x16x32_bf16 v[50:53], v[142:145], v[176:179], v[50:53]
	v_mfma_f32_16x16x32_bf16 v[50:53], v[148:151], v[180:183], v[50:53]
	v_mfma_f32_16x16x32_bf16 v[54:57], v[134:137], v[176:179], v[54:57]
	v_mfma_f32_16x16x32_bf16 v[54:57], v[138:141], v[180:183], v[54:57]
	v_mfma_f32_16x16x32_bf16 v[42:45], v[134:137], v[184:187], v[42:45]
	v_mfma_f32_16x16x32_bf16 v[42:45], v[138:141], v[188:191], v[42:45]
	v_mfma_f32_16x16x32_bf16 v[34:37], v[142:145], v[184:187], v[34:37]
	v_mfma_f32_16x16x32_bf16 v[34:37], v[148:151], v[188:191], v[34:37]
	v_mfma_f32_16x16x32_bf16 v[14:17], v[152:155], v[184:187], v[14:17]
	v_mfma_f32_16x16x32_bf16 v[14:17], v[156:159], v[188:191], v[14:17]
	v_mfma_f32_16x16x32_bf16 v[10:13], v[160:163], v[184:187], v[10:13]
	v_mfma_f32_16x16x32_bf16 v[10:13], v[164:167], v[188:191], v[10:13]
	v_mfma_f32_16x16x32_bf16 v[2:5], v[160:163], v[192:195], v[2:5]
	v_mfma_f32_16x16x32_bf16 v[2:5], v[164:167], v[196:199], v[2:5]
	v_mfma_f32_16x16x32_bf16 v[6:9], v[152:155], v[192:195], v[6:9]
	v_mfma_f32_16x16x32_bf16 v[6:9], v[156:159], v[196:199], v[6:9]
	v_mfma_f32_16x16x32_bf16 v[18:21], v[142:145], v[192:195], v[18:21]
	v_mfma_f32_16x16x32_bf16 v[18:21], v[148:151], v[196:199], v[18:21]
	v_mfma_f32_16x16x32_bf16 v[26:29], v[134:137], v[192:195], v[26:29]
	v_mfma_f32_16x16x32_bf16 v[26:29], v[138:141], v[196:199], v[26:29]
	s_setprio 0
	s_barrier
	s_add_i32 s79, s79, 2
	s_addk_i32 s77, 0x100
	s_addk_i32 s78, 0x100
	s_cmp_ge_i32 s79, s3
	s_cbranch_scc0 .LBB0_799
	v_pk_mul_f32 v[184:185], v[128:129], 0.5 op_sel_hi:[1,0]
	v_pk_mul_f32 v[186:187], v[126:127], 0.5 op_sel_hi:[1,0]
	v_pk_mul_f32 v[188:189], v[124:125], 0.5 op_sel_hi:[1,0]
	v_pk_mul_f32 v[190:191], v[122:123], 0.5 op_sel_hi:[1,0]
	v_pk_mul_f32 v[198:199], v[112:113], 0.5 op_sel_hi:[1,0]
	v_pk_mul_f32 v[196:197], v[110:111], 0.5 op_sel_hi:[1,0]
	v_pk_mul_f32 v[194:195], v[104:105], 0.5 op_sel_hi:[1,0]
	v_pk_mul_f32 v[192:193], v[102:103], 0.5 op_sel_hi:[1,0]
	v_pk_mul_f32 v[182:183], v[120:121], 0.5 op_sel_hi:[1,0]
	v_pk_mul_f32 v[180:181], v[118:119], 0.5 op_sel_hi:[1,0]
	v_pk_mul_f32 v[178:179], v[116:117], 0.5 op_sel_hi:[1,0]
	v_pk_mul_f32 v[176:177], v[114:115], 0.5 op_sel_hi:[1,0]
	v_pk_mul_f32 v[172:173], v[96:97], 0.5 op_sel_hi:[1,0]
	v_pk_mul_f32 v[170:171], v[94:95], 0.5 op_sel_hi:[1,0]
	v_pk_mul_f32 v[168:169], v[88:89], 0.5 op_sel_hi:[1,0]
	v_pk_mul_f32 v[166:167], v[86:87], 0.5 op_sel_hi:[1,0]
	v_pk_mul_f32 v[164:165], v[108:109], 0.5 op_sel_hi:[1,0]
	v_pk_mul_f32 v[162:163], v[106:107], 0.5 op_sel_hi:[1,0]
	v_pk_mul_f32 v[160:161], v[100:101], 0.5 op_sel_hi:[1,0]
	v_pk_mul_f32 v[158:159], v[98:99], 0.5 op_sel_hi:[1,0]
	v_pk_mul_f32 v[156:157], v[80:81], 0.5 op_sel_hi:[1,0]
	v_pk_mul_f32 v[154:155], v[78:79], 0.5 op_sel_hi:[1,0]
	v_pk_mul_f32 v[152:153], v[76:77], 0.5 op_sel_hi:[1,0]
	v_pk_mul_f32 v[150:151], v[74:75], 0.5 op_sel_hi:[1,0]
	v_pk_mul_f32 v[144:145], v[92:93], 0.5 op_sel_hi:[1,0]
	v_pk_mul_f32 v[142:143], v[90:91], 0.5 op_sel_hi:[1,0]
	v_pk_mul_f32 v[140:141], v[84:85], 0.5 op_sel_hi:[1,0]
	v_pk_mul_f32 v[138:139], v[82:83], 0.5 op_sel_hi:[1,0]
	v_pk_mul_f32 v[136:137], v[72:73], 0.5 op_sel_hi:[1,0]
	v_pk_mul_f32 v[134:135], v[70:71], 0.5 op_sel_hi:[1,0]
	v_pk_mul_f32 v[128:129], v[68:69], 0.5 op_sel_hi:[1,0]
	v_pk_mul_f32 v[126:127], v[66:67], 0.5 op_sel_hi:[1,0]
	v_pk_mul_f32 v[122:123], v[64:65], 0.5 op_sel_hi:[1,0]
	v_pk_mul_f32 v[120:121], v[62:63], 0.5 op_sel_hi:[1,0]
	v_pk_mul_f32 v[118:119], v[60:61], 0.5 op_sel_hi:[1,0]
	v_pk_mul_f32 v[116:117], v[58:59], 0.5 op_sel_hi:[1,0]
	v_pk_mul_f32 v[112:113], v[48:49], 0.5 op_sel_hi:[1,0]
	v_pk_mul_f32 v[110:111], v[46:47], 0.5 op_sel_hi:[1,0]
	v_pk_mul_f32 v[108:109], v[40:41], 0.5 op_sel_hi:[1,0]
	v_pk_mul_f32 v[106:107], v[38:39], 0.5 op_sel_hi:[1,0]
	v_pk_mul_f32 v[104:105], v[56:57], 0.5 op_sel_hi:[1,0]
	v_pk_mul_f32 v[102:103], v[54:55], 0.5 op_sel_hi:[1,0]
	v_pk_mul_f32 v[100:101], v[52:53], 0.5 op_sel_hi:[1,0]
	v_pk_mul_f32 v[98:99], v[50:51], 0.5 op_sel_hi:[1,0]
	v_pk_mul_f32 v[96:97], v[32:33], 0.5 op_sel_hi:[1,0]
	v_pk_mul_f32 v[94:95], v[30:31], 0.5 op_sel_hi:[1,0]
	v_pk_mul_f32 v[92:93], v[24:25], 0.5 op_sel_hi:[1,0]
	v_pk_mul_f32 v[90:91], v[22:23], 0.5 op_sel_hi:[1,0]
	v_pk_mul_f32 v[88:89], v[44:45], 0.5 op_sel_hi:[1,0]
	v_pk_mul_f32 v[86:87], v[42:43], 0.5 op_sel_hi:[1,0]
	v_pk_mul_f32 v[84:85], v[36:37], 0.5 op_sel_hi:[1,0]
	v_pk_mul_f32 v[82:83], v[34:35], 0.5 op_sel_hi:[1,0]
	v_pk_mul_f32 v[80:81], v[16:17], 0.5 op_sel_hi:[1,0]
	v_pk_mul_f32 v[78:79], v[14:15], 0.5 op_sel_hi:[1,0]
	v_pk_mul_f32 v[76:77], v[12:13], 0.5 op_sel_hi:[1,0]
	v_pk_mul_f32 v[74:75], v[10:11], 0.5 op_sel_hi:[1,0]
	v_pk_mul_f32 v[72:73], v[28:29], 0.5 op_sel_hi:[1,0]
	v_pk_mul_f32 v[70:71], v[26:27], 0.5 op_sel_hi:[1,0]
	v_pk_mul_f32 v[68:69], v[20:21], 0.5 op_sel_hi:[1,0]
	v_pk_mul_f32 v[66:67], v[18:19], 0.5 op_sel_hi:[1,0]
	v_pk_mul_f32 v[64:65], v[8:9], 0.5 op_sel_hi:[1,0]
	v_pk_mul_f32 v[62:63], v[6:7], 0.5 op_sel_hi:[1,0]
	v_pk_mul_f32 v[60:61], v[4:5], 0.5 op_sel_hi:[1,0]
	v_pk_mul_f32 v[58:59], v[2:3], 0.5 op_sel_hi:[1,0]
	s_and_b64 vcc, exec, s[38:39]
	s_cbranch_vccz .LBB0_802

.LBB0_892:
	ds_read_b128 v[130:133], v172
	ds_read_b128 v[134:137], v172 offset:1024
	ds_read_b128 v[148:151], v172 offset:2048
	ds_read_b128 v[152:155], v172 offset:3072
	ds_read_b128 v[156:159], v173
	ds_read_b128 v[160:163], v173 offset:1024
	ds_read_b128 v[164:167], v173 offset:2048
	ds_read_b128 v[180:183], v173 offset:3072
	ds_read_b128 v[184:187], v174
	ds_read_b128 v[188:191], v174 offset:1024
	ds_read_b128 v[192:195], v174 offset:2048
	ds_read_b128 v[196:199], v174 offset:3072
	ds_read_b128 v[200:203], v174 offset:4096
	ds_read_b128 v[204:207], v174 offset:5120
	ds_read_b128 v[208:211], v174 offset:6144
	ds_read_b128 v[212:215], v174 offset:7168
	s_add_i32 s18, s8, 0xffe80080
	s_cmp_eq_u32 s77, s52
	s_cselect_b32 s53, s6, s18
	s_cselect_b32 s58, s7, s9
	s_or_b32 s57, s53, 0x80
	s_add_i32 s18, s8, 0xfff80000
	s_mov_b32 m0, s78
	s_nop 0
	buffer_load_dwordx4 v170, s[12:15], s18 offen lds
	s_mov_b32 m0, s79
	s_nop 0
	buffer_load_dwordx4 v170, s[12:15], s8 offen lds
	s_waitcnt vmcnt(8)
	s_waitcnt lgkmcnt(0)
	s_setprio 1
	v_mfma_f32_16x16x32_bf16 v[126:129], v[130:133], v[184:187], v[126:129]
	s_barrier
	v_mfma_f32_16x16x32_bf16 v[126:129], v[134:137], v[188:191], v[126:129]
	v_mfma_f32_16x16x32_bf16 v[118:121], v[148:151], v[184:187], v[118:121]
	v_mfma_f32_16x16x32_bf16 v[118:121], v[152:155], v[188:191], v[118:121]
	v_mfma_f32_16x16x32_bf16 v[122:125], v[156:159], v[184:187], v[122:125]
	v_mfma_f32_16x16x32_bf16 v[122:125], v[160:163], v[188:191], v[122:125]
	v_mfma_f32_16x16x32_bf16 v[114:117], v[164:167], v[184:187], v[114:117]
	v_mfma_f32_16x16x32_bf16 v[114:117], v[180:183], v[188:191], v[114:117]
	v_mfma_f32_16x16x32_bf16 v[98:101], v[164:167], v[192:195], v[98:101]
	v_mfma_f32_16x16x32_bf16 v[98:101], v[180:183], v[196:199], v[98:101]
	v_mfma_f32_16x16x32_bf16 v[106:109], v[156:159], v[192:195], v[106:109]
	v_mfma_f32_16x16x32_bf16 v[106:109], v[160:163], v[196:199], v[106:109]
	v_mfma_f32_16x16x32_bf16 v[102:105], v[148:151], v[192:195], v[102:105]
	v_mfma_f32_16x16x32_bf16 v[102:105], v[152:155], v[196:199], v[102:105]
	v_mfma_f32_16x16x32_bf16 v[110:113], v[130:133], v[192:195], v[110:113]
	v_mfma_f32_16x16x32_bf16 v[110:113], v[134:137], v[196:199], v[110:113]
	v_mfma_f32_16x16x32_bf16 v[94:97], v[130:133], v[200:203], v[94:97]
	v_mfma_f32_16x16x32_bf16 v[94:97], v[134:137], v[204:207], v[94:97]
	v_mfma_f32_16x16x32_bf16 v[90:93], v[148:151], v[200:203], v[90:93]
	v_mfma_f32_16x16x32_bf16 v[90:93], v[152:155], v[204:207], v[90:93]
	v_mfma_f32_16x16x32_bf16 v[86:89], v[156:159], v[200:203], v[86:89]
	v_mfma_f32_16x16x32_bf16 v[86:89], v[160:163], v[204:207], v[86:89]
	v_mfma_f32_16x16x32_bf16 v[82:85], v[164:167], v[200:203], v[82:85]
	v_mfma_f32_16x16x32_bf16 v[82:85], v[180:183], v[204:207], v[82:85]
	v_mfma_f32_16x16x32_bf16 v[66:69], v[164:167], v[208:211], v[66:69]
	v_mfma_f32_16x16x32_bf16 v[66:69], v[180:183], v[212:215], v[66:69]
	v_mfma_f32_16x16x32_bf16 v[74:77], v[156:159], v[208:211], v[74:77]
	v_mfma_f32_16x16x32_bf16 v[74:77], v[160:163], v[212:215], v[74:77]
	v_mfma_f32_16x16x32_bf16 v[70:73], v[148:151], v[208:211], v[70:73]
	v_mfma_f32_16x16x32_bf16 v[70:73], v[152:155], v[212:215], v[70:73]
	v_mfma_f32_16x16x32_bf16 v[78:81], v[130:133], v[208:211], v[78:81]
	v_mfma_f32_16x16x32_bf16 v[78:81], v[134:137], v[212:215], v[78:81]
	s_setprio 0
	s_barrier
	ds_read_b128 v[184:187], v174 offset:16384
	ds_read_b128 v[188:191], v174 offset:17408
	ds_read_b128 v[192:195], v174 offset:18432
	ds_read_b128 v[196:199], v174 offset:19456
	ds_read_b128 v[200:203], v174 offset:20480
	ds_read_b128 v[204:207], v174 offset:21504
	ds_read_b128 v[208:211], v174 offset:22528
	ds_read_b128 v[212:215], v174 offset:23552
	s_mov_b32 m0, s27
	s_mov_b32 s18, s14
	s_mov_b32 s19, s15
	buffer_load_dwordx4 v171, s[16:19], s58 offen lds
	s_add_i32 s59, s58, 0x80000
	s_mov_b32 m0, s60
	s_nop 0
	buffer_load_dwordx4 v171, s[16:19], s59 offen lds
	s_add_i32 s59, s58, 0x100000
	s_mov_b32 m0, s61
	s_nop 0
	buffer_load_dwordx4 v171, s[16:19], s59 offen lds
	s_add_i32 s59, s58, 0x180000
	s_mov_b32 m0, s62
	s_nop 0
	buffer_load_dwordx4 v171, s[16:19], s59 offen lds
	s_mov_b32 m0, s25
	s_add_i32 s59, s53, 0x80000
	buffer_load_dwordx4 v170, s[12:15], s53 offen lds
	s_mov_b32 m0, s63
	s_nop 0
	buffer_load_dwordx4 v170, s[12:15], s59 offen lds
	s_waitcnt vmcnt(8)
	s_waitcnt lgkmcnt(0)
	s_setprio 1
	v_mfma_f32_16x16x32_bf16 v[62:65], v[130:133], v[184:187], v[62:65]
	s_barrier
	v_mfma_f32_16x16x32_bf16 v[62:65], v[134:137], v[188:191], v[62:65]
	v_mfma_f32_16x16x32_bf16 v[54:57], v[148:151], v[184:187], v[54:57]
	v_mfma_f32_16x16x32_bf16 v[54:57], v[152:155], v[188:191], v[54:57]
	v_mfma_f32_16x16x32_bf16 v[58:61], v[156:159], v[184:187], v[58:61]
	v_mfma_f32_16x16x32_bf16 v[58:61], v[160:163], v[188:191], v[58:61]
	v_mfma_f32_16x16x32_bf16 v[50:53], v[164:167], v[184:187], v[50:53]
	v_mfma_f32_16x16x32_bf16 v[50:53], v[180:183], v[188:191], v[50:53]
	v_mfma_f32_16x16x32_bf16 v[34:37], v[164:167], v[192:195], v[34:37]
	v_mfma_f32_16x16x32_bf16 v[34:37], v[180:183], v[196:199], v[34:37]
	v_mfma_f32_16x16x32_bf16 v[42:45], v[156:159], v[192:195], v[42:45]
	v_mfma_f32_16x16x32_bf16 v[42:45], v[160:163], v[196:199], v[42:45]
	v_mfma_f32_16x16x32_bf16 v[38:41], v[148:151], v[192:195], v[38:41]
	v_mfma_f32_16x16x32_bf16 v[38:41], v[152:155], v[196:199], v[38:41]
	v_mfma_f32_16x16x32_bf16 v[46:49], v[130:133], v[192:195], v[46:49]
	v_mfma_f32_16x16x32_bf16 v[46:49], v[134:137], v[196:199], v[46:49]
	v_mfma_f32_16x16x32_bf16 v[30:33], v[130:133], v[200:203], v[30:33]
	v_mfma_f32_16x16x32_bf16 v[30:33], v[134:137], v[204:207], v[30:33]
	v_mfma_f32_16x16x32_bf16 v[22:25], v[148:151], v[200:203], v[22:25]
	v_mfma_f32_16x16x32_bf16 v[22:25], v[152:155], v[204:207], v[22:25]
	v_mfma_f32_16x16x32_bf16 v[26:29], v[156:159], v[200:203], v[26:29]
	v_mfma_f32_16x16x32_bf16 v[26:29], v[160:163], v[204:207], v[26:29]
	v_mfma_f32_16x16x32_bf16 v[18:21], v[164:167], v[200:203], v[18:21]
	v_mfma_f32_16x16x32_bf16 v[18:21], v[180:183], v[204:207], v[18:21]
	v_mfma_f32_16x16x32_bf16 v[2:5], v[164:167], v[208:211], v[2:5]
	v_mfma_f32_16x16x32_bf16 v[2:5], v[180:183], v[212:215], v[2:5]
	v_mfma_f32_16x16x32_bf16 v[10:13], v[156:159], v[208:211], v[10:13]
	v_mfma_f32_16x16x32_bf16 v[10:13], v[160:163], v[212:215], v[10:13]
	v_mfma_f32_16x16x32_bf16 v[6:9], v[148:151], v[208:211], v[6:9]
	v_mfma_f32_16x16x32_bf16 v[6:9], v[152:155], v[212:215], v[6:9]
	v_mfma_f32_16x16x32_bf16 v[14:17], v[130:133], v[208:211], v[14:17]
	v_mfma_f32_16x16x32_bf16 v[14:17], v[134:137], v[212:215], v[14:17]
	s_setprio 0
	s_barrier
	ds_read_b128 v[130:133], v175
	ds_read_b128 v[134:137], v175 offset:1024
	ds_read_b128 v[148:151], v175 offset:2048
	ds_read_b128 v[152:155], v175 offset:3072
	ds_read_b128 v[156:159], v176
	ds_read_b128 v[160:163], v176 offset:1024
	ds_read_b128 v[164:167], v176 offset:2048
	ds_read_b128 v[180:183], v176 offset:3072
	ds_read_b128 v[184:187], v174 offset:32768
	ds_read_b128 v[188:191], v174 offset:33792
	ds_read_b128 v[192:195], v174 offset:34816
	ds_read_b128 v[196:199], v174 offset:35840
	ds_read_b128 v[200:203], v174 offset:36864
	ds_read_b128 v[204:207], v174 offset:37888
	ds_read_b128 v[208:211], v174 offset:38912
	ds_read_b128 v[212:215], v174 offset:39936
	s_mov_b32 m0, s64
	s_add_i32 s59, s53, 0x100000
	buffer_load_dwordx4 v170, s[12:15], s59 offen lds
	s_add_i32 s59, s53, 0x180000
	s_mov_b32 m0, s65
	s_nop 0
	buffer_load_dwordx4 v170, s[12:15], s59 offen lds
	s_waitcnt vmcnt(8)
	s_waitcnt lgkmcnt(0)
	s_setprio 1
	v_mfma_f32_16x16x32_bf16 v[126:129], v[130:133], v[184:187], v[126:129]
	s_barrier
	v_mfma_f32_16x16x32_bf16 v[126:129], v[134:137], v[188:191], v[126:129]
	v_mfma_f32_16x16x32_bf16 v[118:121], v[148:151], v[184:187], v[118:121]
	v_mfma_f32_16x16x32_bf16 v[118:121], v[152:155], v[188:191], v[118:121]
	v_mfma_f32_16x16x32_bf16 v[122:125], v[156:159], v[184:187], v[122:125]
	v_mfma_f32_16x16x32_bf16 v[122:125], v[160:163], v[188:191], v[122:125]
	v_mfma_f32_16x16x32_bf16 v[114:117], v[164:167], v[184:187], v[114:117]
	v_mfma_f32_16x16x32_bf16 v[114:117], v[180:183], v[188:191], v[114:117]
	v_mfma_f32_16x16x32_bf16 v[98:101], v[164:167], v[192:195], v[98:101]
	v_mfma_f32_16x16x32_bf16 v[98:101], v[180:183], v[196:199], v[98:101]
	v_mfma_f32_16x16x32_bf16 v[106:109], v[156:159], v[192:195], v[106:109]
	v_mfma_f32_16x16x32_bf16 v[106:109], v[160:163], v[196:199], v[106:109]
	v_mfma_f32_16x16x32_bf16 v[102:105], v[148:151], v[192:195], v[102:105]
	v_mfma_f32_16x16x32_bf16 v[102:105], v[152:155], v[196:199], v[102:105]
	v_mfma_f32_16x16x32_bf16 v[110:113], v[130:133], v[192:195], v[110:113]
	v_mfma_f32_16x16x32_bf16 v[110:113], v[134:137], v[196:199], v[110:113]
	v_mfma_f32_16x16x32_bf16 v[94:97], v[130:133], v[200:203], v[94:97]
	v_mfma_f32_16x16x32_bf16 v[94:97], v[134:137], v[204:207], v[94:97]
	v_mfma_f32_16x16x32_bf16 v[90:93], v[148:151], v[200:203], v[90:93]
	v_mfma_f32_16x16x32_bf16 v[90:93], v[152:155], v[204:207], v[90:93]
	v_mfma_f32_16x16x32_bf16 v[86:89], v[156:159], v[200:203], v[86:89]
	v_mfma_f32_16x16x32_bf16 v[86:89], v[160:163], v[204:207], v[86:89]
	v_mfma_f32_16x16x32_bf16 v[82:85], v[164:167], v[200:203], v[82:85]
	v_mfma_f32_16x16x32_bf16 v[82:85], v[180:183], v[204:207], v[82:85]
	v_mfma_f32_16x16x32_bf16 v[66:69], v[164:167], v[208:211], v[66:69]
	v_mfma_f32_16x16x32_bf16 v[66:69], v[180:183], v[212:215], v[66:69]
	v_mfma_f32_16x16x32_bf16 v[74:77], v[156:159], v[208:211], v[74:77]
	v_mfma_f32_16x16x32_bf16 v[74:77], v[160:163], v[212:215], v[74:77]
	v_mfma_f32_16x16x32_bf16 v[70:73], v[148:151], v[208:211], v[70:73]
	v_mfma_f32_16x16x32_bf16 v[70:73], v[152:155], v[212:215], v[70:73]
	v_mfma_f32_16x16x32_bf16 v[78:81], v[130:133], v[208:211], v[78:81]
	v_mfma_f32_16x16x32_bf16 v[78:81], v[134:137], v[212:215], v[78:81]
	s_setprio 0
	s_barrier
	ds_read_b128 v[184:187], v174 offset:49152
	ds_read_b128 v[188:191], v174 offset:50176
	ds_read_b128 v[192:195], v174 offset:51200
	ds_read_b128 v[196:199], v174 offset:52224
	ds_read_b128 v[200:203], v174 offset:53248
	ds_read_b128 v[204:207], v174 offset:54272
	ds_read_b128 v[208:211], v174 offset:55296
	ds_read_b128 v[212:215], v174 offset:56320
	s_mov_b32 m0, s70
	s_or_b32 s59, s58, 0x80
	buffer_load_dwordx4 v171, s[16:19], s59 offen lds
	s_add_i32 s59, s58, 0x80080
	s_mov_b32 m0, s71
	s_add_i32 s53, s53, 0x80080
	buffer_load_dwordx4 v171, s[16:19], s59 offen lds
	s_add_i32 s59, s58, 0x100080
	s_mov_b32 m0, s74
	s_add_i32 s58, s58, 0x180080
	buffer_load_dwordx4 v171, s[16:19], s59 offen lds
	s_mov_b32 m0, s75
	s_nop 0
	buffer_load_dwordx4 v171, s[16:19], s58 offen lds
	s_mov_b32 m0, s72
	s_nop 0
	buffer_load_dwordx4 v170, s[12:15], s57 offen lds
	s_mov_b32 m0, s73
	s_nop 0
	buffer_load_dwordx4 v170, s[12:15], s53 offen lds
	s_waitcnt vmcnt(8)
	s_waitcnt lgkmcnt(0)
	s_setprio 1
	v_mfma_f32_16x16x32_bf16 v[62:65], v[130:133], v[184:187], v[62:65]
	s_barrier
	v_mfma_f32_16x16x32_bf16 v[62:65], v[134:137], v[188:191], v[62:65]
	v_mfma_f32_16x16x32_bf16 v[54:57], v[148:151], v[184:187], v[54:57]
	v_mfma_f32_16x16x32_bf16 v[54:57], v[152:155], v[188:191], v[54:57]
	v_mfma_f32_16x16x32_bf16 v[58:61], v[156:159], v[184:187], v[58:61]
	v_mfma_f32_16x16x32_bf16 v[58:61], v[160:163], v[188:191], v[58:61]
	v_mfma_f32_16x16x32_bf16 v[50:53], v[164:167], v[184:187], v[50:53]
	v_mfma_f32_16x16x32_bf16 v[50:53], v[180:183], v[188:191], v[50:53]
	v_mfma_f32_16x16x32_bf16 v[34:37], v[164:167], v[192:195], v[34:37]
	v_mfma_f32_16x16x32_bf16 v[34:37], v[180:183], v[196:199], v[34:37]
	v_mfma_f32_16x16x32_bf16 v[42:45], v[156:159], v[192:195], v[42:45]
	v_mfma_f32_16x16x32_bf16 v[42:45], v[160:163], v[196:199], v[42:45]
	v_mfma_f32_16x16x32_bf16 v[38:41], v[148:151], v[192:195], v[38:41]
	v_mfma_f32_16x16x32_bf16 v[38:41], v[152:155], v[196:199], v[38:41]
	v_mfma_f32_16x16x32_bf16 v[46:49], v[130:133], v[192:195], v[46:49]
	v_mfma_f32_16x16x32_bf16 v[46:49], v[134:137], v[196:199], v[46:49]
	v_mfma_f32_16x16x32_bf16 v[30:33], v[130:133], v[200:203], v[30:33]
	v_mfma_f32_16x16x32_bf16 v[30:33], v[134:137], v[204:207], v[30:33]
	v_mfma_f32_16x16x32_bf16 v[22:25], v[148:151], v[200:203], v[22:25]
	v_mfma_f32_16x16x32_bf16 v[22:25], v[152:155], v[204:207], v[22:25]
	v_mfma_f32_16x16x32_bf16 v[26:29], v[156:159], v[200:203], v[26:29]
	v_mfma_f32_16x16x32_bf16 v[26:29], v[160:163], v[204:207], v[26:29]
	v_mfma_f32_16x16x32_bf16 v[18:21], v[164:167], v[200:203], v[18:21]
	v_mfma_f32_16x16x32_bf16 v[18:21], v[180:183], v[204:207], v[18:21]
	v_mfma_f32_16x16x32_bf16 v[2:5], v[164:167], v[208:211], v[2:5]
	v_mfma_f32_16x16x32_bf16 v[2:5], v[180:183], v[212:215], v[2:5]
	v_mfma_f32_16x16x32_bf16 v[10:13], v[156:159], v[208:211], v[10:13]
	v_mfma_f32_16x16x32_bf16 v[10:13], v[160:163], v[212:215], v[10:13]
	v_mfma_f32_16x16x32_bf16 v[6:9], v[148:151], v[208:211], v[6:9]
	v_mfma_f32_16x16x32_bf16 v[6:9], v[152:155], v[212:215], v[6:9]
	v_mfma_f32_16x16x32_bf16 v[14:17], v[130:133], v[208:211], v[14:17]
	v_mfma_f32_16x16x32_bf16 v[14:17], v[134:137], v[212:215], v[14:17]
	s_setprio 0
	s_barrier
	s_add_i32 s52, s52, 2
	s_addk_i32 s8, 0x100
	s_addk_i32 s9, 0x100
	s_cmp_ge_i32 s52, s21
	s_cbranch_scc0 .LBB0_892
	s_and_b64 vcc, exec, s[48:49]
	s_cbranch_vccz .LBB0_895

.LBB0_1020:
	v_add_u32_e32 v142, 0x10000, v162
	v_add_u32_e32 v150, 0x14000, v162
	ds_read_b128 v[130:133], v142
	ds_read_b128 v[134:137], v142 offset:1024
	ds_read_b128 v[138:141], v142 offset:2048
	ds_read_b128 v[142:145], v142 offset:3072
	ds_read_b128 v[154:157], v150
	ds_read_b128 v[164:167], v150 offset:1024
	ds_read_b128 v[168:171], v150 offset:2048
	ds_read_b128 v[172:175], v150 offset:3072
	s_add_i32 s90, s6, 0x100
	s_add_i32 s7, s88, s6
	s_cmp_eq_u32 s81, s89
	s_cselect_b32 s91, 0, s90
	s_cselect_b32 s93, s87, s7
	s_add_i32 s91, s91, s70
	s_or_b32 s92, s91, 0x80
	s_add_i32 s6, s3, s6
	s_mov_b32 m0, s82
	s_add_i32 s7, s6, 0x20080
	ds_read_b128 v[176:179], v163
	ds_read_b128 v[180:183], v163 offset:1024
	ds_read_b128 v[184:187], v163 offset:2048
	ds_read_b128 v[188:191], v163 offset:3072
	ds_read_b128 v[192:195], v163 offset:4096
	ds_read_b128 v[196:199], v163 offset:5120
	ds_read_b128 v[200:203], v163 offset:6144
	ds_read_b128 v[204:207], v163 offset:7168
	buffer_load_dwordx4 v161, s[12:15], s7 offen lds
	s_add_i32 s6, s6, 0x30080
	s_mov_b32 m0, s83
	s_nop 0
	buffer_load_dwordx4 v161, s[12:15], s6 offen lds
	s_waitcnt vmcnt(8)
	s_waitcnt lgkmcnt(0)
	s_setprio 1
	v_mfma_f32_16x16x32_bf16 v[126:129], v[130:133], v[176:179], v[126:129]
	s_barrier
	v_mfma_f32_16x16x32_bf16 v[126:129], v[134:137], v[180:183], v[126:129]
	v_mfma_f32_16x16x32_bf16 v[122:125], v[138:141], v[176:179], v[122:125]
	v_mfma_f32_16x16x32_bf16 v[122:125], v[142:145], v[180:183], v[122:125]
	v_mfma_f32_16x16x32_bf16 v[118:121], v[154:157], v[176:179], v[118:121]
	v_mfma_f32_16x16x32_bf16 v[118:121], v[164:167], v[180:183], v[118:121]
	v_mfma_f32_16x16x32_bf16 v[114:117], v[168:171], v[176:179], v[114:117]
	v_mfma_f32_16x16x32_bf16 v[114:117], v[172:175], v[180:183], v[114:117]
	v_mfma_f32_16x16x32_bf16 v[98:101], v[168:171], v[184:187], v[98:101]
	v_mfma_f32_16x16x32_bf16 v[98:101], v[172:175], v[188:191], v[98:101]
	v_mfma_f32_16x16x32_bf16 v[102:105], v[154:157], v[184:187], v[102:105]
	v_mfma_f32_16x16x32_bf16 v[102:105], v[164:167], v[188:191], v[102:105]
	v_mfma_f32_16x16x32_bf16 v[106:109], v[138:141], v[184:187], v[106:109]
	v_mfma_f32_16x16x32_bf16 v[106:109], v[142:145], v[188:191], v[106:109]
	v_mfma_f32_16x16x32_bf16 v[110:113], v[130:133], v[184:187], v[110:113]
	v_mfma_f32_16x16x32_bf16 v[110:113], v[134:137], v[188:191], v[110:113]
	v_mfma_f32_16x16x32_bf16 v[94:97], v[130:133], v[192:195], v[94:97]
	v_mfma_f32_16x16x32_bf16 v[94:97], v[134:137], v[196:199], v[94:97]
	v_mfma_f32_16x16x32_bf16 v[90:93], v[138:141], v[192:195], v[90:93]
	v_mfma_f32_16x16x32_bf16 v[90:93], v[142:145], v[196:199], v[90:93]
	v_mfma_f32_16x16x32_bf16 v[86:89], v[154:157], v[192:195], v[86:89]
	v_mfma_f32_16x16x32_bf16 v[86:89], v[164:167], v[196:199], v[86:89]
	v_mfma_f32_16x16x32_bf16 v[82:85], v[168:171], v[192:195], v[82:85]
	v_mfma_f32_16x16x32_bf16 v[82:85], v[172:175], v[196:199], v[82:85]
	v_mfma_f32_16x16x32_bf16 v[66:69], v[168:171], v[200:203], v[66:69]
	v_mfma_f32_16x16x32_bf16 v[66:69], v[172:175], v[204:207], v[66:69]
	v_mfma_f32_16x16x32_bf16 v[70:73], v[154:157], v[200:203], v[70:73]
	v_mfma_f32_16x16x32_bf16 v[70:73], v[164:167], v[204:207], v[70:73]
	v_mfma_f32_16x16x32_bf16 v[74:77], v[138:141], v[200:203], v[74:77]
	v_mfma_f32_16x16x32_bf16 v[74:77], v[142:145], v[204:207], v[74:77]
	v_mfma_f32_16x16x32_bf16 v[78:81], v[130:133], v[200:203], v[78:81]
	v_mfma_f32_16x16x32_bf16 v[78:81], v[134:137], v[204:207], v[78:81]
	s_setprio 0
	s_barrier
	ds_read_b128 v[176:179], v163 offset:16384
	ds_read_b128 v[180:183], v163 offset:17408
	ds_read_b128 v[184:187], v163 offset:18432
	ds_read_b128 v[188:191], v163 offset:19456
	ds_read_b128 v[192:195], v163 offset:20480
	ds_read_b128 v[196:199], v163 offset:21504
	ds_read_b128 v[200:203], v163 offset:22528
	ds_read_b128 v[204:207], v163 offset:23552
	s_mov_b32 m0, s66
	s_mov_b32 s6, s14
	s_mov_b32 s7, s15
	buffer_load_dwordx4 v160, s[4:7], s93 offen lds
	s_add_i32 s94, s93, 0x10000
	s_mov_b32 m0, s67
	s_nop 0
	buffer_load_dwordx4 v160, s[4:7], s94 offen lds
	s_add_i32 s94, s93, 0x20000
	s_mov_b32 m0, s68
	s_nop 0
	buffer_load_dwordx4 v160, s[4:7], s94 offen lds
	s_add_i32 s94, s93, 0x30000
	s_mov_b32 m0, s69
	s_nop 0
	buffer_load_dwordx4 v160, s[4:7], s94 offen lds
	s_mov_b32 m0, s65
	s_add_i32 s94, s91, 0x10000
	buffer_load_dwordx4 v161, s[12:15], s91 offen lds
	s_mov_b32 m0, s71
	s_nop 0
	buffer_load_dwordx4 v161, s[12:15], s94 offen lds
	s_waitcnt vmcnt(8)
	s_waitcnt lgkmcnt(0)
	s_setprio 1
	v_mfma_f32_16x16x32_bf16 v[62:65], v[130:133], v[176:179], v[62:65]
	s_barrier
	v_mfma_f32_16x16x32_bf16 v[62:65], v[134:137], v[180:183], v[62:65]
	v_mfma_f32_16x16x32_bf16 v[58:61], v[138:141], v[176:179], v[58:61]
	v_mfma_f32_16x16x32_bf16 v[58:61], v[142:145], v[180:183], v[58:61]
	v_mfma_f32_16x16x32_bf16 v[54:57], v[154:157], v[176:179], v[54:57]
	v_mfma_f32_16x16x32_bf16 v[54:57], v[164:167], v[180:183], v[54:57]
	v_mfma_f32_16x16x32_bf16 v[50:53], v[168:171], v[176:179], v[50:53]
	v_mfma_f32_16x16x32_bf16 v[50:53], v[172:175], v[180:183], v[50:53]
	v_mfma_f32_16x16x32_bf16 v[34:37], v[168:171], v[184:187], v[34:37]
	v_mfma_f32_16x16x32_bf16 v[34:37], v[172:175], v[188:191], v[34:37]
	v_mfma_f32_16x16x32_bf16 v[38:41], v[154:157], v[184:187], v[38:41]
	v_mfma_f32_16x16x32_bf16 v[38:41], v[164:167], v[188:191], v[38:41]
	v_mfma_f32_16x16x32_bf16 v[42:45], v[138:141], v[184:187], v[42:45]
	v_mfma_f32_16x16x32_bf16 v[42:45], v[142:145], v[188:191], v[42:45]
	v_mfma_f32_16x16x32_bf16 v[46:49], v[130:133], v[184:187], v[46:49]
	v_mfma_f32_16x16x32_bf16 v[46:49], v[134:137], v[188:191], v[46:49]
	v_mfma_f32_16x16x32_bf16 v[30:33], v[130:133], v[192:195], v[30:33]
	v_mfma_f32_16x16x32_bf16 v[30:33], v[134:137], v[196:199], v[30:33]
	v_mfma_f32_16x16x32_bf16 v[26:29], v[138:141], v[192:195], v[26:29]
	v_mfma_f32_16x16x32_bf16 v[26:29], v[142:145], v[196:199], v[26:29]
	v_mfma_f32_16x16x32_bf16 v[22:25], v[154:157], v[192:195], v[22:25]
	v_mfma_f32_16x16x32_bf16 v[22:25], v[164:167], v[196:199], v[22:25]
	v_mfma_f32_16x16x32_bf16 v[18:21], v[168:171], v[192:195], v[18:21]
	v_mfma_f32_16x16x32_bf16 v[18:21], v[172:175], v[196:199], v[18:21]
	v_mfma_f32_16x16x32_bf16 v[2:5], v[168:171], v[200:203], v[2:5]
	v_mfma_f32_16x16x32_bf16 v[2:5], v[172:175], v[204:207], v[2:5]
	v_mfma_f32_16x16x32_bf16 v[6:9], v[154:157], v[200:203], v[6:9]
	v_mfma_f32_16x16x32_bf16 v[6:9], v[164:167], v[204:207], v[6:9]
	v_mfma_f32_16x16x32_bf16 v[10:13], v[138:141], v[200:203], v[10:13]
	v_mfma_f32_16x16x32_bf16 v[10:13], v[142:145], v[204:207], v[10:13]
	v_mfma_f32_16x16x32_bf16 v[14:17], v[130:133], v[200:203], v[14:17]
	v_mfma_f32_16x16x32_bf16 v[14:17], v[134:137], v[204:207], v[14:17]
	s_setprio 0
	s_barrier
	v_add_u32_e32 v142, 0x18000, v162
	v_add_u32_e32 v150, 0x1c000, v162
	ds_read_b128 v[130:133], v142
	ds_read_b128 v[134:137], v142 offset:1024
	ds_read_b128 v[138:141], v142 offset:2048
	ds_read_b128 v[142:145], v142 offset:3072
	ds_read_b128 v[154:157], v150
	ds_read_b128 v[164:167], v150 offset:1024
	ds_read_b128 v[168:171], v150 offset:2048
	ds_read_b128 v[172:175], v150 offset:3072
	s_mov_b32 m0, s72
	s_add_i32 s94, s91, 0x20000
	ds_read_b128 v[176:179], v163 offset:32768
	ds_read_b128 v[180:183], v163 offset:33792
	ds_read_b128 v[184:187], v163 offset:34816
	ds_read_b128 v[188:191], v163 offset:35840
	ds_read_b128 v[192:195], v163 offset:36864
	ds_read_b128 v[196:199], v163 offset:37888
	ds_read_b128 v[200:203], v163 offset:38912
	ds_read_b128 v[204:207], v163 offset:39936
	buffer_load_dwordx4 v161, s[12:15], s94 offen lds
	s_add_i32 s94, s91, 0x30000
	s_mov_b32 m0, s73
	s_nop 0
	buffer_load_dwordx4 v161, s[12:15], s94 offen lds
	s_waitcnt vmcnt(8)
	s_waitcnt lgkmcnt(0)
	s_setprio 1
	v_mfma_f32_16x16x32_bf16 v[126:129], v[130:133], v[176:179], v[126:129]
	s_barrier
	v_mfma_f32_16x16x32_bf16 v[126:129], v[134:137], v[180:183], v[126:129]
	v_mfma_f32_16x16x32_bf16 v[122:125], v[138:141], v[176:179], v[122:125]
	v_mfma_f32_16x16x32_bf16 v[122:125], v[142:145], v[180:183], v[122:125]
	v_mfma_f32_16x16x32_bf16 v[118:121], v[154:157], v[176:179], v[118:121]
	v_mfma_f32_16x16x32_bf16 v[118:121], v[164:167], v[180:183], v[118:121]
	v_mfma_f32_16x16x32_bf16 v[114:117], v[168:171], v[176:179], v[114:117]
	v_mfma_f32_16x16x32_bf16 v[114:117], v[172:175], v[180:183], v[114:117]
	v_mfma_f32_16x16x32_bf16 v[98:101], v[168:171], v[184:187], v[98:101]
	v_mfma_f32_16x16x32_bf16 v[98:101], v[172:175], v[188:191], v[98:101]
	v_mfma_f32_16x16x32_bf16 v[102:105], v[154:157], v[184:187], v[102:105]
	v_mfma_f32_16x16x32_bf16 v[102:105], v[164:167], v[188:191], v[102:105]
	v_mfma_f32_16x16x32_bf16 v[106:109], v[138:141], v[184:187], v[106:109]
	v_mfma_f32_16x16x32_bf16 v[106:109], v[142:145], v[188:191], v[106:109]
	v_mfma_f32_16x16x32_bf16 v[110:113], v[130:133], v[184:187], v[110:113]
	v_mfma_f32_16x16x32_bf16 v[110:113], v[134:137], v[188:191], v[110:113]
	v_mfma_f32_16x16x32_bf16 v[94:97], v[130:133], v[192:195], v[94:97]
	v_mfma_f32_16x16x32_bf16 v[94:97], v[134:137], v[196:199], v[94:97]
	v_mfma_f32_16x16x32_bf16 v[90:93], v[138:141], v[192:195], v[90:93]
	v_mfma_f32_16x16x32_bf16 v[90:93], v[142:145], v[196:199], v[90:93]
	v_mfma_f32_16x16x32_bf16 v[86:89], v[154:157], v[192:195], v[86:89]
	v_mfma_f32_16x16x32_bf16 v[86:89], v[164:167], v[196:199], v[86:89]
	v_mfma_f32_16x16x32_bf16 v[82:85], v[168:171], v[192:195], v[82:85]
	v_mfma_f32_16x16x32_bf16 v[82:85], v[172:175], v[196:199], v[82:85]
	v_mfma_f32_16x16x32_bf16 v[66:69], v[168:171], v[200:203], v[66:69]
	v_mfma_f32_16x16x32_bf16 v[66:69], v[172:175], v[204:207], v[66:69]
	v_mfma_f32_16x16x32_bf16 v[70:73], v[154:157], v[200:203], v[70:73]
	v_mfma_f32_16x16x32_bf16 v[70:73], v[164:167], v[204:207], v[70:73]
	v_mfma_f32_16x16x32_bf16 v[74:77], v[138:141], v[200:203], v[74:77]
	v_mfma_f32_16x16x32_bf16 v[74:77], v[142:145], v[204:207], v[74:77]
	v_mfma_f32_16x16x32_bf16 v[78:81], v[130:133], v[200:203], v[78:81]
	v_mfma_f32_16x16x32_bf16 v[78:81], v[134:137], v[204:207], v[78:81]
	s_setprio 0
	s_barrier
	ds_read_b128 v[176:179], v163 offset:49152
	ds_read_b128 v[180:183], v163 offset:50176
	ds_read_b128 v[184:187], v163 offset:51200
	ds_read_b128 v[188:191], v163 offset:52224
	ds_read_b128 v[192:195], v163 offset:53248
	ds_read_b128 v[196:199], v163 offset:54272
	ds_read_b128 v[200:203], v163 offset:55296
	ds_read_b128 v[204:207], v163 offset:56320
	s_mov_b32 m0, s74
	s_or_b32 s94, s93, 0x80
	buffer_load_dwordx4 v160, s[4:7], s94 offen lds
	s_add_i32 s94, s93, 0x10080
	s_mov_b32 m0, s75
	s_add_i32 s91, s91, 0x10080
	buffer_load_dwordx4 v160, s[4:7], s94 offen lds
	s_add_i32 s94, s93, 0x20080
	s_mov_b32 m0, s78
	s_add_i32 s93, s93, 0x30080
	buffer_load_dwordx4 v160, s[4:7], s94 offen lds
	s_mov_b32 m0, s79
	s_nop 0
	buffer_load_dwordx4 v160, s[4:7], s93 offen lds
	s_mov_b32 m0, s76
	s_nop 0
	buffer_load_dwordx4 v161, s[12:15], s92 offen lds
	s_mov_b32 m0, s77
	s_nop 0
	buffer_load_dwordx4 v161, s[12:15], s91 offen lds
	s_waitcnt vmcnt(8)
	s_waitcnt lgkmcnt(0)
	s_setprio 1
	v_mfma_f32_16x16x32_bf16 v[62:65], v[130:133], v[176:179], v[62:65]
	s_barrier
	v_mfma_f32_16x16x32_bf16 v[62:65], v[134:137], v[180:183], v[62:65]
	v_mfma_f32_16x16x32_bf16 v[58:61], v[138:141], v[176:179], v[58:61]
	v_mfma_f32_16x16x32_bf16 v[58:61], v[142:145], v[180:183], v[58:61]
	v_mfma_f32_16x16x32_bf16 v[54:57], v[154:157], v[176:179], v[54:57]
	v_mfma_f32_16x16x32_bf16 v[54:57], v[164:167], v[180:183], v[54:57]
	v_mfma_f32_16x16x32_bf16 v[50:53], v[168:171], v[176:179], v[50:53]
	v_mfma_f32_16x16x32_bf16 v[50:53], v[172:175], v[180:183], v[50:53]
	v_mfma_f32_16x16x32_bf16 v[34:37], v[168:171], v[184:187], v[34:37]
	v_mfma_f32_16x16x32_bf16 v[34:37], v[172:175], v[188:191], v[34:37]
	v_mfma_f32_16x16x32_bf16 v[38:41], v[154:157], v[184:187], v[38:41]
	v_mfma_f32_16x16x32_bf16 v[38:41], v[164:167], v[188:191], v[38:41]
	v_mfma_f32_16x16x32_bf16 v[42:45], v[138:141], v[184:187], v[42:45]
	v_mfma_f32_16x16x32_bf16 v[42:45], v[142:145], v[188:191], v[42:45]
	v_mfma_f32_16x16x32_bf16 v[46:49], v[130:133], v[184:187], v[46:49]
	v_mfma_f32_16x16x32_bf16 v[46:49], v[134:137], v[188:191], v[46:49]
	v_mfma_f32_16x16x32_bf16 v[30:33], v[130:133], v[192:195], v[30:33]
	v_mfma_f32_16x16x32_bf16 v[30:33], v[134:137], v[196:199], v[30:33]
	v_mfma_f32_16x16x32_bf16 v[26:29], v[138:141], v[192:195], v[26:29]
	v_mfma_f32_16x16x32_bf16 v[26:29], v[142:145], v[196:199], v[26:29]
	v_mfma_f32_16x16x32_bf16 v[22:25], v[154:157], v[192:195], v[22:25]
	v_mfma_f32_16x16x32_bf16 v[22:25], v[164:167], v[196:199], v[22:25]
	v_mfma_f32_16x16x32_bf16 v[18:21], v[168:171], v[192:195], v[18:21]
	v_mfma_f32_16x16x32_bf16 v[18:21], v[172:175], v[196:199], v[18:21]
	v_mfma_f32_16x16x32_bf16 v[2:5], v[168:171], v[200:203], v[2:5]
	v_mfma_f32_16x16x32_bf16 v[2:5], v[172:175], v[204:207], v[2:5]
	v_mfma_f32_16x16x32_bf16 v[6:9], v[154:157], v[200:203], v[6:9]
	v_mfma_f32_16x16x32_bf16 v[6:9], v[164:167], v[204:207], v[6:9]
	v_mfma_f32_16x16x32_bf16 v[10:13], v[138:141], v[200:203], v[10:13]
	v_mfma_f32_16x16x32_bf16 v[10:13], v[142:145], v[204:207], v[10:13]
	v_mfma_f32_16x16x32_bf16 v[14:17], v[130:133], v[200:203], v[14:17]
	v_mfma_f32_16x16x32_bf16 v[14:17], v[134:137], v[204:207], v[14:17]
	s_setprio 0
	s_barrier
	s_add_i32 s89, s89, 2
	s_cmp_ge_i32 s89, s63
	s_mov_b32 s6, s90
	s_cbranch_scc0 .LBB0_1020
	s_and_b64 vcc, exec, s[54:55]
	s_cbranch_vccz .LBB0_1023

.LBB0_1035:
	ds_read_b128 v[140:143], v134
	ds_read_b128 v[148:151], v134 offset:1024
	ds_read_b128 v[152:155], v134 offset:2048
	ds_read_b128 v[156:159], v134 offset:3072
	ds_read_b128 v[160:163], v135
	ds_read_b128 v[164:167], v135 offset:1024
	ds_read_b128 v[168:171], v135 offset:2048
	ds_read_b128 v[172:175], v135 offset:3072
	ds_read_b128 v[176:179], v136
	ds_read_b128 v[180:183], v136 offset:1024
	ds_read_b128 v[184:187], v136 offset:2048
	ds_read_b128 v[188:191], v136 offset:3072
	ds_read_b128 v[192:195], v136 offset:4096
	ds_read_b128 v[196:199], v136 offset:5120
	ds_read_b128 v[200:203], v136 offset:6144
	ds_read_b128 v[204:207], v136 offset:7168
	s_add_i32 s73, s70, 0xfffb8080
	s_cmp_eq_u32 s53, s72
	s_cselect_b32 s73, s68, s73
	s_cselect_b32 s75, s69, s71
	s_add_i32 s74, s73, 0x80
	s_add_i32 s76, s70, 0xfffe8000
	s_mov_b32 m0, s54
	s_nop 0
	buffer_load_dwordx4 v132, s[12:15], s76 offen lds
	s_mov_b32 m0, s55
	s_nop 0
	buffer_load_dwordx4 v132, s[12:15], s70 offen lds
	s_waitcnt vmcnt(8)
	s_waitcnt lgkmcnt(0)
	s_setprio 1
	v_mfma_f32_16x16x32_bf16 v[126:129], v[140:143], v[176:179], v[126:129]
	s_barrier
	v_mfma_f32_16x16x32_bf16 v[126:129], v[148:151], v[180:183], v[126:129]
	v_mfma_f32_16x16x32_bf16 v[122:125], v[152:155], v[176:179], v[122:125]
	v_mfma_f32_16x16x32_bf16 v[122:125], v[156:159], v[180:183], v[122:125]
	v_mfma_f32_16x16x32_bf16 v[118:121], v[160:163], v[176:179], v[118:121]
	v_mfma_f32_16x16x32_bf16 v[118:121], v[164:167], v[180:183], v[118:121]
	v_mfma_f32_16x16x32_bf16 v[114:117], v[168:171], v[176:179], v[114:117]
	v_mfma_f32_16x16x32_bf16 v[114:117], v[172:175], v[180:183], v[114:117]
	v_mfma_f32_16x16x32_bf16 v[98:101], v[168:171], v[184:187], v[98:101]
	v_mfma_f32_16x16x32_bf16 v[98:101], v[172:175], v[188:191], v[98:101]
	v_mfma_f32_16x16x32_bf16 v[102:105], v[160:163], v[184:187], v[102:105]
	v_mfma_f32_16x16x32_bf16 v[102:105], v[164:167], v[188:191], v[102:105]
	v_mfma_f32_16x16x32_bf16 v[106:109], v[152:155], v[184:187], v[106:109]
	v_mfma_f32_16x16x32_bf16 v[106:109], v[156:159], v[188:191], v[106:109]
	v_mfma_f32_16x16x32_bf16 v[110:113], v[140:143], v[184:187], v[110:113]
	v_mfma_f32_16x16x32_bf16 v[110:113], v[148:151], v[188:191], v[110:113]
	v_mfma_f32_16x16x32_bf16 v[94:97], v[140:143], v[192:195], v[94:97]
	v_mfma_f32_16x16x32_bf16 v[94:97], v[148:151], v[196:199], v[94:97]
	v_mfma_f32_16x16x32_bf16 v[90:93], v[152:155], v[192:195], v[90:93]
	v_mfma_f32_16x16x32_bf16 v[90:93], v[156:159], v[196:199], v[90:93]
	v_mfma_f32_16x16x32_bf16 v[86:89], v[160:163], v[192:195], v[86:89]
	v_mfma_f32_16x16x32_bf16 v[86:89], v[164:167], v[196:199], v[86:89]
	v_mfma_f32_16x16x32_bf16 v[82:85], v[168:171], v[192:195], v[82:85]
	v_mfma_f32_16x16x32_bf16 v[82:85], v[172:175], v[196:199], v[82:85]
	v_mfma_f32_16x16x32_bf16 v[66:69], v[168:171], v[200:203], v[66:69]
	v_mfma_f32_16x16x32_bf16 v[66:69], v[172:175], v[204:207], v[66:69]
	v_mfma_f32_16x16x32_bf16 v[70:73], v[160:163], v[200:203], v[70:73]
	v_mfma_f32_16x16x32_bf16 v[70:73], v[164:167], v[204:207], v[70:73]
	v_mfma_f32_16x16x32_bf16 v[74:77], v[152:155], v[200:203], v[74:77]
	v_mfma_f32_16x16x32_bf16 v[74:77], v[156:159], v[204:207], v[74:77]
	v_mfma_f32_16x16x32_bf16 v[78:81], v[140:143], v[200:203], v[78:81]
	v_mfma_f32_16x16x32_bf16 v[78:81], v[148:151], v[204:207], v[78:81]
	s_setprio 0
	s_barrier
	ds_read_b128 v[176:179], v136 offset:16384
	ds_read_b128 v[180:183], v136 offset:17408
	ds_read_b128 v[184:187], v136 offset:18432
	ds_read_b128 v[188:191], v136 offset:19456
	ds_read_b128 v[192:195], v136 offset:20480
	ds_read_b128 v[196:199], v136 offset:21504
	ds_read_b128 v[200:203], v136 offset:22528
	ds_read_b128 v[204:207], v136 offset:23552
	s_mov_b32 m0, s30
	s_nop 0
	buffer_load_dwordx4 v133, s[16:19], s75 offen lds
	s_add_i32 s76, s75, 0x200000
	s_mov_b32 m0, s31
	s_nop 0
	buffer_load_dwordx4 v133, s[16:19], s76 offen lds
	s_add_i32 s76, s75, 0x400000
	s_mov_b32 m0, s35
	s_nop 0
	buffer_load_dwordx4 v133, s[16:19], s76 offen lds
	s_add_i32 s76, s75, 0x600000
	s_mov_b32 m0, s42
	s_nop 0
	buffer_load_dwordx4 v133, s[16:19], s76 offen lds
	s_mov_b32 m0, s27
	s_add_i32 s76, s73, 0x18000
	buffer_load_dwordx4 v132, s[12:15], s73 offen lds
	s_mov_b32 m0, s43
	s_nop 0
	buffer_load_dwordx4 v132, s[12:15], s76 offen lds
	s_waitcnt vmcnt(8)
	s_waitcnt lgkmcnt(0)
	s_setprio 1
	v_mfma_f32_16x16x32_bf16 v[62:65], v[140:143], v[176:179], v[62:65]
	s_barrier
	v_mfma_f32_16x16x32_bf16 v[62:65], v[148:151], v[180:183], v[62:65]
	v_mfma_f32_16x16x32_bf16 v[58:61], v[152:155], v[176:179], v[58:61]
	v_mfma_f32_16x16x32_bf16 v[58:61], v[156:159], v[180:183], v[58:61]
	v_mfma_f32_16x16x32_bf16 v[54:57], v[160:163], v[176:179], v[54:57]
	v_mfma_f32_16x16x32_bf16 v[54:57], v[164:167], v[180:183], v[54:57]
	v_mfma_f32_16x16x32_bf16 v[50:53], v[168:171], v[176:179], v[50:53]
	v_mfma_f32_16x16x32_bf16 v[50:53], v[172:175], v[180:183], v[50:53]
	v_mfma_f32_16x16x32_bf16 v[34:37], v[168:171], v[184:187], v[34:37]
	v_mfma_f32_16x16x32_bf16 v[34:37], v[172:175], v[188:191], v[34:37]
	v_mfma_f32_16x16x32_bf16 v[38:41], v[160:163], v[184:187], v[38:41]
	v_mfma_f32_16x16x32_bf16 v[38:41], v[164:167], v[188:191], v[38:41]
	v_mfma_f32_16x16x32_bf16 v[42:45], v[152:155], v[184:187], v[42:45]
	v_mfma_f32_16x16x32_bf16 v[42:45], v[156:159], v[188:191], v[42:45]
	v_mfma_f32_16x16x32_bf16 v[46:49], v[140:143], v[184:187], v[46:49]
	v_mfma_f32_16x16x32_bf16 v[46:49], v[148:151], v[188:191], v[46:49]
	v_mfma_f32_16x16x32_bf16 v[30:33], v[140:143], v[192:195], v[30:33]
	v_mfma_f32_16x16x32_bf16 v[30:33], v[148:151], v[196:199], v[30:33]
	v_mfma_f32_16x16x32_bf16 v[26:29], v[152:155], v[192:195], v[26:29]
	v_mfma_f32_16x16x32_bf16 v[26:29], v[156:159], v[196:199], v[26:29]
	v_mfma_f32_16x16x32_bf16 v[22:25], v[160:163], v[192:195], v[22:25]
	v_mfma_f32_16x16x32_bf16 v[22:25], v[164:167], v[196:199], v[22:25]
	v_mfma_f32_16x16x32_bf16 v[18:21], v[168:171], v[192:195], v[18:21]
	v_mfma_f32_16x16x32_bf16 v[18:21], v[172:175], v[196:199], v[18:21]
	v_mfma_f32_16x16x32_bf16 v[2:5], v[168:171], v[200:203], v[2:5]
	v_mfma_f32_16x16x32_bf16 v[2:5], v[172:175], v[204:207], v[2:5]
	v_mfma_f32_16x16x32_bf16 v[6:9], v[160:163], v[200:203], v[6:9]
	v_mfma_f32_16x16x32_bf16 v[6:9], v[164:167], v[204:207], v[6:9]
	v_mfma_f32_16x16x32_bf16 v[10:13], v[152:155], v[200:203], v[10:13]
	v_mfma_f32_16x16x32_bf16 v[10:13], v[156:159], v[204:207], v[10:13]
	v_mfma_f32_16x16x32_bf16 v[14:17], v[140:143], v[200:203], v[14:17]
	v_mfma_f32_16x16x32_bf16 v[14:17], v[148:151], v[204:207], v[14:17]
	s_setprio 0
	s_barrier
	ds_read_b128 v[140:143], v137
	ds_read_b128 v[148:151], v137 offset:1024
	ds_read_b128 v[152:155], v137 offset:2048
	ds_read_b128 v[156:159], v137 offset:3072
	ds_read_b128 v[160:163], v138
	ds_read_b128 v[164:167], v138 offset:1024
	ds_read_b128 v[168:171], v138 offset:2048
	ds_read_b128 v[172:175], v138 offset:3072
	ds_read_b128 v[176:179], v136 offset:32768
	ds_read_b128 v[180:183], v136 offset:33792
	ds_read_b128 v[184:187], v136 offset:34816
	ds_read_b128 v[188:191], v136 offset:35840
	ds_read_b128 v[192:195], v136 offset:36864
	ds_read_b128 v[196:199], v136 offset:37888
	ds_read_b128 v[200:203], v136 offset:38912
	ds_read_b128 v[204:207], v136 offset:39936
	s_mov_b32 m0, s44
	s_add_i32 s76, s73, 0x30000
	buffer_load_dwordx4 v132, s[12:15], s76 offen lds
	s_add_i32 s76, s73, 0x48000
	s_mov_b32 m0, s45
	s_nop 0
	buffer_load_dwordx4 v132, s[12:15], s76 offen lds
	s_waitcnt vmcnt(8)
	s_waitcnt lgkmcnt(0)
	s_setprio 1
	v_mfma_f32_16x16x32_bf16 v[126:129], v[140:143], v[176:179], v[126:129]
	s_barrier
	v_mfma_f32_16x16x32_bf16 v[126:129], v[148:151], v[180:183], v[126:129]
	v_mfma_f32_16x16x32_bf16 v[122:125], v[152:155], v[176:179], v[122:125]
	v_mfma_f32_16x16x32_bf16 v[122:125], v[156:159], v[180:183], v[122:125]
	v_mfma_f32_16x16x32_bf16 v[118:121], v[160:163], v[176:179], v[118:121]
	v_mfma_f32_16x16x32_bf16 v[118:121], v[164:167], v[180:183], v[118:121]
	v_mfma_f32_16x16x32_bf16 v[114:117], v[168:171], v[176:179], v[114:117]
	v_mfma_f32_16x16x32_bf16 v[114:117], v[172:175], v[180:183], v[114:117]
	v_mfma_f32_16x16x32_bf16 v[98:101], v[168:171], v[184:187], v[98:101]
	v_mfma_f32_16x16x32_bf16 v[98:101], v[172:175], v[188:191], v[98:101]
	v_mfma_f32_16x16x32_bf16 v[102:105], v[160:163], v[184:187], v[102:105]
	v_mfma_f32_16x16x32_bf16 v[102:105], v[164:167], v[188:191], v[102:105]
	v_mfma_f32_16x16x32_bf16 v[106:109], v[152:155], v[184:187], v[106:109]
	v_mfma_f32_16x16x32_bf16 v[106:109], v[156:159], v[188:191], v[106:109]
	v_mfma_f32_16x16x32_bf16 v[110:113], v[140:143], v[184:187], v[110:113]
	v_mfma_f32_16x16x32_bf16 v[110:113], v[148:151], v[188:191], v[110:113]
	v_mfma_f32_16x16x32_bf16 v[94:97], v[140:143], v[192:195], v[94:97]
	v_mfma_f32_16x16x32_bf16 v[94:97], v[148:151], v[196:199], v[94:97]
	v_mfma_f32_16x16x32_bf16 v[90:93], v[152:155], v[192:195], v[90:93]
	v_mfma_f32_16x16x32_bf16 v[90:93], v[156:159], v[196:199], v[90:93]
	v_mfma_f32_16x16x32_bf16 v[86:89], v[160:163], v[192:195], v[86:89]
	v_mfma_f32_16x16x32_bf16 v[86:89], v[164:167], v[196:199], v[86:89]
	v_mfma_f32_16x16x32_bf16 v[82:85], v[168:171], v[192:195], v[82:85]
	v_mfma_f32_16x16x32_bf16 v[82:85], v[172:175], v[196:199], v[82:85]
	v_mfma_f32_16x16x32_bf16 v[66:69], v[168:171], v[200:203], v[66:69]
	v_mfma_f32_16x16x32_bf16 v[66:69], v[172:175], v[204:207], v[66:69]
	v_mfma_f32_16x16x32_bf16 v[70:73], v[160:163], v[200:203], v[70:73]
	v_mfma_f32_16x16x32_bf16 v[70:73], v[164:167], v[204:207], v[70:73]
	v_mfma_f32_16x16x32_bf16 v[74:77], v[152:155], v[200:203], v[74:77]
	v_mfma_f32_16x16x32_bf16 v[74:77], v[156:159], v[204:207], v[74:77]
	v_mfma_f32_16x16x32_bf16 v[78:81], v[140:143], v[200:203], v[78:81]
	v_mfma_f32_16x16x32_bf16 v[78:81], v[148:151], v[204:207], v[78:81]
	s_setprio 0
	s_barrier
	ds_read_b128 v[176:179], v136 offset:49152
	ds_read_b128 v[180:183], v136 offset:50176
	ds_read_b128 v[184:187], v136 offset:51200
	ds_read_b128 v[188:191], v136 offset:52224
	ds_read_b128 v[192:195], v136 offset:53248
	ds_read_b128 v[196:199], v136 offset:54272
	ds_read_b128 v[200:203], v136 offset:55296
	ds_read_b128 v[204:207], v136 offset:56320
	s_mov_b32 m0, s46
	s_add_i32 s76, s75, 0x80
	buffer_load_dwordx4 v133, s[16:19], s76 offen lds
	s_add_i32 s76, s75, 0x200080
	s_mov_b32 m0, s47
	s_add_i32 s73, s73, 0x18080
	buffer_load_dwordx4 v133, s[16:19], s76 offen lds
	s_add_i32 s76, s75, 0x400080
	s_mov_b32 m0, s50
	s_add_i32 s75, s75, 0x600080
	buffer_load_dwordx4 v133, s[16:19], s76 offen lds
	s_mov_b32 m0, s51
	s_nop 0
	buffer_load_dwordx4 v133, s[16:19], s75 offen lds
	s_mov_b32 m0, s48
	s_nop 0
	buffer_load_dwordx4 v132, s[12:15], s74 offen lds
	s_mov_b32 m0, s49
	s_nop 0
	buffer_load_dwordx4 v132, s[12:15], s73 offen lds
	s_waitcnt vmcnt(8)
	s_waitcnt lgkmcnt(0)
	s_setprio 1
	v_mfma_f32_16x16x32_bf16 v[62:65], v[140:143], v[176:179], v[62:65]
	s_barrier
	v_mfma_f32_16x16x32_bf16 v[62:65], v[148:151], v[180:183], v[62:65]
	v_mfma_f32_16x16x32_bf16 v[58:61], v[152:155], v[176:179], v[58:61]
	v_mfma_f32_16x16x32_bf16 v[58:61], v[156:159], v[180:183], v[58:61]
	v_mfma_f32_16x16x32_bf16 v[54:57], v[160:163], v[176:179], v[54:57]
	v_mfma_f32_16x16x32_bf16 v[54:57], v[164:167], v[180:183], v[54:57]
	v_mfma_f32_16x16x32_bf16 v[50:53], v[168:171], v[176:179], v[50:53]
	v_mfma_f32_16x16x32_bf16 v[50:53], v[172:175], v[180:183], v[50:53]
	v_mfma_f32_16x16x32_bf16 v[34:37], v[168:171], v[184:187], v[34:37]
	v_mfma_f32_16x16x32_bf16 v[34:37], v[172:175], v[188:191], v[34:37]
	v_mfma_f32_16x16x32_bf16 v[38:41], v[160:163], v[184:187], v[38:41]
	v_mfma_f32_16x16x32_bf16 v[38:41], v[164:167], v[188:191], v[38:41]
	v_mfma_f32_16x16x32_bf16 v[42:45], v[152:155], v[184:187], v[42:45]
	v_mfma_f32_16x16x32_bf16 v[42:45], v[156:159], v[188:191], v[42:45]
	v_mfma_f32_16x16x32_bf16 v[46:49], v[140:143], v[184:187], v[46:49]
	v_mfma_f32_16x16x32_bf16 v[46:49], v[148:151], v[188:191], v[46:49]
	v_mfma_f32_16x16x32_bf16 v[30:33], v[140:143], v[192:195], v[30:33]
	v_mfma_f32_16x16x32_bf16 v[30:33], v[148:151], v[196:199], v[30:33]
	v_mfma_f32_16x16x32_bf16 v[26:29], v[152:155], v[192:195], v[26:29]
	v_mfma_f32_16x16x32_bf16 v[26:29], v[156:159], v[196:199], v[26:29]
	v_mfma_f32_16x16x32_bf16 v[22:25], v[160:163], v[192:195], v[22:25]
	v_mfma_f32_16x16x32_bf16 v[22:25], v[164:167], v[196:199], v[22:25]
	v_mfma_f32_16x16x32_bf16 v[18:21], v[168:171], v[192:195], v[18:21]
	v_mfma_f32_16x16x32_bf16 v[18:21], v[172:175], v[196:199], v[18:21]
	v_mfma_f32_16x16x32_bf16 v[2:5], v[168:171], v[200:203], v[2:5]
	v_mfma_f32_16x16x32_bf16 v[2:5], v[172:175], v[204:207], v[2:5]
	v_mfma_f32_16x16x32_bf16 v[6:9], v[160:163], v[200:203], v[6:9]
	v_mfma_f32_16x16x32_bf16 v[6:9], v[164:167], v[204:207], v[6:9]
	v_mfma_f32_16x16x32_bf16 v[10:13], v[152:155], v[200:203], v[10:13]
	v_mfma_f32_16x16x32_bf16 v[10:13], v[156:159], v[204:207], v[10:13]
	v_mfma_f32_16x16x32_bf16 v[14:17], v[140:143], v[200:203], v[14:17]
	v_mfma_f32_16x16x32_bf16 v[14:17], v[148:151], v[204:207], v[14:17]
	s_setprio 0
	s_barrier
	s_add_i32 s72, s72, 2
	s_addk_i32 s70, 0x100
	s_addk_i32 s71, 0x100
	s_cmp_ge_i32 s72, s21
	s_cbranch_scc0 .LBB0_1035

.LBB0_1050:
	ds_read_b128 v[132:135], v142
	ds_read_b128 v[136:139], v142 offset:1024
	ds_read_b128 v[148:151], v142 offset:2048
	ds_read_b128 v[152:155], v142 offset:3072
	ds_read_b128 v[156:159], v143
	ds_read_b128 v[160:163], v143 offset:1024
	ds_read_b128 v[164:167], v143 offset:2048
	ds_read_b128 v[168:171], v143 offset:3072
	ds_read_b128 v[172:175], v144
	ds_read_b128 v[176:179], v144 offset:1024
	ds_read_b128 v[180:183], v144 offset:2048
	ds_read_b128 v[184:187], v144 offset:3072
	ds_read_b128 v[188:191], v144 offset:4096
	ds_read_b128 v[192:195], v144 offset:5120
	ds_read_b128 v[196:199], v144 offset:6144
	ds_read_b128 v[200:203], v144 offset:7168
	s_add_i32 s18, s61, 0xfff40080
	s_cmp_eq_u32 s54, s62
	s_cselect_b32 s64, s35, s18
	s_add_i32 s63, s64, 0x80
	s_add_i32 s18, s61, 0xfffc0000
	s_mov_b32 m0, s55
	s_nop 0
	buffer_load_dwordx4 v140, s[12:15], s18 offen lds
	s_mov_b32 m0, s56
	s_nop 0
	buffer_load_dwordx4 v140, s[12:15], s61 offen lds
	s_waitcnt vmcnt(8)
	s_waitcnt lgkmcnt(0)
	s_setprio 1
	v_mfma_f32_16x16x32_bf16 v[126:129], v[132:135], v[172:175], v[126:129]
	s_barrier
	v_mfma_f32_16x16x32_bf16 v[126:129], v[136:139], v[176:179], v[126:129]
	v_mfma_f32_16x16x32_bf16 v[122:125], v[148:151], v[172:175], v[122:125]
	v_mfma_f32_16x16x32_bf16 v[122:125], v[152:155], v[176:179], v[122:125]
	v_mfma_f32_16x16x32_bf16 v[118:121], v[156:159], v[172:175], v[118:121]
	v_mfma_f32_16x16x32_bf16 v[118:121], v[160:163], v[176:179], v[118:121]
	v_mfma_f32_16x16x32_bf16 v[114:117], v[164:167], v[172:175], v[114:117]
	v_mfma_f32_16x16x32_bf16 v[114:117], v[168:171], v[176:179], v[114:117]
	v_mfma_f32_16x16x32_bf16 v[98:101], v[164:167], v[180:183], v[98:101]
	v_mfma_f32_16x16x32_bf16 v[98:101], v[168:171], v[184:187], v[98:101]
	v_mfma_f32_16x16x32_bf16 v[102:105], v[156:159], v[180:183], v[102:105]
	v_mfma_f32_16x16x32_bf16 v[102:105], v[160:163], v[184:187], v[102:105]
	v_mfma_f32_16x16x32_bf16 v[106:109], v[148:151], v[180:183], v[106:109]
	v_mfma_f32_16x16x32_bf16 v[106:109], v[152:155], v[184:187], v[106:109]
	v_mfma_f32_16x16x32_bf16 v[110:113], v[132:135], v[180:183], v[110:113]
	v_mfma_f32_16x16x32_bf16 v[110:113], v[136:139], v[184:187], v[110:113]
	v_mfma_f32_16x16x32_bf16 v[94:97], v[132:135], v[188:191], v[94:97]
	v_mfma_f32_16x16x32_bf16 v[94:97], v[136:139], v[192:195], v[94:97]
	v_mfma_f32_16x16x32_bf16 v[90:93], v[148:151], v[188:191], v[90:93]
	v_mfma_f32_16x16x32_bf16 v[90:93], v[152:155], v[192:195], v[90:93]
	v_mfma_f32_16x16x32_bf16 v[86:89], v[156:159], v[188:191], v[86:89]
	v_mfma_f32_16x16x32_bf16 v[86:89], v[160:163], v[192:195], v[86:89]
	v_mfma_f32_16x16x32_bf16 v[82:85], v[164:167], v[188:191], v[82:85]
	v_mfma_f32_16x16x32_bf16 v[82:85], v[168:171], v[192:195], v[82:85]
	v_mfma_f32_16x16x32_bf16 v[66:69], v[164:167], v[196:199], v[66:69]
	v_mfma_f32_16x16x32_bf16 v[66:69], v[168:171], v[200:203], v[66:69]
	v_mfma_f32_16x16x32_bf16 v[70:73], v[156:159], v[196:199], v[70:73]
	v_mfma_f32_16x16x32_bf16 v[70:73], v[160:163], v[200:203], v[70:73]
	v_mfma_f32_16x16x32_bf16 v[74:77], v[148:151], v[196:199], v[74:77]
	v_mfma_f32_16x16x32_bf16 v[74:77], v[152:155], v[200:203], v[74:77]
	v_mfma_f32_16x16x32_bf16 v[78:81], v[132:135], v[196:199], v[78:81]
	v_mfma_f32_16x16x32_bf16 v[78:81], v[136:139], v[200:203], v[78:81]
	s_setprio 0
	s_barrier
	ds_read_b128 v[172:175], v144 offset:16384
	ds_read_b128 v[176:179], v144 offset:17408
	ds_read_b128 v[180:183], v144 offset:18432
	ds_read_b128 v[184:187], v144 offset:19456
	ds_read_b128 v[188:191], v144 offset:20480
	ds_read_b128 v[192:195], v144 offset:21504
	ds_read_b128 v[196:199], v144 offset:22528
	ds_read_b128 v[200:203], v144 offset:23552
	s_mov_b32 m0, s25
	s_mov_b32 s18, s14
	s_mov_b32 s19, s15
	buffer_load_dwordx4 v141, s[16:19], s64 offen lds
	s_add_i32 s65, s64, 0x40000
	s_mov_b32 m0, s27
	s_add_i32 s66, s64, 0x80000
	buffer_load_dwordx4 v141, s[16:19], s65 offen lds
	s_mov_b32 m0, s30
	s_add_i32 s67, s64, 0xc0000
	buffer_load_dwordx4 v141, s[16:19], s66 offen lds
	s_mov_b32 m0, s31
	s_nop 0
	buffer_load_dwordx4 v141, s[16:19], s67 offen lds
	s_mov_b32 m0, s21
	s_nop 0
	buffer_load_dwordx4 v140, s[12:15], s64 offen lds
	s_mov_b32 m0, s38
	s_nop 0
	buffer_load_dwordx4 v140, s[12:15], s65 offen lds
	s_waitcnt vmcnt(8)
	s_waitcnt lgkmcnt(0)
	s_setprio 1
	v_mfma_f32_16x16x32_bf16 v[62:65], v[132:135], v[172:175], v[62:65]
	s_barrier
	v_mfma_f32_16x16x32_bf16 v[62:65], v[136:139], v[176:179], v[62:65]
	v_mfma_f32_16x16x32_bf16 v[58:61], v[148:151], v[172:175], v[58:61]
	v_mfma_f32_16x16x32_bf16 v[58:61], v[152:155], v[176:179], v[58:61]
	v_mfma_f32_16x16x32_bf16 v[54:57], v[156:159], v[172:175], v[54:57]
	v_mfma_f32_16x16x32_bf16 v[54:57], v[160:163], v[176:179], v[54:57]
	v_mfma_f32_16x16x32_bf16 v[50:53], v[164:167], v[172:175], v[50:53]
	v_mfma_f32_16x16x32_bf16 v[50:53], v[168:171], v[176:179], v[50:53]
	v_mfma_f32_16x16x32_bf16 v[34:37], v[164:167], v[180:183], v[34:37]
	v_mfma_f32_16x16x32_bf16 v[34:37], v[168:171], v[184:187], v[34:37]
	v_mfma_f32_16x16x32_bf16 v[38:41], v[156:159], v[180:183], v[38:41]
	v_mfma_f32_16x16x32_bf16 v[38:41], v[160:163], v[184:187], v[38:41]
	v_mfma_f32_16x16x32_bf16 v[42:45], v[148:151], v[180:183], v[42:45]
	v_mfma_f32_16x16x32_bf16 v[42:45], v[152:155], v[184:187], v[42:45]
	v_mfma_f32_16x16x32_bf16 v[46:49], v[132:135], v[180:183], v[46:49]
	v_mfma_f32_16x16x32_bf16 v[46:49], v[136:139], v[184:187], v[46:49]
	v_mfma_f32_16x16x32_bf16 v[30:33], v[132:135], v[188:191], v[30:33]
	v_mfma_f32_16x16x32_bf16 v[30:33], v[136:139], v[192:195], v[30:33]
	v_mfma_f32_16x16x32_bf16 v[26:29], v[148:151], v[188:191], v[26:29]
	v_mfma_f32_16x16x32_bf16 v[26:29], v[152:155], v[192:195], v[26:29]
	v_mfma_f32_16x16x32_bf16 v[22:25], v[156:159], v[188:191], v[22:25]
	v_mfma_f32_16x16x32_bf16 v[22:25], v[160:163], v[192:195], v[22:25]
	v_mfma_f32_16x16x32_bf16 v[18:21], v[164:167], v[188:191], v[18:21]
	v_mfma_f32_16x16x32_bf16 v[18:21], v[168:171], v[192:195], v[18:21]
	v_mfma_f32_16x16x32_bf16 v[2:5], v[164:167], v[196:199], v[2:5]
	v_mfma_f32_16x16x32_bf16 v[2:5], v[168:171], v[200:203], v[2:5]
	v_mfma_f32_16x16x32_bf16 v[6:9], v[156:159], v[196:199], v[6:9]
	v_mfma_f32_16x16x32_bf16 v[6:9], v[160:163], v[200:203], v[6:9]
	v_mfma_f32_16x16x32_bf16 v[10:13], v[148:151], v[196:199], v[10:13]
	v_mfma_f32_16x16x32_bf16 v[10:13], v[152:155], v[200:203], v[10:13]
	v_mfma_f32_16x16x32_bf16 v[14:17], v[132:135], v[196:199], v[14:17]
	v_mfma_f32_16x16x32_bf16 v[14:17], v[136:139], v[200:203], v[14:17]
	s_setprio 0
	s_barrier
	ds_read_b128 v[132:135], v145
	ds_read_b128 v[136:139], v145 offset:1024
	ds_read_b128 v[148:151], v145 offset:2048
	ds_read_b128 v[152:155], v145 offset:3072
	ds_read_b128 v[156:159], v147
	ds_read_b128 v[160:163], v147 offset:1024
	ds_read_b128 v[164:167], v147 offset:2048
	ds_read_b128 v[168:171], v147 offset:3072
	ds_read_b128 v[172:175], v144 offset:32768
	ds_read_b128 v[176:179], v144 offset:33792
	ds_read_b128 v[180:183], v144 offset:34816
	ds_read_b128 v[184:187], v144 offset:35840
	ds_read_b128 v[188:191], v144 offset:36864
	ds_read_b128 v[192:195], v144 offset:37888
	ds_read_b128 v[196:199], v144 offset:38912
	ds_read_b128 v[200:203], v144 offset:39936
	s_mov_b32 m0, s39
	s_nop 0
	buffer_load_dwordx4 v140, s[12:15], s66 offen lds
	s_mov_b32 m0, s40
	s_nop 0
	buffer_load_dwordx4 v140, s[12:15], s67 offen lds
	s_waitcnt vmcnt(8)
	s_waitcnt lgkmcnt(0)
	s_setprio 1
	v_mfma_f32_16x16x32_bf16 v[126:129], v[132:135], v[172:175], v[126:129]
	s_barrier
	v_mfma_f32_16x16x32_bf16 v[126:129], v[136:139], v[176:179], v[126:129]
	v_mfma_f32_16x16x32_bf16 v[122:125], v[148:151], v[172:175], v[122:125]
	v_mfma_f32_16x16x32_bf16 v[122:125], v[152:155], v[176:179], v[122:125]
	v_mfma_f32_16x16x32_bf16 v[118:121], v[156:159], v[172:175], v[118:121]
	v_mfma_f32_16x16x32_bf16 v[118:121], v[160:163], v[176:179], v[118:121]
	v_mfma_f32_16x16x32_bf16 v[114:117], v[164:167], v[172:175], v[114:117]
	v_mfma_f32_16x16x32_bf16 v[114:117], v[168:171], v[176:179], v[114:117]
	v_mfma_f32_16x16x32_bf16 v[98:101], v[164:167], v[180:183], v[98:101]
	v_mfma_f32_16x16x32_bf16 v[98:101], v[168:171], v[184:187], v[98:101]
	v_mfma_f32_16x16x32_bf16 v[102:105], v[156:159], v[180:183], v[102:105]
	v_mfma_f32_16x16x32_bf16 v[102:105], v[160:163], v[184:187], v[102:105]
	v_mfma_f32_16x16x32_bf16 v[106:109], v[148:151], v[180:183], v[106:109]
	v_mfma_f32_16x16x32_bf16 v[106:109], v[152:155], v[184:187], v[106:109]
	v_mfma_f32_16x16x32_bf16 v[110:113], v[132:135], v[180:183], v[110:113]
	v_mfma_f32_16x16x32_bf16 v[110:113], v[136:139], v[184:187], v[110:113]
	v_mfma_f32_16x16x32_bf16 v[94:97], v[132:135], v[188:191], v[94:97]
	v_mfma_f32_16x16x32_bf16 v[94:97], v[136:139], v[192:195], v[94:97]
	v_mfma_f32_16x16x32_bf16 v[90:93], v[148:151], v[188:191], v[90:93]
	v_mfma_f32_16x16x32_bf16 v[90:93], v[152:155], v[192:195], v[90:93]
	v_mfma_f32_16x16x32_bf16 v[86:89], v[156:159], v[188:191], v[86:89]
	v_mfma_f32_16x16x32_bf16 v[86:89], v[160:163], v[192:195], v[86:89]
	v_mfma_f32_16x16x32_bf16 v[82:85], v[164:167], v[188:191], v[82:85]
	v_mfma_f32_16x16x32_bf16 v[82:85], v[168:171], v[192:195], v[82:85]
	v_mfma_f32_16x16x32_bf16 v[66:69], v[164:167], v[196:199], v[66:69]
	v_mfma_f32_16x16x32_bf16 v[66:69], v[168:171], v[200:203], v[66:69]
	v_mfma_f32_16x16x32_bf16 v[70:73], v[156:159], v[196:199], v[70:73]
	v_mfma_f32_16x16x32_bf16 v[70:73], v[160:163], v[200:203], v[70:73]
	v_mfma_f32_16x16x32_bf16 v[74:77], v[148:151], v[196:199], v[74:77]
	v_mfma_f32_16x16x32_bf16 v[74:77], v[152:155], v[200:203], v[74:77]
	v_mfma_f32_16x16x32_bf16 v[78:81], v[132:135], v[196:199], v[78:81]
	v_mfma_f32_16x16x32_bf16 v[78:81], v[136:139], v[200:203], v[78:81]
	s_setprio 0
	s_barrier
	ds_read_b128 v[172:175], v144 offset:49152
	ds_read_b128 v[176:179], v144 offset:50176
	ds_read_b128 v[180:183], v144 offset:51200
	ds_read_b128 v[184:187], v144 offset:52224
	ds_read_b128 v[188:191], v144 offset:53248
	ds_read_b128 v[192:195], v144 offset:54272
	ds_read_b128 v[196:199], v144 offset:55296
	ds_read_b128 v[200:203], v144 offset:56320
	s_mov_b32 m0, s48
	s_nop 0
	buffer_load_dwordx4 v141, s[16:19], s63 offen lds
	s_add_i32 s65, s64, 0x40080
	s_mov_b32 m0, s49
	s_add_i32 s66, s64, 0x80080
	buffer_load_dwordx4 v141, s[16:19], s65 offen lds
	s_mov_b32 m0, s52
	s_add_i32 s64, s64, 0xc0080
	buffer_load_dwordx4 v141, s[16:19], s66 offen lds
	s_mov_b32 m0, s53
	s_nop 0
	buffer_load_dwordx4 v141, s[16:19], s64 offen lds
	s_mov_b32 m0, s50
	s_nop 0
	buffer_load_dwordx4 v140, s[12:15], s63 offen lds
	s_mov_b32 m0, s51
	s_nop 0
	buffer_load_dwordx4 v140, s[12:15], s65 offen lds
	s_waitcnt vmcnt(8)
	s_waitcnt lgkmcnt(0)
	s_setprio 1
	v_mfma_f32_16x16x32_bf16 v[62:65], v[132:135], v[172:175], v[62:65]
	s_barrier
	v_mfma_f32_16x16x32_bf16 v[62:65], v[136:139], v[176:179], v[62:65]
	v_mfma_f32_16x16x32_bf16 v[58:61], v[148:151], v[172:175], v[58:61]
	v_mfma_f32_16x16x32_bf16 v[58:61], v[152:155], v[176:179], v[58:61]
	v_mfma_f32_16x16x32_bf16 v[54:57], v[156:159], v[172:175], v[54:57]
	v_mfma_f32_16x16x32_bf16 v[54:57], v[160:163], v[176:179], v[54:57]
	v_mfma_f32_16x16x32_bf16 v[50:53], v[164:167], v[172:175], v[50:53]
	v_mfma_f32_16x16x32_bf16 v[50:53], v[168:171], v[176:179], v[50:53]
	v_mfma_f32_16x16x32_bf16 v[34:37], v[164:167], v[180:183], v[34:37]
	v_mfma_f32_16x16x32_bf16 v[34:37], v[168:171], v[184:187], v[34:37]
	v_mfma_f32_16x16x32_bf16 v[38:41], v[156:159], v[180:183], v[38:41]
	v_mfma_f32_16x16x32_bf16 v[38:41], v[160:163], v[184:187], v[38:41]
	v_mfma_f32_16x16x32_bf16 v[42:45], v[148:151], v[180:183], v[42:45]
	v_mfma_f32_16x16x32_bf16 v[42:45], v[152:155], v[184:187], v[42:45]
	v_mfma_f32_16x16x32_bf16 v[46:49], v[132:135], v[180:183], v[46:49]
	v_mfma_f32_16x16x32_bf16 v[46:49], v[136:139], v[184:187], v[46:49]
	v_mfma_f32_16x16x32_bf16 v[30:33], v[132:135], v[188:191], v[30:33]
	v_mfma_f32_16x16x32_bf16 v[30:33], v[136:139], v[192:195], v[30:33]
	v_mfma_f32_16x16x32_bf16 v[26:29], v[148:151], v[188:191], v[26:29]
	v_mfma_f32_16x16x32_bf16 v[26:29], v[152:155], v[192:195], v[26:29]
	v_mfma_f32_16x16x32_bf16 v[22:25], v[156:159], v[188:191], v[22:25]
	v_mfma_f32_16x16x32_bf16 v[22:25], v[160:163], v[192:195], v[22:25]
	v_mfma_f32_16x16x32_bf16 v[18:21], v[164:167], v[188:191], v[18:21]
	v_mfma_f32_16x16x32_bf16 v[18:21], v[168:171], v[192:195], v[18:21]
	v_mfma_f32_16x16x32_bf16 v[2:5], v[164:167], v[196:199], v[2:5]
	v_mfma_f32_16x16x32_bf16 v[2:5], v[168:171], v[200:203], v[2:5]
	v_mfma_f32_16x16x32_bf16 v[6:9], v[156:159], v[196:199], v[6:9]
	v_mfma_f32_16x16x32_bf16 v[6:9], v[160:163], v[200:203], v[6:9]
	v_mfma_f32_16x16x32_bf16 v[10:13], v[148:151], v[196:199], v[10:13]
	v_mfma_f32_16x16x32_bf16 v[10:13], v[152:155], v[200:203], v[10:13]
	v_mfma_f32_16x16x32_bf16 v[14:17], v[132:135], v[196:199], v[14:17]
	v_mfma_f32_16x16x32_bf16 v[14:17], v[136:139], v[200:203], v[14:17]
	s_setprio 0
	s_barrier
	s_add_i32 s62, s62, 2
	s_addk_i32 s61, 0x100
	s_cmp_ge_i32 s62, s3
	s_cbranch_scc0 .LBB0_1050

.LBB0_1181:
	v_add_u32_e32 v2, 0x10000, v232
	ds_read_b128 v[134:137], v2
	ds_read_b128 v[138:141], v2 offset:1024
	ds_read_b128 v[142:145], v2 offset:2048
	ds_read_b128 v[146:149], v2 offset:3072
	v_add_u32_e32 v2, 0x14000, v232
	ds_read_b128 v[150:153], v2
	ds_read_b128 v[154:157], v2 offset:1024
	ds_read_b128 v[158:161], v2 offset:2048
	ds_read_b128 v[162:165], v2 offset:3072
	s_add_i32 s50, s47, s90
	s_and_b64 s[18:19], exec, s[18:19]
	s_cselect_b32 s51, s88, s50
	s_add_i32 s50, s92, 0x80
	s_or_b32 s52, s51, 0x80
	s_add_i32 s18, s89, s93
	s_add_i32 s94, s94, 0x1bfffc80
	s_cmp_lt_u32 s91, 8
	s_cselect_b32 s18, s18, s94
	s_mov_b32 m0, s74
	s_add_i32 s19, s18, 0x80000
	ds_read_b128 v[166:169], v233
	ds_read_b128 v[170:173], v233 offset:1024
	ds_read_b128 v[174:177], v233 offset:2048
	ds_read_b128 v[178:181], v233 offset:3072
	ds_read_b128 v[182:185], v233 offset:4096
	ds_read_b128 v[186:189], v233 offset:5120
	ds_read_b128 v[190:193], v233 offset:6144
	ds_read_b128 v[194:197], v233 offset:7168
	buffer_load_dwordx4 v230, s[12:15], s19 offen lds
	s_add_i32 s18, s18, 0xc0000
	s_mov_b32 m0, s75
	s_nop 0
	buffer_load_dwordx4 v230, s[12:15], s18 offen lds
	s_waitcnt vmcnt(8)
	s_waitcnt lgkmcnt(0)
	s_setprio 1
	v_mfma_f32_16x16x32_bf16 v[130:133], v[134:137], v[166:169], v[130:133]
	s_barrier
	v_mfma_f32_16x16x32_bf16 v[130:133], v[138:141], v[170:173], v[130:133]
	v_mfma_f32_16x16x32_bf16 v[126:129], v[142:145], v[166:169], v[126:129]
	v_mfma_f32_16x16x32_bf16 v[126:129], v[146:149], v[170:173], v[126:129]
	v_mfma_f32_16x16x32_bf16 v[122:125], v[150:153], v[166:169], v[122:125]
	v_mfma_f32_16x16x32_bf16 v[122:125], v[154:157], v[170:173], v[122:125]
	v_mfma_f32_16x16x32_bf16 v[118:121], v[158:161], v[166:169], v[118:121]
	v_mfma_f32_16x16x32_bf16 v[118:121], v[162:165], v[170:173], v[118:121]
	v_mfma_f32_16x16x32_bf16 v[102:105], v[158:161], v[174:177], v[102:105]
	v_mfma_f32_16x16x32_bf16 v[102:105], v[162:165], v[178:181], v[102:105]
	v_mfma_f32_16x16x32_bf16 v[106:109], v[150:153], v[174:177], v[106:109]
	v_mfma_f32_16x16x32_bf16 v[106:109], v[154:157], v[178:181], v[106:109]
	v_mfma_f32_16x16x32_bf16 v[110:113], v[142:145], v[174:177], v[110:113]
	v_mfma_f32_16x16x32_bf16 v[110:113], v[146:149], v[178:181], v[110:113]
	v_mfma_f32_16x16x32_bf16 v[114:117], v[134:137], v[174:177], v[114:117]
	v_mfma_f32_16x16x32_bf16 v[114:117], v[138:141], v[178:181], v[114:117]
	v_mfma_f32_16x16x32_bf16 v[98:101], v[134:137], v[182:185], v[98:101]
	v_mfma_f32_16x16x32_bf16 v[98:101], v[138:141], v[186:189], v[98:101]
	v_mfma_f32_16x16x32_bf16 v[94:97], v[142:145], v[182:185], v[94:97]
	v_mfma_f32_16x16x32_bf16 v[94:97], v[146:149], v[186:189], v[94:97]
	v_mfma_f32_16x16x32_bf16 v[90:93], v[150:153], v[182:185], v[90:93]
	v_mfma_f32_16x16x32_bf16 v[90:93], v[154:157], v[186:189], v[90:93]
	v_mfma_f32_16x16x32_bf16 v[86:89], v[158:161], v[182:185], v[86:89]
	v_mfma_f32_16x16x32_bf16 v[86:89], v[162:165], v[186:189], v[86:89]
	v_mfma_f32_16x16x32_bf16 v[70:73], v[158:161], v[190:193], v[70:73]
	v_mfma_f32_16x16x32_bf16 v[70:73], v[162:165], v[194:197], v[70:73]
	v_mfma_f32_16x16x32_bf16 v[74:77], v[150:153], v[190:193], v[74:77]
	v_mfma_f32_16x16x32_bf16 v[74:77], v[154:157], v[194:197], v[74:77]
	v_mfma_f32_16x16x32_bf16 v[78:81], v[142:145], v[190:193], v[78:81]
	v_mfma_f32_16x16x32_bf16 v[78:81], v[146:149], v[194:197], v[78:81]
	v_mfma_f32_16x16x32_bf16 v[82:85], v[134:137], v[190:193], v[82:85]
	v_mfma_f32_16x16x32_bf16 v[82:85], v[138:141], v[194:197], v[82:85]
	s_setprio 0
	s_barrier
	ds_read_b128 v[166:169], v233 offset:16384
	ds_read_b128 v[170:173], v233 offset:17408
	ds_read_b128 v[174:177], v233 offset:18432
	ds_read_b128 v[178:181], v233 offset:19456
	ds_read_b128 v[182:185], v233 offset:20480
	ds_read_b128 v[186:189], v233 offset:21504
	ds_read_b128 v[190:193], v233 offset:22528
	ds_read_b128 v[194:197], v233 offset:23552
	s_mov_b32 m0, s27
	s_mov_b32 s18, s14
	s_mov_b32 s19, s15
	buffer_load_dwordx4 v231, s[16:19], s51 offen lds
	s_add_i32 s53, s51, 0x18000
	s_mov_b32 m0, s30
	s_nop 0
	buffer_load_dwordx4 v231, s[16:19], s53 offen lds
	s_add_i32 s53, s51, 0x30000
	s_mov_b32 m0, s31
	s_nop 0
	buffer_load_dwordx4 v231, s[16:19], s53 offen lds
	s_add_i32 s53, s51, 0x48000
	s_mov_b32 m0, s54
	s_nop 0
	buffer_load_dwordx4 v231, s[16:19], s53 offen lds
	s_mov_b32 m0, s25
	s_add_i32 s53, s92, 0x40000
	buffer_load_dwordx4 v230, s[12:15], s92 offen lds
	s_mov_b32 m0, s55
	s_nop 0
	buffer_load_dwordx4 v230, s[12:15], s53 offen lds
	s_waitcnt vmcnt(8)
	s_waitcnt lgkmcnt(0)
	s_setprio 1
	v_mfma_f32_16x16x32_bf16 v[66:69], v[134:137], v[166:169], v[66:69]
	s_barrier
	v_mfma_f32_16x16x32_bf16 v[62:65], v[142:145], v[166:169], v[62:65]
	v_mfma_f32_16x16x32_bf16 v[50:53], v[134:137], v[174:177], v[50:53]
	v_mfma_f32_16x16x32_bf16 v[46:49], v[142:145], v[174:177], v[46:49]
	v_mfma_f32_16x16x32_bf16 v[34:37], v[134:137], v[182:185], v[34:37]
	v_mfma_f32_16x16x32_bf16 v[30:33], v[142:145], v[182:185], v[30:33]
	v_mfma_f32_16x16x32_bf16 v[18:21], v[134:137], v[190:193], v[18:21]
	v_mfma_f32_16x16x32_bf16 v[14:17], v[142:145], v[190:193], v[14:17]
	v_mfma_f32_16x16x32_bf16 v[58:61], v[150:153], v[166:169], v[58:61]
	v_mfma_f32_16x16x32_bf16 v[54:57], v[158:161], v[166:169], v[54:57]
	v_mfma_f32_16x16x32_bf16 v[42:45], v[150:153], v[174:177], v[42:45]
	v_mfma_f32_16x16x32_bf16 v[38:41], v[158:161], v[174:177], v[38:41]
	v_mfma_f32_16x16x32_bf16 v[26:29], v[150:153], v[182:185], v[26:29]
	v_mfma_f32_16x16x32_bf16 v[22:25], v[158:161], v[182:185], v[22:25]
	v_mfma_f32_16x16x32_bf16 v[10:13], v[150:153], v[190:193], v[10:13]
	v_mfma_f32_16x16x32_bf16 v[4:7], v[158:161], v[190:193], v[6:9]
	v_mfma_f32_16x16x32_bf16 v[66:69], v[138:141], v[170:173], v[66:69]
	v_mfma_f32_16x16x32_bf16 v[62:65], v[146:149], v[170:173], v[62:65]
	v_mfma_f32_16x16x32_bf16 v[50:53], v[138:141], v[178:181], v[50:53]
	v_mfma_f32_16x16x32_bf16 v[46:49], v[146:149], v[178:181], v[46:49]
	v_mfma_f32_16x16x32_bf16 v[34:37], v[138:141], v[186:189], v[34:37]
	v_mfma_f32_16x16x32_bf16 v[30:33], v[146:149], v[186:189], v[30:33]
	v_mfma_f32_16x16x32_bf16 v[18:21], v[138:141], v[194:197], v[18:21]
	v_mfma_f32_16x16x32_bf16 v[14:17], v[146:149], v[194:197], v[14:17]
	v_mfma_f32_16x16x32_bf16 v[58:61], v[154:157], v[170:173], v[58:61]
	v_mfma_f32_16x16x32_bf16 v[54:57], v[162:165], v[170:173], v[54:57]
	v_mfma_f32_16x16x32_bf16 v[42:45], v[154:157], v[178:181], v[42:45]
	v_mfma_f32_16x16x32_bf16 v[38:41], v[162:165], v[178:181], v[38:41]
	v_mfma_f32_16x16x32_bf16 v[26:29], v[154:157], v[186:189], v[26:29]
	v_mfma_f32_16x16x32_bf16 v[22:25], v[162:165], v[186:189], v[22:25]
	v_mfma_f32_16x16x32_bf16 v[10:13], v[154:157], v[194:197], v[10:13]
	v_mfma_f32_16x16x32_bf16 v[4:7], v[162:165], v[194:197], v[4:7]
	s_setprio 0
	s_barrier
	v_add_u32_e32 v2, 0x18000, v232
	ds_read_b128 v[134:137], v2
	ds_read_b128 v[138:141], v2 offset:1024
	ds_read_b128 v[142:145], v2 offset:2048
	ds_read_b128 v[146:149], v2 offset:3072
	v_add_u32_e32 v2, 0x1c000, v232
	ds_read_b128 v[150:153], v2
	ds_read_b128 v[154:157], v2 offset:1024
	ds_read_b128 v[158:161], v2 offset:2048
	ds_read_b128 v[162:165], v2 offset:3072
	s_mov_b32 m0, s56
	s_add_i32 s53, s92, 0x80000
	ds_read_b128 v[166:169], v233 offset:32768
	ds_read_b128 v[170:173], v233 offset:33792
	ds_read_b128 v[174:177], v233 offset:34816
	ds_read_b128 v[178:181], v233 offset:35840
	ds_read_b128 v[182:185], v233 offset:36864
	ds_read_b128 v[186:189], v233 offset:37888
	ds_read_b128 v[190:193], v233 offset:38912
	ds_read_b128 v[194:197], v233 offset:39936
	buffer_load_dwordx4 v230, s[12:15], s53 offen lds
	s_add_i32 s53, s92, 0xc0000
	s_mov_b32 m0, s57
	s_nop 0
	buffer_load_dwordx4 v230, s[12:15], s53 offen lds
	s_waitcnt vmcnt(8)
	s_waitcnt lgkmcnt(0)
	s_setprio 1
	v_mfma_f32_16x16x32_bf16 v[130:133], v[134:137], v[166:169], v[130:133]
	s_barrier
	v_mfma_f32_16x16x32_bf16 v[130:133], v[138:141], v[170:173], v[130:133]
	v_mfma_f32_16x16x32_bf16 v[126:129], v[142:145], v[166:169], v[126:129]
	v_mfma_f32_16x16x32_bf16 v[126:129], v[146:149], v[170:173], v[126:129]
	v_mfma_f32_16x16x32_bf16 v[122:125], v[150:153], v[166:169], v[122:125]
	v_mfma_f32_16x16x32_bf16 v[122:125], v[154:157], v[170:173], v[122:125]
	v_mfma_f32_16x16x32_bf16 v[118:121], v[158:161], v[166:169], v[118:121]
	v_mfma_f32_16x16x32_bf16 v[118:121], v[162:165], v[170:173], v[118:121]
	v_mfma_f32_16x16x32_bf16 v[102:105], v[158:161], v[174:177], v[102:105]
	v_mfma_f32_16x16x32_bf16 v[102:105], v[162:165], v[178:181], v[102:105]
	v_mfma_f32_16x16x32_bf16 v[106:109], v[150:153], v[174:177], v[106:109]
	v_mfma_f32_16x16x32_bf16 v[106:109], v[154:157], v[178:181], v[106:109]
	v_mfma_f32_16x16x32_bf16 v[110:113], v[142:145], v[174:177], v[110:113]
	v_mfma_f32_16x16x32_bf16 v[110:113], v[146:149], v[178:181], v[110:113]
	v_mfma_f32_16x16x32_bf16 v[114:117], v[134:137], v[174:177], v[114:117]
	v_mfma_f32_16x16x32_bf16 v[114:117], v[138:141], v[178:181], v[114:117]
	v_mfma_f32_16x16x32_bf16 v[98:101], v[134:137], v[182:185], v[98:101]
	v_mfma_f32_16x16x32_bf16 v[98:101], v[138:141], v[186:189], v[98:101]
	v_mfma_f32_16x16x32_bf16 v[94:97], v[142:145], v[182:185], v[94:97]
	v_mfma_f32_16x16x32_bf16 v[94:97], v[146:149], v[186:189], v[94:97]
	v_mfma_f32_16x16x32_bf16 v[90:93], v[150:153], v[182:185], v[90:93]
	v_mfma_f32_16x16x32_bf16 v[90:93], v[154:157], v[186:189], v[90:93]
	v_mfma_f32_16x16x32_bf16 v[86:89], v[158:161], v[182:185], v[86:89]
	v_mfma_f32_16x16x32_bf16 v[86:89], v[162:165], v[186:189], v[86:89]
	v_mfma_f32_16x16x32_bf16 v[70:73], v[158:161], v[190:193], v[70:73]
	v_mfma_f32_16x16x32_bf16 v[70:73], v[162:165], v[194:197], v[70:73]
	v_mfma_f32_16x16x32_bf16 v[74:77], v[150:153], v[190:193], v[74:77]
	v_mfma_f32_16x16x32_bf16 v[74:77], v[154:157], v[194:197], v[74:77]
	v_mfma_f32_16x16x32_bf16 v[78:81], v[142:145], v[190:193], v[78:81]
	v_mfma_f32_16x16x32_bf16 v[78:81], v[146:149], v[194:197], v[78:81]
	v_mfma_f32_16x16x32_bf16 v[82:85], v[134:137], v[190:193], v[82:85]
	v_mfma_f32_16x16x32_bf16 v[82:85], v[138:141], v[194:197], v[82:85]
	s_setprio 0
	s_barrier
	ds_read_b128 v[166:169], v233 offset:49152
	ds_read_b128 v[170:173], v233 offset:50176
	ds_read_b128 v[174:177], v233 offset:51200
	ds_read_b128 v[178:181], v233 offset:52224
	ds_read_b128 v[182:185], v233 offset:53248
	ds_read_b128 v[186:189], v233 offset:54272
	ds_read_b128 v[190:193], v233 offset:55296
	ds_read_b128 v[194:197], v233 offset:56320
	s_mov_b32 m0, s64
	s_nop 0
	buffer_load_dwordx4 v231, s[16:19], s52 offen lds
	s_add_i32 s52, s51, 0x18080
	s_mov_b32 m0, s65
	s_nop 0
	buffer_load_dwordx4 v231, s[16:19], s52 offen lds
	s_add_i32 s52, s51, 0x30080
	s_mov_b32 m0, s68
	s_add_i32 s51, s51, 0x48080
	buffer_load_dwordx4 v231, s[16:19], s52 offen lds
	s_mov_b32 m0, s69
	s_nop 0
	buffer_load_dwordx4 v231, s[16:19], s51 offen lds
	s_mov_b32 m0, s66
	s_add_i32 s18, s92, 0x40080
	buffer_load_dwordx4 v230, s[12:15], s50 offen lds
	s_mov_b32 m0, s67
	s_nop 0
	buffer_load_dwordx4 v230, s[12:15], s18 offen lds
	s_waitcnt vmcnt(8)
	s_waitcnt lgkmcnt(0)
	s_setprio 1
	v_mfma_f32_16x16x32_bf16 v[66:69], v[134:137], v[166:169], v[66:69]
	s_barrier
	v_mfma_f32_16x16x32_bf16 v[62:65], v[142:145], v[166:169], v[62:65]
	v_mfma_f32_16x16x32_bf16 v[50:53], v[134:137], v[174:177], v[50:53]
	v_mfma_f32_16x16x32_bf16 v[46:49], v[142:145], v[174:177], v[46:49]
	v_mfma_f32_16x16x32_bf16 v[34:37], v[134:137], v[182:185], v[34:37]
	v_mfma_f32_16x16x32_bf16 v[30:33], v[142:145], v[182:185], v[30:33]
	v_mfma_f32_16x16x32_bf16 v[18:21], v[134:137], v[190:193], v[18:21]
	v_mfma_f32_16x16x32_bf16 v[14:17], v[142:145], v[190:193], v[14:17]
	v_mfma_f32_16x16x32_bf16 v[58:61], v[150:153], v[166:169], v[58:61]
	v_mfma_f32_16x16x32_bf16 v[54:57], v[158:161], v[166:169], v[54:57]
	v_mfma_f32_16x16x32_bf16 v[42:45], v[150:153], v[174:177], v[42:45]
	v_mfma_f32_16x16x32_bf16 v[38:41], v[158:161], v[174:177], v[38:41]
	v_mfma_f32_16x16x32_bf16 v[26:29], v[150:153], v[182:185], v[26:29]
	v_mfma_f32_16x16x32_bf16 v[22:25], v[158:161], v[182:185], v[22:25]
	v_mfma_f32_16x16x32_bf16 v[8:11], v[150:153], v[190:193], v[10:13]
	v_mfma_f32_16x16x32_bf16 v[4:7], v[158:161], v[190:193], v[4:7]
	v_mfma_f32_16x16x32_bf16 v[66:69], v[138:141], v[170:173], v[66:69]
	v_mfma_f32_16x16x32_bf16 v[62:65], v[146:149], v[170:173], v[62:65]
	v_mfma_f32_16x16x32_bf16 v[50:53], v[138:141], v[178:181], v[50:53]
	v_mfma_f32_16x16x32_bf16 v[46:49], v[146:149], v[178:181], v[46:49]
	v_mfma_f32_16x16x32_bf16 v[34:37], v[138:141], v[186:189], v[34:37]
	v_mfma_f32_16x16x32_bf16 v[30:33], v[146:149], v[186:189], v[30:33]
	v_mfma_f32_16x16x32_bf16 v[18:21], v[138:141], v[194:197], v[18:21]
	v_mfma_f32_16x16x32_bf16 v[14:17], v[146:149], v[194:197], v[14:17]
	v_mfma_f32_16x16x32_bf16 v[58:61], v[154:157], v[170:173], v[58:61]
	v_mfma_f32_16x16x32_bf16 v[54:57], v[162:165], v[170:173], v[54:57]
	v_mfma_f32_16x16x32_bf16 v[42:45], v[154:157], v[178:181], v[42:45]
	v_mfma_f32_16x16x32_bf16 v[38:41], v[162:165], v[178:181], v[38:41]
	v_mfma_f32_16x16x32_bf16 v[26:29], v[154:157], v[186:189], v[26:29]
	v_mfma_f32_16x16x32_bf16 v[22:25], v[162:165], v[186:189], v[22:25]
	v_mfma_f32_16x16x32_bf16 v[10:13], v[154:157], v[194:197], v[8:11]
	v_mfma_f32_16x16x32_bf16 v[6:9], v[162:165], v[194:197], v[4:7]
	s_setprio 0
	s_barrier
	s_add_i32 s91, s91, 2
	s_addk_i32 s90, 0x100
	s_cmp_ge_i32 s91, s3
	s_cbranch_scc1 .LBB0_1193

.LBB0_1290:
	ds_read_b128 v[106:109], v224
	ds_read_b128 v[118:121], v224 offset:1024
	ds_read_b128 v[130:133], v224 offset:2048
	ds_read_b128 v[138:141], v224 offset:3072
	ds_read_b128 v[146:149], v225
	ds_read_b128 v[150:153], v225 offset:1024
	ds_read_b128 v[154:157], v225 offset:2048
	ds_read_b128 v[158:161], v225 offset:3072
	ds_read_b128 v[162:165], v226
	ds_read_b128 v[166:169], v226 offset:1024
	ds_read_b128 v[170:173], v226 offset:2048
	ds_read_b128 v[174:177], v226 offset:3072
	ds_read_b128 v[178:181], v226 offset:4096
	ds_read_b128 v[182:185], v226 offset:5120
	ds_read_b128 v[190:193], v226 offset:6144
	ds_read_b128 v[194:197], v226 offset:7168
	s_add_i32 s18, s72, 0xffe80080
	s_cmp_eq_u32 s56, s74
	s_cselect_b32 s75, s6, s18
	s_cselect_b32 s77, s7, s73
	s_or_b32 s76, s75, 0x80
	s_add_i32 s18, s72, 0xfff80000
	s_mov_b32 m0, s57
	s_nop 0
	buffer_load_dwordx4 v222, s[12:15], s18 offen lds
	s_mov_b32 m0, s60
	s_nop 0
	buffer_load_dwordx4 v222, s[12:15], s72 offen lds
	s_waitcnt vmcnt(8)
	s_waitcnt lgkmcnt(0)
	s_setprio 1
	v_mfma_f32_16x16x32_bf16 v[142:145], v[106:109], v[162:165], v[142:145]
	s_barrier
	v_mfma_f32_16x16x32_bf16 v[142:145], v[118:121], v[166:169], v[142:145]
	v_mfma_f32_16x16x32_bf16 v[134:137], v[130:133], v[162:165], v[134:137]
	v_mfma_f32_16x16x32_bf16 v[134:137], v[138:141], v[166:169], v[134:137]
	v_mfma_f32_16x16x32_bf16 v[126:129], v[146:149], v[162:165], v[126:129]
	v_mfma_f32_16x16x32_bf16 v[126:129], v[150:153], v[166:169], v[126:129]
	v_mfma_f32_16x16x32_bf16 v[122:125], v[154:157], v[162:165], v[122:125]
	v_mfma_f32_16x16x32_bf16 v[122:125], v[158:161], v[166:169], v[122:125]
	v_mfma_f32_16x16x32_bf16 v[98:101], v[154:157], v[170:173], v[98:101]
	v_mfma_f32_16x16x32_bf16 v[98:101], v[158:161], v[174:177], v[98:101]
	v_mfma_f32_16x16x32_bf16 v[102:105], v[146:149], v[170:173], v[102:105]
	v_mfma_f32_16x16x32_bf16 v[102:105], v[150:153], v[174:177], v[102:105]
	v_mfma_f32_16x16x32_bf16 v[110:113], v[130:133], v[170:173], v[110:113]
	v_mfma_f32_16x16x32_bf16 v[110:113], v[138:141], v[174:177], v[110:113]
	v_mfma_f32_16x16x32_bf16 v[114:117], v[106:109], v[170:173], v[114:117]
	v_mfma_f32_16x16x32_bf16 v[114:117], v[118:121], v[174:177], v[114:117]
	v_mfma_f32_16x16x32_bf16 v[94:97], v[106:109], v[178:181], v[94:97]
	v_mfma_f32_16x16x32_bf16 v[94:97], v[118:121], v[182:185], v[94:97]
	v_mfma_f32_16x16x32_bf16 v[90:93], v[130:133], v[178:181], v[90:93]
	v_mfma_f32_16x16x32_bf16 v[90:93], v[138:141], v[182:185], v[90:93]
	v_mfma_f32_16x16x32_bf16 v[86:89], v[146:149], v[178:181], v[86:89]
	v_mfma_f32_16x16x32_bf16 v[86:89], v[150:153], v[182:185], v[86:89]
	v_mfma_f32_16x16x32_bf16 v[82:85], v[154:157], v[178:181], v[82:85]
	v_mfma_f32_16x16x32_bf16 v[82:85], v[158:161], v[182:185], v[82:85]
	v_mfma_f32_16x16x32_bf16 v[66:69], v[154:157], v[190:193], v[66:69]
	v_mfma_f32_16x16x32_bf16 v[66:69], v[158:161], v[194:197], v[66:69]
	v_mfma_f32_16x16x32_bf16 v[70:73], v[146:149], v[190:193], v[70:73]
	v_mfma_f32_16x16x32_bf16 v[70:73], v[150:153], v[194:197], v[70:73]
	v_mfma_f32_16x16x32_bf16 v[74:77], v[130:133], v[190:193], v[74:77]
	v_mfma_f32_16x16x32_bf16 v[74:77], v[138:141], v[194:197], v[74:77]
	v_mfma_f32_16x16x32_bf16 v[78:81], v[106:109], v[190:193], v[78:81]
	v_mfma_f32_16x16x32_bf16 v[78:81], v[118:121], v[194:197], v[78:81]
	s_setprio 0
	s_barrier
	ds_read_b128 v[162:165], v226 offset:16384
	ds_read_b128 v[166:169], v226 offset:17408
	ds_read_b128 v[170:173], v226 offset:18432
	ds_read_b128 v[174:177], v226 offset:19456
	ds_read_b128 v[178:181], v226 offset:20480
	ds_read_b128 v[182:185], v226 offset:21504
	ds_read_b128 v[190:193], v226 offset:22528
	ds_read_b128 v[194:197], v226 offset:23552
	s_mov_b32 m0, s27
	s_mov_b32 s18, s14
	s_mov_b32 s19, s15
	buffer_load_dwordx4 v223, s[16:19], s77 offen lds
	s_add_i32 s78, s77, 0x80000
	s_mov_b32 m0, s30
	s_nop 0
	buffer_load_dwordx4 v223, s[16:19], s78 offen lds
	s_add_i32 s78, s77, 0x100000
	s_mov_b32 m0, s31
	s_nop 0
	buffer_load_dwordx4 v223, s[16:19], s78 offen lds
	s_add_i32 s78, s77, 0x180000
	s_mov_b32 m0, s41
	s_nop 0
	buffer_load_dwordx4 v223, s[16:19], s78 offen lds
	s_mov_b32 m0, s25
	s_add_i32 s78, s75, 0x80000
	buffer_load_dwordx4 v222, s[12:15], s75 offen lds
	s_mov_b32 m0, s42
	s_nop 0
	buffer_load_dwordx4 v222, s[12:15], s78 offen lds
	s_waitcnt vmcnt(8)
	s_waitcnt lgkmcnt(0)
	s_setprio 1
	v_mfma_f32_16x16x32_bf16 v[62:65], v[106:109], v[162:165], v[62:65]
	s_barrier
	v_mfma_f32_16x16x32_bf16 v[62:65], v[118:121], v[166:169], v[62:65]
	v_mfma_f32_16x16x32_bf16 v[58:61], v[130:133], v[162:165], v[58:61]
	v_mfma_f32_16x16x32_bf16 v[58:61], v[138:141], v[166:169], v[58:61]
	v_mfma_f32_16x16x32_bf16 v[54:57], v[146:149], v[162:165], v[54:57]
	v_mfma_f32_16x16x32_bf16 v[54:57], v[150:153], v[166:169], v[54:57]
	v_mfma_f32_16x16x32_bf16 v[50:53], v[154:157], v[162:165], v[50:53]
	v_mfma_f32_16x16x32_bf16 v[50:53], v[158:161], v[166:169], v[50:53]
	v_mfma_f32_16x16x32_bf16 v[34:37], v[154:157], v[170:173], v[34:37]
	v_mfma_f32_16x16x32_bf16 v[34:37], v[158:161], v[174:177], v[34:37]
	v_mfma_f32_16x16x32_bf16 v[38:41], v[146:149], v[170:173], v[38:41]
	v_mfma_f32_16x16x32_bf16 v[38:41], v[150:153], v[174:177], v[38:41]
	v_mfma_f32_16x16x32_bf16 v[42:45], v[130:133], v[170:173], v[42:45]
	v_mfma_f32_16x16x32_bf16 v[42:45], v[138:141], v[174:177], v[42:45]
	v_mfma_f32_16x16x32_bf16 v[46:49], v[106:109], v[170:173], v[46:49]
	v_mfma_f32_16x16x32_bf16 v[46:49], v[118:121], v[174:177], v[46:49]
	v_mfma_f32_16x16x32_bf16 v[30:33], v[106:109], v[178:181], v[30:33]
	v_mfma_f32_16x16x32_bf16 v[30:33], v[118:121], v[182:185], v[30:33]
	v_mfma_f32_16x16x32_bf16 v[26:29], v[130:133], v[178:181], v[26:29]
	v_mfma_f32_16x16x32_bf16 v[26:29], v[138:141], v[182:185], v[26:29]
	v_mfma_f32_16x16x32_bf16 v[22:25], v[146:149], v[178:181], v[22:25]
	v_mfma_f32_16x16x32_bf16 v[22:25], v[150:153], v[182:185], v[22:25]
	v_mfma_f32_16x16x32_bf16 v[18:21], v[154:157], v[178:181], v[18:21]
	v_mfma_f32_16x16x32_bf16 v[18:21], v[158:161], v[182:185], v[18:21]
	v_mfma_f32_16x16x32_bf16 v[2:5], v[154:157], v[190:193], v[2:5]
	v_mfma_f32_16x16x32_bf16 v[2:5], v[158:161], v[194:197], v[2:5]
	v_mfma_f32_16x16x32_bf16 v[6:9], v[146:149], v[190:193], v[6:9]
	v_mfma_f32_16x16x32_bf16 v[6:9], v[150:153], v[194:197], v[6:9]
	v_mfma_f32_16x16x32_bf16 v[10:13], v[130:133], v[190:193], v[10:13]
	v_mfma_f32_16x16x32_bf16 v[10:13], v[138:141], v[194:197], v[10:13]
	v_mfma_f32_16x16x32_bf16 v[14:17], v[106:109], v[190:193], v[14:17]
	v_mfma_f32_16x16x32_bf16 v[14:17], v[118:121], v[194:197], v[14:17]
	s_setprio 0
	s_barrier
	ds_read_b128 v[106:109], v227
	ds_read_b128 v[118:121], v227 offset:1024
	ds_read_b128 v[130:133], v227 offset:2048
	ds_read_b128 v[138:141], v227 offset:3072
	ds_read_b128 v[146:149], v228
	ds_read_b128 v[150:153], v228 offset:1024
	ds_read_b128 v[154:157], v228 offset:2048
	ds_read_b128 v[158:161], v228 offset:3072
	ds_read_b128 v[162:165], v226 offset:32768
	ds_read_b128 v[166:169], v226 offset:33792
	ds_read_b128 v[170:173], v226 offset:34816
	ds_read_b128 v[174:177], v226 offset:35840
	ds_read_b128 v[178:181], v226 offset:36864
	ds_read_b128 v[182:185], v226 offset:37888
	ds_read_b128 v[190:193], v226 offset:38912
	ds_read_b128 v[194:197], v226 offset:39936
	s_mov_b32 m0, s43
	s_add_i32 s78, s75, 0x100000
	buffer_load_dwordx4 v222, s[12:15], s78 offen lds
	s_add_i32 s78, s75, 0x180000
	s_mov_b32 m0, s44
	s_nop 0
	buffer_load_dwordx4 v222, s[12:15], s78 offen lds
	s_waitcnt vmcnt(8)
	s_waitcnt lgkmcnt(0)
	s_setprio 1
	v_mfma_f32_16x16x32_bf16 v[142:145], v[106:109], v[162:165], v[142:145]
	s_barrier
	v_mfma_f32_16x16x32_bf16 v[142:145], v[118:121], v[166:169], v[142:145]
	v_mfma_f32_16x16x32_bf16 v[134:137], v[130:133], v[162:165], v[134:137]
	v_mfma_f32_16x16x32_bf16 v[134:137], v[138:141], v[166:169], v[134:137]
	v_mfma_f32_16x16x32_bf16 v[126:129], v[146:149], v[162:165], v[126:129]
	v_mfma_f32_16x16x32_bf16 v[126:129], v[150:153], v[166:169], v[126:129]
	v_mfma_f32_16x16x32_bf16 v[122:125], v[154:157], v[162:165], v[122:125]
	v_mfma_f32_16x16x32_bf16 v[122:125], v[158:161], v[166:169], v[122:125]
	v_mfma_f32_16x16x32_bf16 v[98:101], v[154:157], v[170:173], v[98:101]
	v_mfma_f32_16x16x32_bf16 v[98:101], v[158:161], v[174:177], v[98:101]
	v_mfma_f32_16x16x32_bf16 v[102:105], v[146:149], v[170:173], v[102:105]
	v_mfma_f32_16x16x32_bf16 v[102:105], v[150:153], v[174:177], v[102:105]
	v_mfma_f32_16x16x32_bf16 v[110:113], v[130:133], v[170:173], v[110:113]
	v_mfma_f32_16x16x32_bf16 v[110:113], v[138:141], v[174:177], v[110:113]
	v_mfma_f32_16x16x32_bf16 v[114:117], v[106:109], v[170:173], v[114:117]
	v_mfma_f32_16x16x32_bf16 v[114:117], v[118:121], v[174:177], v[114:117]
	v_mfma_f32_16x16x32_bf16 v[94:97], v[106:109], v[178:181], v[94:97]
	v_mfma_f32_16x16x32_bf16 v[94:97], v[118:121], v[182:185], v[94:97]
	v_mfma_f32_16x16x32_bf16 v[90:93], v[130:133], v[178:181], v[90:93]
	v_mfma_f32_16x16x32_bf16 v[90:93], v[138:141], v[182:185], v[90:93]
	v_mfma_f32_16x16x32_bf16 v[86:89], v[146:149], v[178:181], v[86:89]
	v_mfma_f32_16x16x32_bf16 v[86:89], v[150:153], v[182:185], v[86:89]
	v_mfma_f32_16x16x32_bf16 v[82:85], v[154:157], v[178:181], v[82:85]
	v_mfma_f32_16x16x32_bf16 v[82:85], v[158:161], v[182:185], v[82:85]
	v_mfma_f32_16x16x32_bf16 v[66:69], v[154:157], v[190:193], v[66:69]
	v_mfma_f32_16x16x32_bf16 v[66:69], v[158:161], v[194:197], v[66:69]
	v_mfma_f32_16x16x32_bf16 v[70:73], v[146:149], v[190:193], v[70:73]
	v_mfma_f32_16x16x32_bf16 v[70:73], v[150:153], v[194:197], v[70:73]
	v_mfma_f32_16x16x32_bf16 v[74:77], v[130:133], v[190:193], v[74:77]
	v_mfma_f32_16x16x32_bf16 v[74:77], v[138:141], v[194:197], v[74:77]
	v_mfma_f32_16x16x32_bf16 v[78:81], v[106:109], v[190:193], v[78:81]
	v_mfma_f32_16x16x32_bf16 v[78:81], v[118:121], v[194:197], v[78:81]
	s_setprio 0
	s_barrier
	ds_read_b128 v[162:165], v226 offset:49152
	ds_read_b128 v[166:169], v226 offset:50176
	ds_read_b128 v[170:173], v226 offset:51200
	ds_read_b128 v[174:177], v226 offset:52224
	ds_read_b128 v[178:181], v226 offset:53248
	ds_read_b128 v[182:185], v226 offset:54272
	ds_read_b128 v[190:193], v226 offset:55296
	ds_read_b128 v[194:197], v226 offset:56320
	s_mov_b32 m0, s48
	s_or_b32 s78, s77, 0x80
	buffer_load_dwordx4 v223, s[16:19], s78 offen lds
	s_add_i32 s78, s77, 0x80080
	s_mov_b32 m0, s49
	s_add_i32 s75, s75, 0x80080
	buffer_load_dwordx4 v223, s[16:19], s78 offen lds
	s_add_i32 s78, s77, 0x100080
	s_mov_b32 m0, s52
	s_add_i32 s77, s77, 0x180080
	buffer_load_dwordx4 v223, s[16:19], s78 offen lds
	s_mov_b32 m0, s53
	s_nop 0
	buffer_load_dwordx4 v223, s[16:19], s77 offen lds
	s_mov_b32 m0, s50
	s_nop 0
	buffer_load_dwordx4 v222, s[12:15], s76 offen lds
	s_mov_b32 m0, s51
	s_nop 0
	buffer_load_dwordx4 v222, s[12:15], s75 offen lds
	s_waitcnt vmcnt(8)
	s_waitcnt lgkmcnt(0)
	s_setprio 1
	v_mfma_f32_16x16x32_bf16 v[62:65], v[106:109], v[162:165], v[62:65]
	s_barrier
	v_mfma_f32_16x16x32_bf16 v[62:65], v[118:121], v[166:169], v[62:65]
	v_mfma_f32_16x16x32_bf16 v[58:61], v[130:133], v[162:165], v[58:61]
	v_mfma_f32_16x16x32_bf16 v[58:61], v[138:141], v[166:169], v[58:61]
	v_mfma_f32_16x16x32_bf16 v[54:57], v[146:149], v[162:165], v[54:57]
	v_mfma_f32_16x16x32_bf16 v[54:57], v[150:153], v[166:169], v[54:57]
	v_mfma_f32_16x16x32_bf16 v[50:53], v[154:157], v[162:165], v[50:53]
	v_mfma_f32_16x16x32_bf16 v[50:53], v[158:161], v[166:169], v[50:53]
	v_mfma_f32_16x16x32_bf16 v[34:37], v[154:157], v[170:173], v[34:37]
	v_mfma_f32_16x16x32_bf16 v[34:37], v[158:161], v[174:177], v[34:37]
	v_mfma_f32_16x16x32_bf16 v[38:41], v[146:149], v[170:173], v[38:41]
	v_mfma_f32_16x16x32_bf16 v[38:41], v[150:153], v[174:177], v[38:41]
	v_mfma_f32_16x16x32_bf16 v[42:45], v[130:133], v[170:173], v[42:45]
	v_mfma_f32_16x16x32_bf16 v[42:45], v[138:141], v[174:177], v[42:45]
	v_mfma_f32_16x16x32_bf16 v[46:49], v[106:109], v[170:173], v[46:49]
	v_mfma_f32_16x16x32_bf16 v[46:49], v[118:121], v[174:177], v[46:49]
	v_mfma_f32_16x16x32_bf16 v[30:33], v[106:109], v[178:181], v[30:33]
	v_mfma_f32_16x16x32_bf16 v[30:33], v[118:121], v[182:185], v[30:33]
	v_mfma_f32_16x16x32_bf16 v[26:29], v[130:133], v[178:181], v[26:29]
	v_mfma_f32_16x16x32_bf16 v[26:29], v[138:141], v[182:185], v[26:29]
	v_mfma_f32_16x16x32_bf16 v[22:25], v[146:149], v[178:181], v[22:25]
	v_mfma_f32_16x16x32_bf16 v[22:25], v[150:153], v[182:185], v[22:25]
	v_mfma_f32_16x16x32_bf16 v[18:21], v[154:157], v[178:181], v[18:21]
	v_mfma_f32_16x16x32_bf16 v[18:21], v[158:161], v[182:185], v[18:21]
	v_mfma_f32_16x16x32_bf16 v[2:5], v[154:157], v[190:193], v[2:5]
	v_mfma_f32_16x16x32_bf16 v[2:5], v[158:161], v[194:197], v[2:5]
	v_mfma_f32_16x16x32_bf16 v[6:9], v[146:149], v[190:193], v[6:9]
	v_mfma_f32_16x16x32_bf16 v[6:9], v[150:153], v[194:197], v[6:9]
	v_mfma_f32_16x16x32_bf16 v[10:13], v[130:133], v[190:193], v[10:13]
	v_mfma_f32_16x16x32_bf16 v[10:13], v[138:141], v[194:197], v[10:13]
	v_mfma_f32_16x16x32_bf16 v[14:17], v[106:109], v[190:193], v[14:17]
	v_mfma_f32_16x16x32_bf16 v[14:17], v[118:121], v[194:197], v[14:17]
	s_setprio 0
	s_barrier
	s_add_i32 s74, s74, 2
	s_addk_i32 s72, 0x100
	s_addk_i32 s73, 0x100
	s_cmp_ge_i32 s74, s3
	s_cbranch_scc0 .LBB0_1290
	s_and_b64 vcc, exec, s[38:39]
	s_cbranch_vccz .LBB0_1293

.LBB0_1382:
	ds_read_b128 v[144:147], v138
	ds_read_b128 v[148:151], v138 offset:1024
	ds_read_b128 v[152:155], v138 offset:2048
	ds_read_b128 v[156:159], v138 offset:3072
	ds_read_b128 v[160:163], v139
	ds_read_b128 v[164:167], v139 offset:1024
	ds_read_b128 v[168:171], v139 offset:2048
	ds_read_b128 v[172:175], v139 offset:3072
	ds_read_b128 v[176:179], v140
	ds_read_b128 v[180:183], v140 offset:1024
	ds_read_b128 v[184:187], v140 offset:2048
	ds_read_b128 v[188:191], v140 offset:3072
	ds_read_b128 v[192:195], v140 offset:4096
	ds_read_b128 v[196:199], v140 offset:5120
	ds_read_b128 v[200:203], v140 offset:6144
	ds_read_b128 v[204:207], v140 offset:7168
	s_add_i32 s14, s74, 0xffe80080
	s_cmp_eq_u32 s61, s76
	s_cselect_b32 s77, s72, s14
	s_cselect_b32 s79, s73, s75
	s_or_b32 s78, s77, 0x80
	s_add_i32 s14, s74, 0xfff80000
	s_mov_b32 m0, s62
	s_nop 0
	buffer_load_dwordx4 v136, s[16:19], s14 offen lds
	s_mov_b32 m0, s63
	s_nop 0
	buffer_load_dwordx4 v136, s[16:19], s74 offen lds
	s_waitcnt vmcnt(8)
	s_waitcnt lgkmcnt(0)
	s_setprio 1
	v_mfma_f32_16x16x32_bf16 v[118:121], v[144:147], v[176:179], v[118:121]
	s_barrier
	v_mfma_f32_16x16x32_bf16 v[118:121], v[148:151], v[180:183], v[118:121]
	v_mfma_f32_16x16x32_bf16 v[114:117], v[152:155], v[176:179], v[114:117]
	v_mfma_f32_16x16x32_bf16 v[114:117], v[156:159], v[180:183], v[114:117]
	v_mfma_f32_16x16x32_bf16 v[126:129], v[160:163], v[176:179], v[126:129]
	v_mfma_f32_16x16x32_bf16 v[126:129], v[164:167], v[180:183], v[126:129]
	v_mfma_f32_16x16x32_bf16 v[122:125], v[168:171], v[176:179], v[122:125]
	v_mfma_f32_16x16x32_bf16 v[122:125], v[172:175], v[180:183], v[122:125]
	v_mfma_f32_16x16x32_bf16 v[98:101], v[168:171], v[184:187], v[98:101]
	v_mfma_f32_16x16x32_bf16 v[98:101], v[172:175], v[188:191], v[98:101]
	v_mfma_f32_16x16x32_bf16 v[106:109], v[160:163], v[184:187], v[106:109]
	v_mfma_f32_16x16x32_bf16 v[106:109], v[164:167], v[188:191], v[106:109]
	v_mfma_f32_16x16x32_bf16 v[102:105], v[152:155], v[184:187], v[102:105]
	v_mfma_f32_16x16x32_bf16 v[102:105], v[156:159], v[188:191], v[102:105]
	v_mfma_f32_16x16x32_bf16 v[110:113], v[144:147], v[184:187], v[110:113]
	v_mfma_f32_16x16x32_bf16 v[110:113], v[148:151], v[188:191], v[110:113]
	v_mfma_f32_16x16x32_bf16 v[94:97], v[144:147], v[192:195], v[94:97]
	v_mfma_f32_16x16x32_bf16 v[94:97], v[148:151], v[196:199], v[94:97]
	v_mfma_f32_16x16x32_bf16 v[86:89], v[152:155], v[192:195], v[86:89]
	v_mfma_f32_16x16x32_bf16 v[86:89], v[156:159], v[196:199], v[86:89]
	v_mfma_f32_16x16x32_bf16 v[90:93], v[160:163], v[192:195], v[90:93]
	v_mfma_f32_16x16x32_bf16 v[90:93], v[164:167], v[196:199], v[90:93]
	v_mfma_f32_16x16x32_bf16 v[82:85], v[168:171], v[192:195], v[82:85]
	v_mfma_f32_16x16x32_bf16 v[82:85], v[172:175], v[196:199], v[82:85]
	v_mfma_f32_16x16x32_bf16 v[70:73], v[168:171], v[200:203], v[70:73]
	v_mfma_f32_16x16x32_bf16 v[70:73], v[172:175], v[204:207], v[70:73]
	v_mfma_f32_16x16x32_bf16 v[74:77], v[160:163], v[200:203], v[74:77]
	v_mfma_f32_16x16x32_bf16 v[74:77], v[164:167], v[204:207], v[74:77]
	v_mfma_f32_16x16x32_bf16 v[66:69], v[152:155], v[200:203], v[66:69]
	v_mfma_f32_16x16x32_bf16 v[66:69], v[156:159], v[204:207], v[66:69]
	v_mfma_f32_16x16x32_bf16 v[78:81], v[144:147], v[200:203], v[78:81]
	v_mfma_f32_16x16x32_bf16 v[78:81], v[148:151], v[204:207], v[78:81]
	s_setprio 0
	s_barrier
	ds_read_b128 v[176:179], v140 offset:16384
	ds_read_b128 v[180:183], v140 offset:17408
	ds_read_b128 v[184:187], v140 offset:18432
	ds_read_b128 v[188:191], v140 offset:19456
	ds_read_b128 v[192:195], v140 offset:20480
	ds_read_b128 v[196:199], v140 offset:21504
	ds_read_b128 v[200:203], v140 offset:22528
	ds_read_b128 v[204:207], v140 offset:23552
	s_mov_b32 m0, s45
	s_mov_b32 s14, s18
	s_mov_b32 s15, s19
	buffer_load_dwordx4 v137, s[12:15], s79 offen lds
	s_add_i32 s80, s79, 0x80000
	s_mov_b32 m0, s46
	s_nop 0
	buffer_load_dwordx4 v137, s[12:15], s80 offen lds
	s_add_i32 s80, s79, 0x100000
	s_mov_b32 m0, s47
	s_nop 0
	buffer_load_dwordx4 v137, s[12:15], s80 offen lds
	s_add_i32 s80, s79, 0x180000
	s_mov_b32 m0, s48
	s_nop 0
	buffer_load_dwordx4 v137, s[12:15], s80 offen lds
	s_mov_b32 m0, s44
	s_add_i32 s80, s77, 0x80000
	buffer_load_dwordx4 v136, s[16:19], s77 offen lds
	s_mov_b32 m0, s49
	s_nop 0
	buffer_load_dwordx4 v136, s[16:19], s80 offen lds
	s_waitcnt vmcnt(8)
	s_waitcnt lgkmcnt(0)
	s_setprio 1
	v_mfma_f32_16x16x32_bf16 v[62:65], v[144:147], v[176:179], v[62:65]
	s_barrier
	v_mfma_f32_16x16x32_bf16 v[62:65], v[148:151], v[180:183], v[62:65]
	v_mfma_f32_16x16x32_bf16 v[54:57], v[152:155], v[176:179], v[54:57]
	v_mfma_f32_16x16x32_bf16 v[54:57], v[156:159], v[180:183], v[54:57]
	v_mfma_f32_16x16x32_bf16 v[58:61], v[160:163], v[176:179], v[58:61]
	v_mfma_f32_16x16x32_bf16 v[58:61], v[164:167], v[180:183], v[58:61]
	v_mfma_f32_16x16x32_bf16 v[50:53], v[168:171], v[176:179], v[50:53]
	v_mfma_f32_16x16x32_bf16 v[50:53], v[172:175], v[180:183], v[50:53]
	v_mfma_f32_16x16x32_bf16 v[34:37], v[168:171], v[184:187], v[34:37]
	v_mfma_f32_16x16x32_bf16 v[34:37], v[172:175], v[188:191], v[34:37]
	v_mfma_f32_16x16x32_bf16 v[42:45], v[160:163], v[184:187], v[42:45]
	v_mfma_f32_16x16x32_bf16 v[42:45], v[164:167], v[188:191], v[42:45]
	v_mfma_f32_16x16x32_bf16 v[38:41], v[152:155], v[184:187], v[38:41]
	v_mfma_f32_16x16x32_bf16 v[38:41], v[156:159], v[188:191], v[38:41]
	v_mfma_f32_16x16x32_bf16 v[46:49], v[144:147], v[184:187], v[46:49]
	v_mfma_f32_16x16x32_bf16 v[46:49], v[148:151], v[188:191], v[46:49]
	v_mfma_f32_16x16x32_bf16 v[30:33], v[144:147], v[192:195], v[30:33]
	v_mfma_f32_16x16x32_bf16 v[30:33], v[148:151], v[196:199], v[30:33]
	v_mfma_f32_16x16x32_bf16 v[22:25], v[152:155], v[192:195], v[22:25]
	v_mfma_f32_16x16x32_bf16 v[22:25], v[156:159], v[196:199], v[22:25]
	v_mfma_f32_16x16x32_bf16 v[26:29], v[160:163], v[192:195], v[26:29]
	v_mfma_f32_16x16x32_bf16 v[26:29], v[164:167], v[196:199], v[26:29]
	v_mfma_f32_16x16x32_bf16 v[18:21], v[168:171], v[192:195], v[18:21]
	v_mfma_f32_16x16x32_bf16 v[18:21], v[172:175], v[196:199], v[18:21]
	v_mfma_f32_16x16x32_bf16 v[2:5], v[168:171], v[200:203], v[2:5]
	v_mfma_f32_16x16x32_bf16 v[2:5], v[172:175], v[204:207], v[2:5]
	v_mfma_f32_16x16x32_bf16 v[10:13], v[160:163], v[200:203], v[10:13]
	v_mfma_f32_16x16x32_bf16 v[10:13], v[164:167], v[204:207], v[10:13]
	v_mfma_f32_16x16x32_bf16 v[6:9], v[152:155], v[200:203], v[6:9]
	v_mfma_f32_16x16x32_bf16 v[6:9], v[156:159], v[204:207], v[6:9]
	v_mfma_f32_16x16x32_bf16 v[14:17], v[144:147], v[200:203], v[14:17]
	v_mfma_f32_16x16x32_bf16 v[14:17], v[148:151], v[204:207], v[14:17]
	s_setprio 0
	s_barrier
	ds_read_b128 v[144:147], v141
	ds_read_b128 v[148:151], v141 offset:1024
	ds_read_b128 v[152:155], v141 offset:2048
	ds_read_b128 v[156:159], v141 offset:3072
	ds_read_b128 v[160:163], v142
	ds_read_b128 v[164:167], v142 offset:1024
	ds_read_b128 v[168:171], v142 offset:2048
	ds_read_b128 v[172:175], v142 offset:3072
	ds_read_b128 v[176:179], v140 offset:32768
	ds_read_b128 v[180:183], v140 offset:33792
	ds_read_b128 v[184:187], v140 offset:34816
	ds_read_b128 v[188:191], v140 offset:35840
	ds_read_b128 v[192:195], v140 offset:36864
	ds_read_b128 v[196:199], v140 offset:37888
	ds_read_b128 v[200:203], v140 offset:38912
	ds_read_b128 v[204:207], v140 offset:39936
	s_mov_b32 m0, s50
	s_add_i32 s80, s77, 0x100000
	buffer_load_dwordx4 v136, s[16:19], s80 offen lds
	s_add_i32 s80, s77, 0x180000
	s_mov_b32 m0, s51
	s_nop 0
	buffer_load_dwordx4 v136, s[16:19], s80 offen lds
	s_waitcnt vmcnt(8)
	s_waitcnt lgkmcnt(0)
	s_setprio 1
	v_mfma_f32_16x16x32_bf16 v[118:121], v[144:147], v[176:179], v[118:121]
	s_barrier
	v_mfma_f32_16x16x32_bf16 v[118:121], v[148:151], v[180:183], v[118:121]
	v_mfma_f32_16x16x32_bf16 v[114:117], v[152:155], v[176:179], v[114:117]
	v_mfma_f32_16x16x32_bf16 v[114:117], v[156:159], v[180:183], v[114:117]
	v_mfma_f32_16x16x32_bf16 v[126:129], v[160:163], v[176:179], v[126:129]
	v_mfma_f32_16x16x32_bf16 v[126:129], v[164:167], v[180:183], v[126:129]
	v_mfma_f32_16x16x32_bf16 v[122:125], v[168:171], v[176:179], v[122:125]
	v_mfma_f32_16x16x32_bf16 v[122:125], v[172:175], v[180:183], v[122:125]
	v_mfma_f32_16x16x32_bf16 v[98:101], v[168:171], v[184:187], v[98:101]
	v_mfma_f32_16x16x32_bf16 v[98:101], v[172:175], v[188:191], v[98:101]
	v_mfma_f32_16x16x32_bf16 v[106:109], v[160:163], v[184:187], v[106:109]
	v_mfma_f32_16x16x32_bf16 v[106:109], v[164:167], v[188:191], v[106:109]
	v_mfma_f32_16x16x32_bf16 v[102:105], v[152:155], v[184:187], v[102:105]
	v_mfma_f32_16x16x32_bf16 v[102:105], v[156:159], v[188:191], v[102:105]
	v_mfma_f32_16x16x32_bf16 v[110:113], v[144:147], v[184:187], v[110:113]
	v_mfma_f32_16x16x32_bf16 v[110:113], v[148:151], v[188:191], v[110:113]
	v_mfma_f32_16x16x32_bf16 v[94:97], v[144:147], v[192:195], v[94:97]
	v_mfma_f32_16x16x32_bf16 v[94:97], v[148:151], v[196:199], v[94:97]
	v_mfma_f32_16x16x32_bf16 v[86:89], v[152:155], v[192:195], v[86:89]
	v_mfma_f32_16x16x32_bf16 v[86:89], v[156:159], v[196:199], v[86:89]
	v_mfma_f32_16x16x32_bf16 v[90:93], v[160:163], v[192:195], v[90:93]
	v_mfma_f32_16x16x32_bf16 v[90:93], v[164:167], v[196:199], v[90:93]
	v_mfma_f32_16x16x32_bf16 v[82:85], v[168:171], v[192:195], v[82:85]
	v_mfma_f32_16x16x32_bf16 v[82:85], v[172:175], v[196:199], v[82:85]
	v_mfma_f32_16x16x32_bf16 v[70:73], v[168:171], v[200:203], v[70:73]
	v_mfma_f32_16x16x32_bf16 v[70:73], v[172:175], v[204:207], v[70:73]
	v_mfma_f32_16x16x32_bf16 v[74:77], v[160:163], v[200:203], v[74:77]
	v_mfma_f32_16x16x32_bf16 v[74:77], v[164:167], v[204:207], v[74:77]
	v_mfma_f32_16x16x32_bf16 v[66:69], v[152:155], v[200:203], v[66:69]
	v_mfma_f32_16x16x32_bf16 v[66:69], v[156:159], v[204:207], v[66:69]
	v_mfma_f32_16x16x32_bf16 v[78:81], v[144:147], v[200:203], v[78:81]
	v_mfma_f32_16x16x32_bf16 v[78:81], v[148:151], v[204:207], v[78:81]
	s_setprio 0
	s_barrier
	ds_read_b128 v[176:179], v140 offset:49152
	ds_read_b128 v[180:183], v140 offset:50176
	ds_read_b128 v[184:187], v140 offset:51200
	ds_read_b128 v[188:191], v140 offset:52224
	ds_read_b128 v[192:195], v140 offset:53248
	ds_read_b128 v[196:199], v140 offset:54272
	ds_read_b128 v[200:203], v140 offset:55296
	ds_read_b128 v[204:207], v140 offset:56320
	s_mov_b32 m0, s53
	s_or_b32 s80, s79, 0x80
	buffer_load_dwordx4 v137, s[12:15], s80 offen lds
	s_add_i32 s80, s79, 0x80080
	s_mov_b32 m0, s54
	s_add_i32 s77, s77, 0x80080
	buffer_load_dwordx4 v137, s[12:15], s80 offen lds
	s_add_i32 s80, s79, 0x100080
	s_mov_b32 m0, s57
	s_add_i32 s79, s79, 0x180080
	buffer_load_dwordx4 v137, s[12:15], s80 offen lds
	s_mov_b32 m0, s58
	s_nop 0
	buffer_load_dwordx4 v137, s[12:15], s79 offen lds
	s_mov_b32 m0, s55
	s_nop 0
	buffer_load_dwordx4 v136, s[16:19], s78 offen lds
	s_mov_b32 m0, s56
	s_nop 0
	buffer_load_dwordx4 v136, s[16:19], s77 offen lds
	s_waitcnt vmcnt(8)
	s_waitcnt lgkmcnt(0)
	s_setprio 1
	v_mfma_f32_16x16x32_bf16 v[62:65], v[144:147], v[176:179], v[62:65]
	s_barrier
	v_mfma_f32_16x16x32_bf16 v[62:65], v[148:151], v[180:183], v[62:65]
	v_mfma_f32_16x16x32_bf16 v[54:57], v[152:155], v[176:179], v[54:57]
	v_mfma_f32_16x16x32_bf16 v[54:57], v[156:159], v[180:183], v[54:57]
	v_mfma_f32_16x16x32_bf16 v[58:61], v[160:163], v[176:179], v[58:61]
	v_mfma_f32_16x16x32_bf16 v[58:61], v[164:167], v[180:183], v[58:61]
	v_mfma_f32_16x16x32_bf16 v[50:53], v[168:171], v[176:179], v[50:53]
	v_mfma_f32_16x16x32_bf16 v[50:53], v[172:175], v[180:183], v[50:53]
	v_mfma_f32_16x16x32_bf16 v[34:37], v[168:171], v[184:187], v[34:37]
	v_mfma_f32_16x16x32_bf16 v[34:37], v[172:175], v[188:191], v[34:37]
	v_mfma_f32_16x16x32_bf16 v[42:45], v[160:163], v[184:187], v[42:45]
	v_mfma_f32_16x16x32_bf16 v[42:45], v[164:167], v[188:191], v[42:45]
	v_mfma_f32_16x16x32_bf16 v[38:41], v[152:155], v[184:187], v[38:41]
	v_mfma_f32_16x16x32_bf16 v[38:41], v[156:159], v[188:191], v[38:41]
	v_mfma_f32_16x16x32_bf16 v[46:49], v[144:147], v[184:187], v[46:49]
	v_mfma_f32_16x16x32_bf16 v[46:49], v[148:151], v[188:191], v[46:49]
	v_mfma_f32_16x16x32_bf16 v[30:33], v[144:147], v[192:195], v[30:33]
	v_mfma_f32_16x16x32_bf16 v[30:33], v[148:151], v[196:199], v[30:33]
	v_mfma_f32_16x16x32_bf16 v[22:25], v[152:155], v[192:195], v[22:25]
	v_mfma_f32_16x16x32_bf16 v[22:25], v[156:159], v[196:199], v[22:25]
	v_mfma_f32_16x16x32_bf16 v[26:29], v[160:163], v[192:195], v[26:29]
	v_mfma_f32_16x16x32_bf16 v[26:29], v[164:167], v[196:199], v[26:29]
	v_mfma_f32_16x16x32_bf16 v[18:21], v[168:171], v[192:195], v[18:21]
	v_mfma_f32_16x16x32_bf16 v[18:21], v[172:175], v[196:199], v[18:21]
	v_mfma_f32_16x16x32_bf16 v[2:5], v[168:171], v[200:203], v[2:5]
	v_mfma_f32_16x16x32_bf16 v[2:5], v[172:175], v[204:207], v[2:5]
	v_mfma_f32_16x16x32_bf16 v[10:13], v[160:163], v[200:203], v[10:13]
	v_mfma_f32_16x16x32_bf16 v[10:13], v[164:167], v[204:207], v[10:13]
	v_mfma_f32_16x16x32_bf16 v[6:9], v[152:155], v[200:203], v[6:9]
	v_mfma_f32_16x16x32_bf16 v[6:9], v[156:159], v[204:207], v[6:9]
	v_mfma_f32_16x16x32_bf16 v[14:17], v[144:147], v[200:203], v[14:17]
	v_mfma_f32_16x16x32_bf16 v[14:17], v[148:151], v[204:207], v[14:17]
	s_setprio 0
	s_barrier
	s_add_i32 s76, s76, 2
	s_addk_i32 s74, 0x100
	s_addk_i32 s75, 0x100
	s_cmp_ge_i32 s76, s27
	s_cbranch_scc0 .LBB0_1382
	s_and_b64 vcc, exec, s[42:43]
	s_cbranch_vccz .LBB0_1385

.LBB0_1402:
	ds_read_b128 v[146:149], v138
	ds_read_b128 v[150:153], v138 offset:1024
	ds_read_b128 v[154:157], v138 offset:2048
	ds_read_b128 v[158:161], v138 offset:3072
	ds_read_b128 v[162:165], v139
	ds_read_b128 v[166:169], v139 offset:1024
	ds_read_b128 v[170:173], v139 offset:2048
	ds_read_b128 v[174:177], v139 offset:3072
	ds_read_b128 v[178:181], v140
	ds_read_b128 v[182:185], v140 offset:1024
	ds_read_b128 v[186:189], v140 offset:2048
	ds_read_b128 v[190:193], v140 offset:3072
	ds_read_b128 v[194:197], v140 offset:4096
	ds_read_b128 v[198:201], v140 offset:5120
	ds_read_b128 v[202:205], v140 offset:6144
	ds_read_b128 v[206:209], v140 offset:7168
	s_add_i32 s22, s75, 0xffe80080
	s_cmp_eq_u32 s62, s77
	s_cselect_b32 s78, s73, s22
	s_cselect_b32 s80, s74, s76
	s_or_b32 s79, s78, 0x80
	s_add_i32 s22, s75, 0xfff80000
	s_mov_b32 m0, s63
	s_nop 0
	buffer_load_dwordx4 v136, s[16:19], s22 offen lds
	s_mov_b32 m0, s64
	s_nop 0
	buffer_load_dwordx4 v136, s[16:19], s75 offen lds
	s_waitcnt vmcnt(8)
	s_waitcnt lgkmcnt(0)
	s_setprio 1
	v_mfma_f32_16x16x32_bf16 v[118:121], v[146:149], v[178:181], v[118:121]
	s_barrier
	v_mfma_f32_16x16x32_bf16 v[118:121], v[150:153], v[182:185], v[118:121]
	v_mfma_f32_16x16x32_bf16 v[114:117], v[154:157], v[178:181], v[114:117]
	v_mfma_f32_16x16x32_bf16 v[114:117], v[158:161], v[182:185], v[114:117]
	v_mfma_f32_16x16x32_bf16 v[126:129], v[162:165], v[178:181], v[126:129]
	v_mfma_f32_16x16x32_bf16 v[126:129], v[166:169], v[182:185], v[126:129]
	v_mfma_f32_16x16x32_bf16 v[122:125], v[170:173], v[178:181], v[122:125]
	v_mfma_f32_16x16x32_bf16 v[122:125], v[174:177], v[182:185], v[122:125]
	v_mfma_f32_16x16x32_bf16 v[98:101], v[170:173], v[186:189], v[98:101]
	v_mfma_f32_16x16x32_bf16 v[98:101], v[174:177], v[190:193], v[98:101]
	v_mfma_f32_16x16x32_bf16 v[106:109], v[162:165], v[186:189], v[106:109]
	v_mfma_f32_16x16x32_bf16 v[106:109], v[166:169], v[190:193], v[106:109]
	v_mfma_f32_16x16x32_bf16 v[102:105], v[154:157], v[186:189], v[102:105]
	v_mfma_f32_16x16x32_bf16 v[102:105], v[158:161], v[190:193], v[102:105]
	v_mfma_f32_16x16x32_bf16 v[110:113], v[146:149], v[186:189], v[110:113]
	v_mfma_f32_16x16x32_bf16 v[110:113], v[150:153], v[190:193], v[110:113]
	v_mfma_f32_16x16x32_bf16 v[94:97], v[146:149], v[194:197], v[94:97]
	v_mfma_f32_16x16x32_bf16 v[94:97], v[150:153], v[198:201], v[94:97]
	v_mfma_f32_16x16x32_bf16 v[86:89], v[154:157], v[194:197], v[86:89]
	v_mfma_f32_16x16x32_bf16 v[86:89], v[158:161], v[198:201], v[86:89]
	v_mfma_f32_16x16x32_bf16 v[90:93], v[162:165], v[194:197], v[90:93]
	v_mfma_f32_16x16x32_bf16 v[90:93], v[166:169], v[198:201], v[90:93]
	v_mfma_f32_16x16x32_bf16 v[82:85], v[170:173], v[194:197], v[82:85]
	v_mfma_f32_16x16x32_bf16 v[82:85], v[174:177], v[198:201], v[82:85]
	v_mfma_f32_16x16x32_bf16 v[70:73], v[170:173], v[202:205], v[70:73]
	v_mfma_f32_16x16x32_bf16 v[70:73], v[174:177], v[206:209], v[70:73]
	v_mfma_f32_16x16x32_bf16 v[74:77], v[162:165], v[202:205], v[74:77]
	v_mfma_f32_16x16x32_bf16 v[74:77], v[166:169], v[206:209], v[74:77]
	v_mfma_f32_16x16x32_bf16 v[66:69], v[154:157], v[202:205], v[66:69]
	v_mfma_f32_16x16x32_bf16 v[66:69], v[158:161], v[206:209], v[66:69]
	v_mfma_f32_16x16x32_bf16 v[78:81], v[146:149], v[202:205], v[78:81]
	v_mfma_f32_16x16x32_bf16 v[78:81], v[150:153], v[206:209], v[78:81]
	s_setprio 0
	s_barrier
	ds_read_b128 v[178:181], v140 offset:16384
	ds_read_b128 v[182:185], v140 offset:17408
	ds_read_b128 v[186:189], v140 offset:18432
	ds_read_b128 v[190:193], v140 offset:19456
	ds_read_b128 v[194:197], v140 offset:20480
	ds_read_b128 v[198:201], v140 offset:21504
	ds_read_b128 v[202:205], v140 offset:22528
	ds_read_b128 v[206:209], v140 offset:23552
	s_mov_b32 m0, s31
	s_mov_b32 s22, s18
	s_mov_b32 s23, s19
	buffer_load_dwordx4 v137, s[20:23], s80 offen lds
	s_add_i32 s81, s80, 0x80000
	s_mov_b32 m0, s48
	s_nop 0
	buffer_load_dwordx4 v137, s[20:23], s81 offen lds
	s_add_i32 s81, s80, 0x100000
	s_mov_b32 m0, s49
	s_nop 0
	buffer_load_dwordx4 v137, s[20:23], s81 offen lds
	s_add_i32 s81, s80, 0x180000
	s_mov_b32 m0, s50
	s_nop 0
	buffer_load_dwordx4 v137, s[20:23], s81 offen lds
	s_mov_b32 m0, s30
	s_add_i32 s81, s78, 0x80000
	buffer_load_dwordx4 v136, s[16:19], s78 offen lds
	s_mov_b32 m0, s51
	s_nop 0
	buffer_load_dwordx4 v136, s[16:19], s81 offen lds
	s_waitcnt vmcnt(8)
	s_waitcnt lgkmcnt(0)
	s_setprio 1
	v_mfma_f32_16x16x32_bf16 v[62:65], v[146:149], v[178:181], v[62:65]
	s_barrier
	v_mfma_f32_16x16x32_bf16 v[62:65], v[150:153], v[182:185], v[62:65]
	v_mfma_f32_16x16x32_bf16 v[54:57], v[154:157], v[178:181], v[54:57]
	v_mfma_f32_16x16x32_bf16 v[54:57], v[158:161], v[182:185], v[54:57]
	v_mfma_f32_16x16x32_bf16 v[58:61], v[162:165], v[178:181], v[58:61]
	v_mfma_f32_16x16x32_bf16 v[58:61], v[166:169], v[182:185], v[58:61]
	v_mfma_f32_16x16x32_bf16 v[50:53], v[170:173], v[178:181], v[50:53]
	v_mfma_f32_16x16x32_bf16 v[50:53], v[174:177], v[182:185], v[50:53]
	v_mfma_f32_16x16x32_bf16 v[34:37], v[170:173], v[186:189], v[34:37]
	v_mfma_f32_16x16x32_bf16 v[34:37], v[174:177], v[190:193], v[34:37]
	v_mfma_f32_16x16x32_bf16 v[42:45], v[162:165], v[186:189], v[42:45]
	v_mfma_f32_16x16x32_bf16 v[42:45], v[166:169], v[190:193], v[42:45]
	v_mfma_f32_16x16x32_bf16 v[38:41], v[154:157], v[186:189], v[38:41]
	v_mfma_f32_16x16x32_bf16 v[38:41], v[158:161], v[190:193], v[38:41]
	v_mfma_f32_16x16x32_bf16 v[46:49], v[146:149], v[186:189], v[46:49]
	v_mfma_f32_16x16x32_bf16 v[46:49], v[150:153], v[190:193], v[46:49]
	v_mfma_f32_16x16x32_bf16 v[30:33], v[146:149], v[194:197], v[30:33]
	v_mfma_f32_16x16x32_bf16 v[30:33], v[150:153], v[198:201], v[30:33]
	v_mfma_f32_16x16x32_bf16 v[22:25], v[154:157], v[194:197], v[22:25]
	v_mfma_f32_16x16x32_bf16 v[22:25], v[158:161], v[198:201], v[22:25]
	v_mfma_f32_16x16x32_bf16 v[26:29], v[162:165], v[194:197], v[26:29]
	v_mfma_f32_16x16x32_bf16 v[26:29], v[166:169], v[198:201], v[26:29]
	v_mfma_f32_16x16x32_bf16 v[18:21], v[170:173], v[194:197], v[18:21]
	v_mfma_f32_16x16x32_bf16 v[18:21], v[174:177], v[198:201], v[18:21]
	v_mfma_f32_16x16x32_bf16 v[2:5], v[170:173], v[202:205], v[2:5]
	v_mfma_f32_16x16x32_bf16 v[2:5], v[174:177], v[206:209], v[2:5]
	v_mfma_f32_16x16x32_bf16 v[10:13], v[162:165], v[202:205], v[10:13]
	v_mfma_f32_16x16x32_bf16 v[10:13], v[166:169], v[206:209], v[10:13]
	v_mfma_f32_16x16x32_bf16 v[6:9], v[154:157], v[202:205], v[6:9]
	v_mfma_f32_16x16x32_bf16 v[6:9], v[158:161], v[206:209], v[6:9]
	v_mfma_f32_16x16x32_bf16 v[14:17], v[146:149], v[202:205], v[14:17]
	v_mfma_f32_16x16x32_bf16 v[14:17], v[150:153], v[206:209], v[14:17]
	s_setprio 0
	s_barrier
	ds_read_b128 v[146:149], v141
	ds_read_b128 v[150:153], v141 offset:1024
	ds_read_b128 v[154:157], v141 offset:2048
	ds_read_b128 v[158:161], v141 offset:3072
	ds_read_b128 v[162:165], v142
	ds_read_b128 v[166:169], v142 offset:1024
	ds_read_b128 v[170:173], v142 offset:2048
	ds_read_b128 v[174:177], v142 offset:3072
	ds_read_b128 v[178:181], v140 offset:32768
	ds_read_b128 v[182:185], v140 offset:33792
	ds_read_b128 v[186:189], v140 offset:34816
	ds_read_b128 v[190:193], v140 offset:35840
	ds_read_b128 v[194:197], v140 offset:36864
	ds_read_b128 v[198:201], v140 offset:37888
	ds_read_b128 v[202:205], v140 offset:38912
	ds_read_b128 v[206:209], v140 offset:39936
	s_mov_b32 m0, s52
	s_add_i32 s81, s78, 0x100000
	buffer_load_dwordx4 v136, s[16:19], s81 offen lds
	s_add_i32 s81, s78, 0x180000
	s_mov_b32 m0, s53
	s_nop 0
	buffer_load_dwordx4 v136, s[16:19], s81 offen lds
	s_waitcnt vmcnt(8)
	s_waitcnt lgkmcnt(0)
	s_setprio 1
	v_mfma_f32_16x16x32_bf16 v[118:121], v[146:149], v[178:181], v[118:121]
	s_barrier
	v_mfma_f32_16x16x32_bf16 v[118:121], v[150:153], v[182:185], v[118:121]
	v_mfma_f32_16x16x32_bf16 v[114:117], v[154:157], v[178:181], v[114:117]
	v_mfma_f32_16x16x32_bf16 v[114:117], v[158:161], v[182:185], v[114:117]
	v_mfma_f32_16x16x32_bf16 v[126:129], v[162:165], v[178:181], v[126:129]
	v_mfma_f32_16x16x32_bf16 v[126:129], v[166:169], v[182:185], v[126:129]
	v_mfma_f32_16x16x32_bf16 v[122:125], v[170:173], v[178:181], v[122:125]
	v_mfma_f32_16x16x32_bf16 v[122:125], v[174:177], v[182:185], v[122:125]
	v_mfma_f32_16x16x32_bf16 v[98:101], v[170:173], v[186:189], v[98:101]
	v_mfma_f32_16x16x32_bf16 v[98:101], v[174:177], v[190:193], v[98:101]
	v_mfma_f32_16x16x32_bf16 v[106:109], v[162:165], v[186:189], v[106:109]
	v_mfma_f32_16x16x32_bf16 v[106:109], v[166:169], v[190:193], v[106:109]
	v_mfma_f32_16x16x32_bf16 v[102:105], v[154:157], v[186:189], v[102:105]
	v_mfma_f32_16x16x32_bf16 v[102:105], v[158:161], v[190:193], v[102:105]
	v_mfma_f32_16x16x32_bf16 v[110:113], v[146:149], v[186:189], v[110:113]
	v_mfma_f32_16x16x32_bf16 v[110:113], v[150:153], v[190:193], v[110:113]
	v_mfma_f32_16x16x32_bf16 v[94:97], v[146:149], v[194:197], v[94:97]
	v_mfma_f32_16x16x32_bf16 v[94:97], v[150:153], v[198:201], v[94:97]
	v_mfma_f32_16x16x32_bf16 v[86:89], v[154:157], v[194:197], v[86:89]
	v_mfma_f32_16x16x32_bf16 v[86:89], v[158:161], v[198:201], v[86:89]
	v_mfma_f32_16x16x32_bf16 v[90:93], v[162:165], v[194:197], v[90:93]
	v_mfma_f32_16x16x32_bf16 v[90:93], v[166:169], v[198:201], v[90:93]
	v_mfma_f32_16x16x32_bf16 v[82:85], v[170:173], v[194:197], v[82:85]
	v_mfma_f32_16x16x32_bf16 v[82:85], v[174:177], v[198:201], v[82:85]
	v_mfma_f32_16x16x32_bf16 v[70:73], v[170:173], v[202:205], v[70:73]
	v_mfma_f32_16x16x32_bf16 v[70:73], v[174:177], v[206:209], v[70:73]
	v_mfma_f32_16x16x32_bf16 v[74:77], v[162:165], v[202:205], v[74:77]
	v_mfma_f32_16x16x32_bf16 v[74:77], v[166:169], v[206:209], v[74:77]
	v_mfma_f32_16x16x32_bf16 v[66:69], v[154:157], v[202:205], v[66:69]
	v_mfma_f32_16x16x32_bf16 v[66:69], v[158:161], v[206:209], v[66:69]
	v_mfma_f32_16x16x32_bf16 v[78:81], v[146:149], v[202:205], v[78:81]
	v_mfma_f32_16x16x32_bf16 v[78:81], v[150:153], v[206:209], v[78:81]
	s_setprio 0
	s_barrier
	ds_read_b128 v[178:181], v140 offset:49152
	ds_read_b128 v[182:185], v140 offset:50176
	ds_read_b128 v[186:189], v140 offset:51200
	ds_read_b128 v[190:193], v140 offset:52224
	ds_read_b128 v[194:197], v140 offset:53248
	ds_read_b128 v[198:201], v140 offset:54272
	ds_read_b128 v[202:205], v140 offset:55296
	ds_read_b128 v[206:209], v140 offset:56320
	s_mov_b32 m0, s54
	s_or_b32 s81, s80, 0x80
	buffer_load_dwordx4 v137, s[20:23], s81 offen lds
	s_add_i32 s81, s80, 0x80080
	s_mov_b32 m0, s55
	s_add_i32 s78, s78, 0x80080
	buffer_load_dwordx4 v137, s[20:23], s81 offen lds
	s_add_i32 s81, s80, 0x100080
	s_mov_b32 m0, s58
	s_add_i32 s80, s80, 0x180080
	buffer_load_dwordx4 v137, s[20:23], s81 offen lds
	s_mov_b32 m0, s59
	s_nop 0
	buffer_load_dwordx4 v137, s[20:23], s80 offen lds
	s_mov_b32 m0, s56
	s_nop 0
	buffer_load_dwordx4 v136, s[16:19], s79 offen lds
	s_mov_b32 m0, s57
	s_nop 0
	buffer_load_dwordx4 v136, s[16:19], s78 offen lds
	s_waitcnt vmcnt(8)
	s_waitcnt lgkmcnt(0)
	s_setprio 1
	v_mfma_f32_16x16x32_bf16 v[62:65], v[146:149], v[178:181], v[62:65]
	s_barrier
	v_mfma_f32_16x16x32_bf16 v[62:65], v[150:153], v[182:185], v[62:65]
	v_mfma_f32_16x16x32_bf16 v[54:57], v[154:157], v[178:181], v[54:57]
	v_mfma_f32_16x16x32_bf16 v[54:57], v[158:161], v[182:185], v[54:57]
	v_mfma_f32_16x16x32_bf16 v[58:61], v[162:165], v[178:181], v[58:61]
	v_mfma_f32_16x16x32_bf16 v[58:61], v[166:169], v[182:185], v[58:61]
	v_mfma_f32_16x16x32_bf16 v[50:53], v[170:173], v[178:181], v[50:53]
	v_mfma_f32_16x16x32_bf16 v[50:53], v[174:177], v[182:185], v[50:53]
	v_mfma_f32_16x16x32_bf16 v[34:37], v[170:173], v[186:189], v[34:37]
	v_mfma_f32_16x16x32_bf16 v[34:37], v[174:177], v[190:193], v[34:37]
	v_mfma_f32_16x16x32_bf16 v[42:45], v[162:165], v[186:189], v[42:45]
	v_mfma_f32_16x16x32_bf16 v[42:45], v[166:169], v[190:193], v[42:45]
	v_mfma_f32_16x16x32_bf16 v[38:41], v[154:157], v[186:189], v[38:41]
	v_mfma_f32_16x16x32_bf16 v[38:41], v[158:161], v[190:193], v[38:41]
	v_mfma_f32_16x16x32_bf16 v[46:49], v[146:149], v[186:189], v[46:49]
	v_mfma_f32_16x16x32_bf16 v[46:49], v[150:153], v[190:193], v[46:49]
	v_mfma_f32_16x16x32_bf16 v[30:33], v[146:149], v[194:197], v[30:33]
	v_mfma_f32_16x16x32_bf16 v[30:33], v[150:153], v[198:201], v[30:33]
	v_mfma_f32_16x16x32_bf16 v[22:25], v[154:157], v[194:197], v[22:25]
	v_mfma_f32_16x16x32_bf16 v[22:25], v[158:161], v[198:201], v[22:25]
	v_mfma_f32_16x16x32_bf16 v[26:29], v[162:165], v[194:197], v[26:29]
	v_mfma_f32_16x16x32_bf16 v[26:29], v[166:169], v[198:201], v[26:29]
	v_mfma_f32_16x16x32_bf16 v[18:21], v[170:173], v[194:197], v[18:21]
	v_mfma_f32_16x16x32_bf16 v[18:21], v[174:177], v[198:201], v[18:21]
	v_mfma_f32_16x16x32_bf16 v[2:5], v[170:173], v[202:205], v[2:5]
	v_mfma_f32_16x16x32_bf16 v[2:5], v[174:177], v[206:209], v[2:5]
	v_mfma_f32_16x16x32_bf16 v[10:13], v[162:165], v[202:205], v[10:13]
	v_mfma_f32_16x16x32_bf16 v[10:13], v[166:169], v[206:209], v[10:13]
	v_mfma_f32_16x16x32_bf16 v[6:9], v[154:157], v[202:205], v[6:9]
	v_mfma_f32_16x16x32_bf16 v[6:9], v[158:161], v[206:209], v[6:9]
	v_mfma_f32_16x16x32_bf16 v[14:17], v[146:149], v[202:205], v[14:17]
	v_mfma_f32_16x16x32_bf16 v[14:17], v[150:153], v[206:209], v[14:17]
	s_setprio 0
	s_barrier
	s_add_i32 s77, s77, 2
	s_addk_i32 s75, 0x100
	s_addk_i32 s76, 0x100
	s_cmp_ge_i32 s77, s13
	s_cbranch_scc0 .LBB0_1402
	s_and_b64 vcc, exec, s[46:47]
	s_cbranch_vccz .LBB0_1405

.LBB0_1519:
	ds_read_b128 v[134:137], v208
	ds_read_b128 v[138:141], v208 offset:1024
	ds_read_b128 v[142:145], v208 offset:2048
	ds_read_b128 v[146:149], v208 offset:3072
	ds_read_b128 v[150:153], v209
	ds_read_b128 v[154:157], v209 offset:1024
	ds_read_b128 v[158:161], v209 offset:2048
	ds_read_b128 v[162:165], v209 offset:3072
	ds_read_b128 v[166:169], v210
	ds_read_b128 v[170:173], v210 offset:1024
	ds_read_b128 v[174:177], v210 offset:2048
	ds_read_b128 v[178:181], v210 offset:3072
	ds_read_b128 v[182:185], v210 offset:4096
	ds_read_b128 v[186:189], v210 offset:5120
	ds_read_b128 v[190:193], v210 offset:6144
	ds_read_b128 v[194:197], v210 offset:7168
	s_add_i32 s18, s80, 0xffbf8080
	s_cmp_eq_u32 s65, s82
	s_cselect_b32 s83, s6, s18
	s_cselect_b32 s85, s7, s81
	s_or_b32 s84, s83, 0x80
	s_add_i32 s18, s80, 0xffea8000
	s_mov_b32 m0, s66
	s_nop 0
	buffer_load_dwordx4 v206, s[12:15], s18 offen lds
	s_mov_b32 m0, s69
	s_nop 0
	buffer_load_dwordx4 v206, s[12:15], s80 offen lds
	s_waitcnt vmcnt(8)
	s_waitcnt lgkmcnt(0)
	s_setprio 1
	v_mfma_f32_16x16x32_bf16 v[126:129], v[134:137], v[166:169], v[126:129]
	s_barrier
	v_mfma_f32_16x16x32_bf16 v[126:129], v[138:141], v[170:173], v[126:129]
	v_mfma_f32_16x16x32_bf16 v[122:125], v[142:145], v[166:169], v[122:125]
	v_mfma_f32_16x16x32_bf16 v[122:125], v[146:149], v[170:173], v[122:125]
	v_mfma_f32_16x16x32_bf16 v[110:113], v[150:153], v[166:169], v[110:113]
	v_mfma_f32_16x16x32_bf16 v[110:113], v[154:157], v[170:173], v[110:113]
	v_mfma_f32_16x16x32_bf16 v[102:105], v[158:161], v[166:169], v[102:105]
	v_mfma_f32_16x16x32_bf16 v[102:105], v[162:165], v[170:173], v[102:105]
	v_mfma_f32_16x16x32_bf16 v[86:89], v[158:161], v[174:177], v[86:89]
	v_mfma_f32_16x16x32_bf16 v[86:89], v[162:165], v[178:181], v[86:89]
	v_mfma_f32_16x16x32_bf16 v[94:97], v[150:153], v[174:177], v[94:97]
	v_mfma_f32_16x16x32_bf16 v[94:97], v[154:157], v[178:181], v[94:97]
	v_mfma_f32_16x16x32_bf16 v[114:117], v[142:145], v[174:177], v[114:117]
	v_mfma_f32_16x16x32_bf16 v[114:117], v[146:149], v[178:181], v[114:117]
	v_mfma_f32_16x16x32_bf16 v[118:121], v[134:137], v[174:177], v[118:121]
	v_mfma_f32_16x16x32_bf16 v[118:121], v[138:141], v[178:181], v[118:121]
	v_mfma_f32_16x16x32_bf16 v[106:109], v[134:137], v[182:185], v[106:109]
	v_mfma_f32_16x16x32_bf16 v[106:109], v[138:141], v[186:189], v[106:109]
	v_mfma_f32_16x16x32_bf16 v[98:101], v[142:145], v[182:185], v[98:101]
	v_mfma_f32_16x16x32_bf16 v[98:101], v[146:149], v[186:189], v[98:101]
	v_mfma_f32_16x16x32_bf16 v[78:81], v[150:153], v[182:185], v[78:81]
	v_mfma_f32_16x16x32_bf16 v[78:81], v[154:157], v[186:189], v[78:81]
	v_mfma_f32_16x16x32_bf16 v[74:77], v[158:161], v[182:185], v[74:77]
	v_mfma_f32_16x16x32_bf16 v[74:77], v[162:165], v[186:189], v[74:77]
	v_mfma_f32_16x16x32_bf16 v[66:69], v[158:161], v[190:193], v[66:69]
	v_mfma_f32_16x16x32_bf16 v[66:69], v[162:165], v[194:197], v[66:69]
	v_mfma_f32_16x16x32_bf16 v[70:73], v[150:153], v[190:193], v[70:73]
	v_mfma_f32_16x16x32_bf16 v[70:73], v[154:157], v[194:197], v[70:73]
	v_mfma_f32_16x16x32_bf16 v[82:85], v[142:145], v[190:193], v[82:85]
	v_mfma_f32_16x16x32_bf16 v[82:85], v[146:149], v[194:197], v[82:85]
	v_mfma_f32_16x16x32_bf16 v[90:93], v[134:137], v[190:193], v[90:93]
	v_mfma_f32_16x16x32_bf16 v[90:93], v[138:141], v[194:197], v[90:93]
	s_setprio 0
	s_barrier
	ds_read_b128 v[166:169], v210 offset:16384
	ds_read_b128 v[170:173], v210 offset:17408
	ds_read_b128 v[174:177], v210 offset:18432
	ds_read_b128 v[178:181], v210 offset:19456
	ds_read_b128 v[182:185], v210 offset:20480
	ds_read_b128 v[186:189], v210 offset:21504
	ds_read_b128 v[190:193], v210 offset:22528
	ds_read_b128 v[194:197], v210 offset:23552
	s_mov_b32 m0, s27
	s_mov_b32 s18, s14
	s_mov_b32 s19, s15
	buffer_load_dwordx4 v207, s[16:19], s85 offen lds
	s_add_i32 s86, s85, 0x158000
	s_mov_b32 m0, s30
	s_nop 0
	buffer_load_dwordx4 v207, s[16:19], s86 offen lds
	s_add_i32 s86, s85, 0x2b0000
	s_mov_b32 m0, s31
	s_nop 0
	buffer_load_dwordx4 v207, s[16:19], s86 offen lds
	s_add_i32 s86, s85, 0x408000
	s_mov_b32 m0, s50
	s_nop 0
	buffer_load_dwordx4 v207, s[16:19], s86 offen lds
	s_mov_b32 m0, s25
	s_add_i32 s86, s83, 0x158000
	buffer_load_dwordx4 v206, s[12:15], s83 offen lds
	s_mov_b32 m0, s51
	s_nop 0
	buffer_load_dwordx4 v206, s[12:15], s86 offen lds
	s_waitcnt vmcnt(8)
	s_waitcnt lgkmcnt(0)
	s_setprio 1
	v_mfma_f32_16x16x32_bf16 v[62:65], v[134:137], v[166:169], v[62:65]
	s_barrier
	v_mfma_f32_16x16x32_bf16 v[62:65], v[138:141], v[170:173], v[62:65]
	v_mfma_f32_16x16x32_bf16 v[58:61], v[142:145], v[166:169], v[58:61]
	v_mfma_f32_16x16x32_bf16 v[58:61], v[146:149], v[170:173], v[58:61]
	v_mfma_f32_16x16x32_bf16 v[46:49], v[150:153], v[166:169], v[46:49]
	v_mfma_f32_16x16x32_bf16 v[46:49], v[154:157], v[170:173], v[46:49]
	v_mfma_f32_16x16x32_bf16 v[38:41], v[158:161], v[166:169], v[38:41]
	v_mfma_f32_16x16x32_bf16 v[38:41], v[162:165], v[170:173], v[38:41]
	v_mfma_f32_16x16x32_bf16 v[22:25], v[158:161], v[174:177], v[22:25]
	v_mfma_f32_16x16x32_bf16 v[22:25], v[162:165], v[178:181], v[22:25]
	v_mfma_f32_16x16x32_bf16 v[30:33], v[150:153], v[174:177], v[30:33]
	v_mfma_f32_16x16x32_bf16 v[30:33], v[154:157], v[178:181], v[30:33]
	v_mfma_f32_16x16x32_bf16 v[50:53], v[142:145], v[174:177], v[50:53]
	v_mfma_f32_16x16x32_bf16 v[50:53], v[146:149], v[178:181], v[50:53]
	v_mfma_f32_16x16x32_bf16 v[54:57], v[134:137], v[174:177], v[54:57]
	v_mfma_f32_16x16x32_bf16 v[54:57], v[138:141], v[178:181], v[54:57]
	v_mfma_f32_16x16x32_bf16 v[42:45], v[134:137], v[182:185], v[42:45]
	v_mfma_f32_16x16x32_bf16 v[42:45], v[138:141], v[186:189], v[42:45]
	v_mfma_f32_16x16x32_bf16 v[34:37], v[142:145], v[182:185], v[34:37]
	v_mfma_f32_16x16x32_bf16 v[34:37], v[146:149], v[186:189], v[34:37]
	v_mfma_f32_16x16x32_bf16 v[14:17], v[150:153], v[182:185], v[14:17]
	v_mfma_f32_16x16x32_bf16 v[14:17], v[154:157], v[186:189], v[14:17]
	v_mfma_f32_16x16x32_bf16 v[10:13], v[158:161], v[182:185], v[10:13]
	v_mfma_f32_16x16x32_bf16 v[10:13], v[162:165], v[186:189], v[10:13]
	v_mfma_f32_16x16x32_bf16 v[2:5], v[158:161], v[190:193], v[2:5]
	v_mfma_f32_16x16x32_bf16 v[2:5], v[162:165], v[194:197], v[2:5]
	v_mfma_f32_16x16x32_bf16 v[6:9], v[150:153], v[190:193], v[6:9]
	v_mfma_f32_16x16x32_bf16 v[6:9], v[154:157], v[194:197], v[6:9]
	v_mfma_f32_16x16x32_bf16 v[18:21], v[142:145], v[190:193], v[18:21]
	v_mfma_f32_16x16x32_bf16 v[18:21], v[146:149], v[194:197], v[18:21]
	v_mfma_f32_16x16x32_bf16 v[26:29], v[134:137], v[190:193], v[26:29]
	v_mfma_f32_16x16x32_bf16 v[26:29], v[138:141], v[194:197], v[26:29]
	s_setprio 0
	s_barrier
	ds_read_b128 v[134:137], v211
	ds_read_b128 v[138:141], v211 offset:1024
	ds_read_b128 v[142:145], v211 offset:2048
	ds_read_b128 v[146:149], v211 offset:3072
	ds_read_b128 v[150:153], v212
	ds_read_b128 v[154:157], v212 offset:1024
	ds_read_b128 v[158:161], v212 offset:2048
	ds_read_b128 v[162:165], v212 offset:3072
	ds_read_b128 v[166:169], v210 offset:32768
	ds_read_b128 v[170:173], v210 offset:33792
	ds_read_b128 v[174:177], v210 offset:34816
	ds_read_b128 v[178:181], v210 offset:35840
	ds_read_b128 v[182:185], v210 offset:36864
	ds_read_b128 v[186:189], v210 offset:37888
	ds_read_b128 v[190:193], v210 offset:38912
	ds_read_b128 v[194:197], v210 offset:39936
	s_mov_b32 m0, s52
	s_add_i32 s86, s83, 0x2b0000
	buffer_load_dwordx4 v206, s[12:15], s86 offen lds
	s_add_i32 s86, s83, 0x408000
	s_mov_b32 m0, s53
	s_nop 0
	buffer_load_dwordx4 v206, s[12:15], s86 offen lds
	s_waitcnt vmcnt(8)
	s_waitcnt lgkmcnt(0)
	s_setprio 1
	v_mfma_f32_16x16x32_bf16 v[126:129], v[134:137], v[166:169], v[126:129]
	s_barrier
	v_mfma_f32_16x16x32_bf16 v[126:129], v[138:141], v[170:173], v[126:129]
	v_mfma_f32_16x16x32_bf16 v[122:125], v[142:145], v[166:169], v[122:125]
	v_mfma_f32_16x16x32_bf16 v[122:125], v[146:149], v[170:173], v[122:125]
	v_mfma_f32_16x16x32_bf16 v[110:113], v[150:153], v[166:169], v[110:113]
	v_mfma_f32_16x16x32_bf16 v[110:113], v[154:157], v[170:173], v[110:113]
	v_mfma_f32_16x16x32_bf16 v[102:105], v[158:161], v[166:169], v[102:105]
	v_mfma_f32_16x16x32_bf16 v[102:105], v[162:165], v[170:173], v[102:105]
	v_mfma_f32_16x16x32_bf16 v[86:89], v[158:161], v[174:177], v[86:89]
	v_mfma_f32_16x16x32_bf16 v[86:89], v[162:165], v[178:181], v[86:89]
	v_mfma_f32_16x16x32_bf16 v[94:97], v[150:153], v[174:177], v[94:97]
	v_mfma_f32_16x16x32_bf16 v[94:97], v[154:157], v[178:181], v[94:97]
	v_mfma_f32_16x16x32_bf16 v[114:117], v[142:145], v[174:177], v[114:117]
	v_mfma_f32_16x16x32_bf16 v[114:117], v[146:149], v[178:181], v[114:117]
	v_mfma_f32_16x16x32_bf16 v[118:121], v[134:137], v[174:177], v[118:121]
	v_mfma_f32_16x16x32_bf16 v[118:121], v[138:141], v[178:181], v[118:121]
	v_mfma_f32_16x16x32_bf16 v[106:109], v[134:137], v[182:185], v[106:109]
	v_mfma_f32_16x16x32_bf16 v[106:109], v[138:141], v[186:189], v[106:109]
	v_mfma_f32_16x16x32_bf16 v[98:101], v[142:145], v[182:185], v[98:101]
	v_mfma_f32_16x16x32_bf16 v[98:101], v[146:149], v[186:189], v[98:101]
	v_mfma_f32_16x16x32_bf16 v[78:81], v[150:153], v[182:185], v[78:81]
	v_mfma_f32_16x16x32_bf16 v[78:81], v[154:157], v[186:189], v[78:81]
	v_mfma_f32_16x16x32_bf16 v[74:77], v[158:161], v[182:185], v[74:77]
	v_mfma_f32_16x16x32_bf16 v[74:77], v[162:165], v[186:189], v[74:77]
	v_mfma_f32_16x16x32_bf16 v[66:69], v[158:161], v[190:193], v[66:69]
	v_mfma_f32_16x16x32_bf16 v[66:69], v[162:165], v[194:197], v[66:69]
	v_mfma_f32_16x16x32_bf16 v[70:73], v[150:153], v[190:193], v[70:73]
	v_mfma_f32_16x16x32_bf16 v[70:73], v[154:157], v[194:197], v[70:73]
	v_mfma_f32_16x16x32_bf16 v[82:85], v[142:145], v[190:193], v[82:85]
	v_mfma_f32_16x16x32_bf16 v[82:85], v[146:149], v[194:197], v[82:85]
	v_mfma_f32_16x16x32_bf16 v[90:93], v[134:137], v[190:193], v[90:93]
	v_mfma_f32_16x16x32_bf16 v[90:93], v[138:141], v[194:197], v[90:93]
	s_setprio 0
	s_barrier
	ds_read_b128 v[166:169], v210 offset:49152
	ds_read_b128 v[170:173], v210 offset:50176
	ds_read_b128 v[174:177], v210 offset:51200
	ds_read_b128 v[178:181], v210 offset:52224
	ds_read_b128 v[182:185], v210 offset:53248
	ds_read_b128 v[186:189], v210 offset:54272
	ds_read_b128 v[190:193], v210 offset:55296
	ds_read_b128 v[194:197], v210 offset:56320
	s_mov_b32 m0, s57
	s_or_b32 s86, s85, 0x80
	buffer_load_dwordx4 v207, s[16:19], s86 offen lds
	s_add_i32 s86, s85, 0x158080
	s_mov_b32 m0, s58
	s_add_i32 s83, s83, 0x158080
	buffer_load_dwordx4 v207, s[16:19], s86 offen lds
	s_add_i32 s86, s85, 0x2b0080
	s_mov_b32 m0, s61
	s_add_i32 s85, s85, 0x408080
	buffer_load_dwordx4 v207, s[16:19], s86 offen lds
	s_mov_b32 m0, s62
	s_nop 0
	buffer_load_dwordx4 v207, s[16:19], s85 offen lds
	s_mov_b32 m0, s59
	s_nop 0
	buffer_load_dwordx4 v206, s[12:15], s84 offen lds
	s_mov_b32 m0, s60
	s_nop 0
	buffer_load_dwordx4 v206, s[12:15], s83 offen lds
	s_waitcnt vmcnt(8)
	s_waitcnt lgkmcnt(0)
	s_setprio 1
	v_mfma_f32_16x16x32_bf16 v[62:65], v[134:137], v[166:169], v[62:65]
	s_barrier
	v_mfma_f32_16x16x32_bf16 v[62:65], v[138:141], v[170:173], v[62:65]
	v_mfma_f32_16x16x32_bf16 v[58:61], v[142:145], v[166:169], v[58:61]
	v_mfma_f32_16x16x32_bf16 v[58:61], v[146:149], v[170:173], v[58:61]
	v_mfma_f32_16x16x32_bf16 v[46:49], v[150:153], v[166:169], v[46:49]
	v_mfma_f32_16x16x32_bf16 v[46:49], v[154:157], v[170:173], v[46:49]
	v_mfma_f32_16x16x32_bf16 v[38:41], v[158:161], v[166:169], v[38:41]
	v_mfma_f32_16x16x32_bf16 v[38:41], v[162:165], v[170:173], v[38:41]
	v_mfma_f32_16x16x32_bf16 v[22:25], v[158:161], v[174:177], v[22:25]
	v_mfma_f32_16x16x32_bf16 v[22:25], v[162:165], v[178:181], v[22:25]
	v_mfma_f32_16x16x32_bf16 v[30:33], v[150:153], v[174:177], v[30:33]
	v_mfma_f32_16x16x32_bf16 v[30:33], v[154:157], v[178:181], v[30:33]
	v_mfma_f32_16x16x32_bf16 v[50:53], v[142:145], v[174:177], v[50:53]
	v_mfma_f32_16x16x32_bf16 v[50:53], v[146:149], v[178:181], v[50:53]
	v_mfma_f32_16x16x32_bf16 v[54:57], v[134:137], v[174:177], v[54:57]
	v_mfma_f32_16x16x32_bf16 v[54:57], v[138:141], v[178:181], v[54:57]
	v_mfma_f32_16x16x32_bf16 v[42:45], v[134:137], v[182:185], v[42:45]
	v_mfma_f32_16x16x32_bf16 v[42:45], v[138:141], v[186:189], v[42:45]
	v_mfma_f32_16x16x32_bf16 v[34:37], v[142:145], v[182:185], v[34:37]
	v_mfma_f32_16x16x32_bf16 v[34:37], v[146:149], v[186:189], v[34:37]
	v_mfma_f32_16x16x32_bf16 v[14:17], v[150:153], v[182:185], v[14:17]
	v_mfma_f32_16x16x32_bf16 v[14:17], v[154:157], v[186:189], v[14:17]
	v_mfma_f32_16x16x32_bf16 v[10:13], v[158:161], v[182:185], v[10:13]
	v_mfma_f32_16x16x32_bf16 v[10:13], v[162:165], v[186:189], v[10:13]
	v_mfma_f32_16x16x32_bf16 v[2:5], v[158:161], v[190:193], v[2:5]
	v_mfma_f32_16x16x32_bf16 v[2:5], v[162:165], v[194:197], v[2:5]
	v_mfma_f32_16x16x32_bf16 v[6:9], v[150:153], v[190:193], v[6:9]
	v_mfma_f32_16x16x32_bf16 v[6:9], v[154:157], v[194:197], v[6:9]
	v_mfma_f32_16x16x32_bf16 v[18:21], v[142:145], v[190:193], v[18:21]
	v_mfma_f32_16x16x32_bf16 v[18:21], v[146:149], v[194:197], v[18:21]
	v_mfma_f32_16x16x32_bf16 v[26:29], v[134:137], v[190:193], v[26:29]
	v_mfma_f32_16x16x32_bf16 v[26:29], v[138:141], v[194:197], v[26:29]
	s_setprio 0
	s_barrier
	s_add_i32 s82, s82, 2
	s_addk_i32 s80, 0x100
	s_addk_i32 s81, 0x100
	s_cmp_ge_i32 s82, s3
	s_cbranch_scc0 .LBB0_1519
	v_pk_mul_f32 v[182:183], v[128:129], 0.5 op_sel_hi:[1,0]
	v_pk_mul_f32 v[184:185], v[126:127], 0.5 op_sel_hi:[1,0]
	v_pk_mul_f32 v[186:187], v[124:125], 0.5 op_sel_hi:[1,0]
	v_pk_mul_f32 v[188:189], v[122:123], 0.5 op_sel_hi:[1,0]
	v_pk_mul_f32 v[196:197], v[112:113], 0.5 op_sel_hi:[1,0]
	v_pk_mul_f32 v[194:195], v[110:111], 0.5 op_sel_hi:[1,0]
	v_pk_mul_f32 v[192:193], v[104:105], 0.5 op_sel_hi:[1,0]
	v_pk_mul_f32 v[190:191], v[102:103], 0.5 op_sel_hi:[1,0]
	v_pk_mul_f32 v[180:181], v[120:121], 0.5 op_sel_hi:[1,0]
	v_pk_mul_f32 v[178:179], v[118:119], 0.5 op_sel_hi:[1,0]
	v_pk_mul_f32 v[176:177], v[116:117], 0.5 op_sel_hi:[1,0]
	v_pk_mul_f32 v[174:175], v[114:115], 0.5 op_sel_hi:[1,0]
	v_pk_mul_f32 v[170:171], v[96:97], 0.5 op_sel_hi:[1,0]
	v_pk_mul_f32 v[168:169], v[94:95], 0.5 op_sel_hi:[1,0]
	v_pk_mul_f32 v[166:167], v[88:89], 0.5 op_sel_hi:[1,0]
	v_pk_mul_f32 v[164:165], v[86:87], 0.5 op_sel_hi:[1,0]
	v_pk_mul_f32 v[162:163], v[108:109], 0.5 op_sel_hi:[1,0]
	v_pk_mul_f32 v[160:161], v[106:107], 0.5 op_sel_hi:[1,0]
	v_pk_mul_f32 v[158:159], v[100:101], 0.5 op_sel_hi:[1,0]
	v_pk_mul_f32 v[156:157], v[98:99], 0.5 op_sel_hi:[1,0]
	v_pk_mul_f32 v[154:155], v[80:81], 0.5 op_sel_hi:[1,0]
	v_pk_mul_f32 v[152:153], v[78:79], 0.5 op_sel_hi:[1,0]
	v_pk_mul_f32 v[150:151], v[76:77], 0.5 op_sel_hi:[1,0]
	v_pk_mul_f32 v[148:149], v[74:75], 0.5 op_sel_hi:[1,0]
	v_pk_mul_f32 v[144:145], v[92:93], 0.5 op_sel_hi:[1,0]
	v_pk_mul_f32 v[142:143], v[90:91], 0.5 op_sel_hi:[1,0]
	v_pk_mul_f32 v[140:141], v[84:85], 0.5 op_sel_hi:[1,0]
	v_pk_mul_f32 v[138:139], v[82:83], 0.5 op_sel_hi:[1,0]
	v_pk_mul_f32 v[136:137], v[72:73], 0.5 op_sel_hi:[1,0]
	v_pk_mul_f32 v[134:135], v[70:71], 0.5 op_sel_hi:[1,0]
	v_pk_mul_f32 v[128:129], v[68:69], 0.5 op_sel_hi:[1,0]
	v_pk_mul_f32 v[126:127], v[66:67], 0.5 op_sel_hi:[1,0]
	v_pk_mul_f32 v[122:123], v[64:65], 0.5 op_sel_hi:[1,0]
	v_pk_mul_f32 v[120:121], v[62:63], 0.5 op_sel_hi:[1,0]
	v_pk_mul_f32 v[118:119], v[60:61], 0.5 op_sel_hi:[1,0]
	v_pk_mul_f32 v[116:117], v[58:59], 0.5 op_sel_hi:[1,0]
	v_pk_mul_f32 v[112:113], v[48:49], 0.5 op_sel_hi:[1,0]
	v_pk_mul_f32 v[110:111], v[46:47], 0.5 op_sel_hi:[1,0]
	v_pk_mul_f32 v[108:109], v[40:41], 0.5 op_sel_hi:[1,0]
	v_pk_mul_f32 v[106:107], v[38:39], 0.5 op_sel_hi:[1,0]
	v_pk_mul_f32 v[104:105], v[56:57], 0.5 op_sel_hi:[1,0]
	v_pk_mul_f32 v[102:103], v[54:55], 0.5 op_sel_hi:[1,0]
	v_pk_mul_f32 v[100:101], v[52:53], 0.5 op_sel_hi:[1,0]
	v_pk_mul_f32 v[98:99], v[50:51], 0.5 op_sel_hi:[1,0]
	v_pk_mul_f32 v[96:97], v[32:33], 0.5 op_sel_hi:[1,0]
	v_pk_mul_f32 v[94:95], v[30:31], 0.5 op_sel_hi:[1,0]
	v_pk_mul_f32 v[92:93], v[24:25], 0.5 op_sel_hi:[1,0]
	v_pk_mul_f32 v[90:91], v[22:23], 0.5 op_sel_hi:[1,0]
	v_pk_mul_f32 v[88:89], v[44:45], 0.5 op_sel_hi:[1,0]
	v_pk_mul_f32 v[86:87], v[42:43], 0.5 op_sel_hi:[1,0]
	v_pk_mul_f32 v[84:85], v[36:37], 0.5 op_sel_hi:[1,0]
	v_pk_mul_f32 v[82:83], v[34:35], 0.5 op_sel_hi:[1,0]
	v_pk_mul_f32 v[80:81], v[16:17], 0.5 op_sel_hi:[1,0]
	v_pk_mul_f32 v[78:79], v[14:15], 0.5 op_sel_hi:[1,0]
	v_pk_mul_f32 v[76:77], v[12:13], 0.5 op_sel_hi:[1,0]
	v_pk_mul_f32 v[74:75], v[10:11], 0.5 op_sel_hi:[1,0]
	v_pk_mul_f32 v[72:73], v[28:29], 0.5 op_sel_hi:[1,0]
	v_pk_mul_f32 v[70:71], v[26:27], 0.5 op_sel_hi:[1,0]
	v_pk_mul_f32 v[68:69], v[20:21], 0.5 op_sel_hi:[1,0]
	v_pk_mul_f32 v[66:67], v[18:19], 0.5 op_sel_hi:[1,0]
	v_pk_mul_f32 v[64:65], v[8:9], 0.5 op_sel_hi:[1,0]
	v_pk_mul_f32 v[62:63], v[6:7], 0.5 op_sel_hi:[1,0]
	v_pk_mul_f32 v[60:61], v[4:5], 0.5 op_sel_hi:[1,0]
	v_pk_mul_f32 v[58:59], v[2:3], 0.5 op_sel_hi:[1,0]
	s_and_b64 vcc, exec, s[40:41]
	s_cbranch_vccz .LBB0_1522
